# pre-barrier MFMA count 2 (all six GEMM loops)
# speedup vs baseline: 1.0197x; 1.0197x over previous
; #define PG8_STAGE(bufoff, gbase, voff) do { _Pragma("unroll") for (int _i = 0; _i < 2; ++_i) \
;         __builtin_amdgcn_global_load_lds((const unsigned*)((const char*)(gbase) + (voff)[_i]), (LAS unsigned*)(lds + (bufoff) + ldsw + _i * 8192), 16, 0, 0); } while (0)
; #define PG8_LDA(dst, b, h) do { _Pragma("unroll") for (int m = 0; m < 4; ++m) _Pragma("unroll") for (int k = 0; k < 2; ++k) dst[m][k] = *(const LAS bf16x8*)(lds + PG8_SA(b, h) + aoff + m * 2048 + k * 1024); } while (0)
; #define PG8_WAIT_V(n) asm volatile("s_waitcnt vmcnt(" #n ")" ::: "memory")
; #define PG8_WAIT_L(n) asm volatile("s_waitcnt lgkmcnt(" #n ")" ::: "memory")
; template <class Epi>
; __device__ __forceinline__ void gemm_phase(LAS unsigned char* lds, const Gemm g, const Sched& S, const Epi& E) {
;     ...
;         for (int t = 0; t < nt; t += 2) {
;             const bool last = (t == nt - 2);
;             const char* a1 = cA + (size_t)(t + 1) * kstep;
;             const char* a2 = last ? nA : cA + (size_t)(t + 2) * kstep; const char* b2 = last ? nB : cB + (size_t)(t + 2) * kstep;
;             const char* a3 = a2 + kstep; const char* b3 = b2 + kstep;
;             PG8_LDB(B0, 0, 0); PG8_SCHED; PG8_LDA(At, 0, 0); PG8_STAGE(PG8_SA(1, 1), a1 + hstepA, voffA);
;             PG8_WAIT_L(8); PG8_BAR; PG8_WAIT_L(0); PG8_MMA(0, 0, At, B0); PG8_BAR; PG8_SCHED;
;             PG8_LDB(B1, 0, 1); PG8_STAGE(PG8_SB(0, 0), b2, voffB);
;             PG8_BAR; PG8_WAIT_L(0); PG8_MMA(0, 1, At, B1); PG8_BAR;
;             PG8_LDA(At, 0, 1); PG8_STAGE(PG8_SA(0, 0), a2, voffA);
;             PG8_BAR; PG8_WAIT_L(0); PG8_MMA(1, 0, At, B0); PG8_BAR; PG8_SCHED;
;             PG8_STAGE(PG8_SB(0, 1), b2 + hstepB, voffB);
;             PG8_WAIT_V(6); PG8_BAR; PG8_MMA(1, 1, At, B1); PG8_BAR;
;             PG8_LDB(B0, 1, 0); PG8_SCHED; PG8_LDA(At, 1, 0); PG8_STAGE(PG8_SA(0, 1), a2 + hstepA, voffA);
;             PG8_WAIT_L(8); PG8_BAR; PG8_WAIT_L(0); PG8_MMA(0, 0, At, B0); PG8_BAR; PG8_SCHED;
;             PG8_LDB(B1, 1, 1); PG8_STAGE(PG8_SB(1, 0), b3, voffB);
;             PG8_BAR; PG8_WAIT_L(0); PG8_MMA(0, 1, At, B1); PG8_BAR;
;             PG8_LDA(At, 1, 1); PG8_STAGE(PG8_SA(1, 0), a3, voffA);
;             PG8_BAR; PG8_WAIT_L(0); PG8_MMA(1, 0, At, B0); PG8_BAR; PG8_SCHED;
;             PG8_STAGE(PG8_SB(1, 1), b3 + hstepB, voffB);
;             PG8_WAIT_V(6); PG8_BAR; PG8_MMA(1, 1, At, B1); PG8_BAR;
.LBB0_400:
	s_add_i32 s14, s66, 2
	s_add_u32 s8, s92, 0x80
	s_addc_u32 s9, s93, 0
	s_add_i32 s15, 0, 0x10000
	v_add_u32_e32 v148, s15, v152
	ds_read_b128 v[144:147], v148
	ds_read_b128 v[172:175], v148 offset:1024
	ds_read_b128 v[176:179], v148 offset:2048
	ds_read_b128 v[180:183], v148 offset:3072
	s_cmp_eq_u32 s71, s66
	s_cselect_b32 s95, s55, s9
	s_cselect_b32 s94, s57, s8
	s_cselect_b32 s97, s59, s35
	s_cselect_b32 s96, s65, s34
	v_lshl_add_u64 v[148:149], s[92:93], 0, v[138:139]
	s_add_i32 m0, s42, 0xc000
	ds_read_b128 v[184:187], v171
	ds_read_b128 v[188:191], v171 offset:1024
	ds_read_b128 v[196:199], v171 offset:2048
	ds_read_b128 v[200:203], v171 offset:3072
	ds_read_b128 v[204:207], v171 offset:4096
	ds_read_b128 v[208:211], v171 offset:5120
	ds_read_b128 v[212:215], v171 offset:6144
	ds_read_b128 v[222:225], v171 offset:7168
	global_load_lds_dwordx4 v[148:149], off
	v_lshl_add_u64 v[148:149], s[92:93], 0, v[140:141]
	s_add_i32 m0, s42, 0xe000
	s_nop 0
	global_load_lds_dwordx4 v[148:149], off
	s_add_i32 s8, 0, 0x14000
	v_add_u32_e32 v148, s8, v152
	ds_read_b128 v[226:229], v148
	ds_read_b128 v[230:233], v148 offset:1024
	ds_read_b128 v[234:237], v148 offset:2048
	ds_read_b128 v[238:241], v148 offset:3072
	s_waitcnt vmcnt(8)
	s_waitcnt lgkmcnt(0)
	v_mfma_f32_16x16x32_bf16 v[126:129], v[144:147], v[184:187], v[126:129]
	v_mfma_f32_16x16x32_bf16 v[122:125], v[176:179], v[184:187], v[122:125]
	s_barrier
	s_setprio 1
	v_mfma_f32_16x16x32_bf16 v[110:113], v[144:147], v[196:199], v[110:113]
	v_mfma_f32_16x16x32_bf16 v[106:109], v[176:179], v[196:199], v[106:109]
	v_mfma_f32_16x16x32_bf16 v[94:97], v[144:147], v[204:207], v[94:97]
	v_mfma_f32_16x16x32_bf16 v[90:93], v[176:179], v[204:207], v[90:93]
	v_mfma_f32_16x16x32_bf16 v[78:81], v[144:147], v[212:215], v[78:81]
	v_mfma_f32_16x16x32_bf16 v[74:77], v[176:179], v[212:215], v[74:77]
	v_mfma_f32_16x16x32_bf16 v[126:129], v[172:175], v[188:191], v[126:129]
	v_mfma_f32_16x16x32_bf16 v[122:125], v[180:183], v[188:191], v[122:125]
	v_mfma_f32_16x16x32_bf16 v[110:113], v[172:175], v[200:203], v[110:113]
	v_mfma_f32_16x16x32_bf16 v[106:109], v[180:183], v[200:203], v[106:109]
	v_mfma_f32_16x16x32_bf16 v[94:97], v[172:175], v[208:211], v[94:97]
	v_mfma_f32_16x16x32_bf16 v[90:93], v[180:183], v[208:211], v[90:93]
	v_mfma_f32_16x16x32_bf16 v[78:81], v[172:175], v[222:225], v[78:81]
	v_mfma_f32_16x16x32_bf16 v[74:77], v[180:183], v[222:225], v[74:77]
	v_mfma_f32_16x16x32_bf16 v[118:121], v[226:229], v[184:187], v[118:121]
	v_mfma_f32_16x16x32_bf16 v[114:117], v[234:237], v[184:187], v[114:117]
	v_mfma_f32_16x16x32_bf16 v[102:105], v[226:229], v[196:199], v[102:105]
	v_mfma_f32_16x16x32_bf16 v[98:101], v[234:237], v[196:199], v[98:101]
	v_mfma_f32_16x16x32_bf16 v[86:89], v[226:229], v[204:207], v[86:89]
	v_mfma_f32_16x16x32_bf16 v[82:85], v[234:237], v[204:207], v[82:85]
	v_mfma_f32_16x16x32_bf16 v[70:73], v[226:229], v[212:215], v[70:73]
	v_mfma_f32_16x16x32_bf16 v[66:69], v[234:237], v[212:215], v[66:69]
	v_mfma_f32_16x16x32_bf16 v[118:121], v[230:233], v[188:191], v[118:121]
	v_mfma_f32_16x16x32_bf16 v[114:117], v[238:241], v[188:191], v[114:117]
	v_mfma_f32_16x16x32_bf16 v[102:105], v[230:233], v[200:203], v[102:105]
	v_mfma_f32_16x16x32_bf16 v[98:101], v[238:241], v[200:203], v[98:101]
	v_mfma_f32_16x16x32_bf16 v[86:89], v[230:233], v[208:211], v[86:89]
	v_mfma_f32_16x16x32_bf16 v[82:85], v[238:241], v[208:211], v[82:85]
	v_mfma_f32_16x16x32_bf16 v[70:73], v[230:233], v[222:225], v[70:73]
	v_mfma_f32_16x16x32_bf16 v[66:69], v[238:241], v[222:225], v[66:69]
	s_setprio 0
	s_barrier
	s_add_i32 s9, s15, s39
	v_lshl_add_u64 v[148:149], s[96:97], 0, v[132:133]
	s_mov_b32 m0, s9
	v_lshl_add_u64 v[192:193], s[96:97], 0, v[136:137]
	global_load_lds_dwordx4 v[148:149], off
	s_add_i32 m0, s9, 0x2000
	s_nop 0
	global_load_lds_dwordx4 v[192:193], off
	s_mov_b32 m0, s42
	v_lshl_add_u64 v[194:195], s[94:95], 0, v[130:131]
	ds_read_b128 v[184:187], v171 offset:16384
	ds_read_b128 v[188:191], v171 offset:17408
	ds_read_b128 v[196:199], v171 offset:18432
	ds_read_b128 v[200:203], v171 offset:19456
	ds_read_b128 v[204:207], v171 offset:20480
	ds_read_b128 v[208:211], v171 offset:21504
	ds_read_b128 v[212:215], v171 offset:22528
	ds_read_b128 v[222:225], v171 offset:23552
	global_load_lds_dwordx4 v[194:195], off
	v_lshl_add_u64 v[216:217], s[94:95], 0, v[134:135]
	s_mov_b32 m0, s43
	s_nop 0
	global_load_lds_dwordx4 v[216:217], off
	s_add_u32 s96, s96, s78
	s_addc_u32 s97, s97, s79
	s_add_i32 s8, s8, s39
	v_lshl_add_u64 v[242:243], s[96:97], 0, v[132:133]
	s_mov_b32 m0, s8
	v_lshl_add_u64 v[244:245], s[96:97], 0, v[136:137]
	global_load_lds_dwordx4 v[242:243], off
	s_add_i32 m0, s8, 0x2000
	s_nop 0
	global_load_lds_dwordx4 v[244:245], off
	s_waitcnt vmcnt(8)
	s_waitcnt lgkmcnt(0)
	v_mfma_f32_16x16x32_bf16 v[62:65], v[144:147], v[184:187], v[62:65]
	v_mfma_f32_16x16x32_bf16 v[58:61], v[176:179], v[184:187], v[58:61]
	s_barrier
; #define PG8_STAGE(bufoff, gbase, voff) do { _Pragma("unroll") for (int _i = 0; _i < 2; ++_i) \
;         __builtin_amdgcn_global_load_lds((const unsigned*)((const char*)(gbase) + (voff)[_i]), (LAS unsigned*)(lds + (bufoff) + ldsw + _i * 8192), 16, 0, 0); } while (0)
; #define PG8_LDA(dst, b, h) do { _Pragma("unroll") for (int m = 0; m < 4; ++m) _Pragma("unroll") for (int k = 0; k < 2; ++k) dst[m][k] = *(const LAS bf16x8*)(lds + PG8_SA(b, h) + aoff + m * 2048 + k * 1024); } while (0)
; #define PG8_LDB(dst, b, h) do { _Pragma("unroll") for (int n = 0; n < 2; ++n) _Pragma("unroll") for (int k = 0; k < 2; ++k) dst[n][k] = *(const LAS bf16x8*)(lds + PG8_SB(b, h) + boff + n * 2048 + k * 1024); } while (0)
; #define PG8_WAIT_V(n) asm volatile("s_waitcnt vmcnt(" #n ")" ::: "memory")
; #define PG8_WAIT_L(n) asm volatile("s_waitcnt lgkmcnt(" #n ")" ::: "memory")
; #define PG8_BAR __builtin_amdgcn_s_barrier()
; #define PG8_SCHED __builtin_amdgcn_sched_barrier(0)
; template <class Epi>
; __device__ __forceinline__ void gemm_phase(LAS unsigned char* lds, const Gemm g, const Sched& S, const Epi& E) {
;     ...
;             PG8_LDB(B0, 0, 0); PG8_SCHED; PG8_LDA(At, 0, 0); PG8_STAGE(PG8_SA(1, 1), a1 + hstepA, voffA);
;             PG8_WAIT_L(8); PG8_BAR; PG8_WAIT_L(0); PG8_MMA(0, 0, At, B0); PG8_BAR; PG8_SCHED;
;             PG8_LDB(B1, 0, 1); PG8_STAGE(PG8_SB(0, 0), b2, voffB);
;             PG8_BAR; PG8_WAIT_L(0); PG8_MMA(0, 1, At, B1); PG8_BAR;
;             PG8_LDA(At, 0, 1); PG8_STAGE(PG8_SA(0, 0), a2, voffA);
;             PG8_BAR; PG8_WAIT_L(0); PG8_MMA(1, 0, At, B0); PG8_BAR; PG8_SCHED;
;             PG8_STAGE(PG8_SB(0, 1), b2 + hstepB, voffB);
;             PG8_WAIT_V(6); PG8_BAR; PG8_MMA(1, 1, At, B1); PG8_BAR;
;             PG8_LDB(B0, 1, 0); PG8_SCHED; PG8_LDA(At, 1, 0); PG8_STAGE(PG8_SA(0, 1), a2 + hstepA, voffA);
;             PG8_WAIT_L(8); PG8_BAR; PG8_WAIT_L(0); PG8_MMA(0, 0, At, B0); PG8_BAR; PG8_SCHED;
;             PG8_LDB(B1, 1, 1); PG8_STAGE(PG8_SB(1, 0), b3, voffB);
;             PG8_BAR; PG8_WAIT_L(0); PG8_MMA(0, 1, At, B1); PG8_BAR;
;             PG8_LDA(At, 1, 1); PG8_STAGE(PG8_SA(1, 0), a3, voffA);
;             PG8_BAR; PG8_WAIT_L(0); PG8_MMA(1, 0, At, B0); PG8_BAR; PG8_SCHED;
;             PG8_STAGE(PG8_SB(1, 1), b3 + hstepB, voffB);
;             PG8_WAIT_V(6); PG8_BAR; PG8_MMA(1, 1, At, B1); PG8_BAR;
	s_setprio 1
	v_mfma_f32_16x16x32_bf16 v[50:53], v[144:147], v[196:199], v[50:53]
	v_mfma_f32_16x16x32_bf16 v[42:45], v[176:179], v[196:199], v[42:45]
	v_mfma_f32_16x16x32_bf16 v[34:37], v[144:147], v[204:207], v[34:37]
	v_mfma_f32_16x16x32_bf16 v[26:29], v[176:179], v[204:207], v[26:29]
	v_mfma_f32_16x16x32_bf16 v[18:21], v[144:147], v[212:215], v[18:21]
	v_mfma_f32_16x16x32_bf16 v[10:13], v[176:179], v[212:215], v[10:13]
	v_mfma_f32_16x16x32_bf16 v[62:65], v[172:175], v[188:191], v[62:65]
	v_mfma_f32_16x16x32_bf16 v[58:61], v[180:183], v[188:191], v[58:61]
	v_mfma_f32_16x16x32_bf16 v[50:53], v[172:175], v[200:203], v[50:53]
	v_mfma_f32_16x16x32_bf16 v[42:45], v[180:183], v[200:203], v[42:45]
	v_mfma_f32_16x16x32_bf16 v[34:37], v[172:175], v[208:211], v[34:37]
	v_mfma_f32_16x16x32_bf16 v[26:29], v[180:183], v[208:211], v[26:29]
	v_mfma_f32_16x16x32_bf16 v[18:21], v[172:175], v[222:225], v[18:21]
	v_mfma_f32_16x16x32_bf16 v[10:13], v[180:183], v[222:225], v[10:13]
	v_mfma_f32_16x16x32_bf16 v[54:57], v[226:229], v[184:187], v[54:57]
	v_mfma_f32_16x16x32_bf16 v[46:49], v[234:237], v[184:187], v[46:49]
	v_mfma_f32_16x16x32_bf16 v[38:41], v[226:229], v[196:199], v[38:41]
	v_mfma_f32_16x16x32_bf16 v[30:33], v[234:237], v[196:199], v[30:33]
	v_mfma_f32_16x16x32_bf16 v[22:25], v[226:229], v[204:207], v[22:25]
	v_mfma_f32_16x16x32_bf16 v[14:17], v[234:237], v[204:207], v[14:17]
	v_mfma_f32_16x16x32_bf16 v[6:9], v[226:229], v[212:215], v[6:9]
	v_mfma_f32_16x16x32_bf16 v[2:5], v[234:237], v[212:215], v[2:5]
	v_mfma_f32_16x16x32_bf16 v[54:57], v[230:233], v[188:191], v[54:57]
	v_mfma_f32_16x16x32_bf16 v[46:49], v[238:241], v[188:191], v[46:49]
	v_mfma_f32_16x16x32_bf16 v[38:41], v[230:233], v[200:203], v[38:41]
	v_mfma_f32_16x16x32_bf16 v[30:33], v[238:241], v[200:203], v[30:33]
	v_mfma_f32_16x16x32_bf16 v[22:25], v[230:233], v[208:211], v[22:25]
	v_mfma_f32_16x16x32_bf16 v[14:17], v[238:241], v[208:211], v[14:17]
	v_mfma_f32_16x16x32_bf16 v[6:9], v[230:233], v[222:225], v[6:9]
	v_mfma_f32_16x16x32_bf16 v[2:5], v[238:241], v[222:225], v[2:5]
	s_setprio 0
	s_barrier
	s_add_i32 s8, 0, 0x18000
	v_add_u32_e32 v180, s8, v152
	ds_read_b128 v[144:147], v180
	ds_read_b128 v[172:175], v180 offset:1024
	ds_read_b128 v[176:179], v180 offset:2048
	ds_read_b128 v[180:183], v180 offset:3072
	s_add_u32 s94, s94, s4
	s_addc_u32 s95, s95, s5
	s_mov_b32 m0, s52
	v_lshl_add_u64 v[226:227], s[94:95], 0, v[130:131]
	ds_read_b128 v[184:187], v171 offset:32768
	ds_read_b128 v[188:191], v171 offset:33792
	ds_read_b128 v[196:199], v171 offset:34816
	ds_read_b128 v[200:203], v171 offset:35840
	ds_read_b128 v[204:207], v171 offset:36864
	ds_read_b128 v[208:211], v171 offset:37888
	ds_read_b128 v[212:215], v171 offset:38912
	ds_read_b128 v[222:225], v171 offset:39936
	global_load_lds_dwordx4 v[226:227], off
	v_lshl_add_u64 v[226:227], s[94:95], 0, v[134:135]
	s_mov_b32 m0, s53
	s_nop 0
	global_load_lds_dwordx4 v[226:227], off
	s_add_i32 s9, 0, 0x1c000
	v_add_u32_e32 v218, s9, v152
	ds_read_b128 v[226:229], v218
	ds_read_b128 v[230:233], v218 offset:1024
	ds_read_b128 v[234:237], v218 offset:2048
	ds_read_b128 v[238:241], v218 offset:3072
	s_waitcnt vmcnt(8)
	s_waitcnt lgkmcnt(0)
	v_mfma_f32_16x16x32_bf16 v[126:129], v[144:147], v[184:187], v[126:129]
	v_mfma_f32_16x16x32_bf16 v[122:125], v[176:179], v[184:187], v[122:125]
	s_barrier
	s_setprio 1
	v_mfma_f32_16x16x32_bf16 v[110:113], v[144:147], v[196:199], v[110:113]
	v_mfma_f32_16x16x32_bf16 v[106:109], v[176:179], v[196:199], v[106:109]
	v_mfma_f32_16x16x32_bf16 v[94:97], v[144:147], v[204:207], v[94:97]
	v_mfma_f32_16x16x32_bf16 v[90:93], v[176:179], v[204:207], v[90:93]
	v_mfma_f32_16x16x32_bf16 v[78:81], v[144:147], v[212:215], v[78:81]
	v_mfma_f32_16x16x32_bf16 v[74:77], v[176:179], v[212:215], v[74:77]
	v_mfma_f32_16x16x32_bf16 v[126:129], v[172:175], v[188:191], v[126:129]
	v_mfma_f32_16x16x32_bf16 v[122:125], v[180:183], v[188:191], v[122:125]
	v_mfma_f32_16x16x32_bf16 v[110:113], v[172:175], v[200:203], v[110:113]
	v_mfma_f32_16x16x32_bf16 v[106:109], v[180:183], v[200:203], v[106:109]
	v_mfma_f32_16x16x32_bf16 v[94:97], v[172:175], v[208:211], v[94:97]
	v_mfma_f32_16x16x32_bf16 v[90:93], v[180:183], v[208:211], v[90:93]
	v_mfma_f32_16x16x32_bf16 v[78:81], v[172:175], v[222:225], v[78:81]
	v_mfma_f32_16x16x32_bf16 v[74:77], v[180:183], v[222:225], v[74:77]
	v_mfma_f32_16x16x32_bf16 v[118:121], v[226:229], v[184:187], v[118:121]
	v_mfma_f32_16x16x32_bf16 v[114:117], v[234:237], v[184:187], v[114:117]
	v_mfma_f32_16x16x32_bf16 v[102:105], v[226:229], v[196:199], v[102:105]
	v_mfma_f32_16x16x32_bf16 v[98:101], v[234:237], v[196:199], v[98:101]
	v_mfma_f32_16x16x32_bf16 v[86:89], v[226:229], v[204:207], v[86:89]
	v_mfma_f32_16x16x32_bf16 v[82:85], v[234:237], v[204:207], v[82:85]
	v_mfma_f32_16x16x32_bf16 v[70:73], v[226:229], v[212:215], v[70:73]
	v_mfma_f32_16x16x32_bf16 v[66:69], v[234:237], v[212:215], v[66:69]
	v_mfma_f32_16x16x32_bf16 v[118:121], v[230:233], v[188:191], v[118:121]
	v_mfma_f32_16x16x32_bf16 v[114:117], v[238:241], v[188:191], v[114:117]
	v_mfma_f32_16x16x32_bf16 v[102:105], v[230:233], v[200:203], v[102:105]
	v_mfma_f32_16x16x32_bf16 v[98:101], v[238:241], v[200:203], v[98:101]
	v_mfma_f32_16x16x32_bf16 v[86:89], v[230:233], v[208:211], v[86:89]
	v_mfma_f32_16x16x32_bf16 v[82:85], v[238:241], v[208:211], v[82:85]
	v_mfma_f32_16x16x32_bf16 v[70:73], v[230:233], v[222:225], v[70:73]
	v_mfma_f32_16x16x32_bf16 v[66:69], v[238:241], v[222:225], v[66:69]
	s_setprio 0
	s_barrier
; __device__ __forceinline__ float pre_get(const Pre& p, int ai, int m, int fr) { return __shfl(p.v[ai], m * 16 + fr); }
; __device__ __forceinline__ float rstd_pre(const float* ss, float v) { return ss ? rsqrtf(v * (1.0f / 2048.0f) + 1e-6f) : 1.0f; }
; #define PG8_STAGE(bufoff, gbase, voff) do { _Pragma("unroll") for (int _i = 0; _i < 2; ++_i) \
;         __builtin_amdgcn_global_load_lds((const unsigned*)((const char*)(gbase) + (voff)[_i]), (LAS unsigned*)(lds + (bufoff) + ldsw + _i * 8192), 16, 0, 0); } while (0)
; #define PG8_LDA(dst, b, h) do { _Pragma("unroll") for (int m = 0; m < 4; ++m) _Pragma("unroll") for (int k = 0; k < 2; ++k) dst[m][k] = *(const LAS bf16x8*)(lds + PG8_SA(b, h) + aoff + m * 2048 + k * 1024); } while (0)
; template <class Epi>
; __device__ __forceinline__ void gemm_phase(LAS unsigned char* lds, const Gemm g, const Sched& S, const Epi& E) {
;     ...
;             PG8_WAIT_V(6); PG8_BAR; PG8_MMA(1, 1, At, B1); PG8_BAR;
;             PG8_LDB(B0, 1, 0); PG8_SCHED; PG8_LDA(At, 1, 0); PG8_STAGE(PG8_SA(0, 1), a2 + hstepA, voffA);
;             PG8_WAIT_L(8); PG8_BAR; PG8_WAIT_L(0); PG8_MMA(0, 0, At, B0); PG8_BAR; PG8_SCHED;
;             PG8_LDB(B1, 1, 1); PG8_STAGE(PG8_SB(1, 0), b3, voffB);
;             PG8_BAR; PG8_WAIT_L(0); PG8_MMA(0, 1, At, B1); PG8_BAR;
;             PG8_LDA(At, 1, 1); PG8_STAGE(PG8_SA(1, 0), a3, voffA);
;             PG8_BAR; PG8_WAIT_L(0); PG8_MMA(1, 0, At, B0); PG8_BAR; PG8_SCHED;
;             PG8_STAGE(PG8_SB(1, 1), b3 + hstepB, voffB);
;             PG8_WAIT_V(6); PG8_BAR; PG8_MMA(1, 1, At, B1); PG8_BAR;
;         }
;     __device__ __forceinline__ void operator()(const Acc& acc, const Unit& u, int wr, int wc, int fr, int fq, const Pre& pre) const {
;     ...
;             for (int m = 0; m < 4; ++m) rs[ai][m] = rstd_pre(ss, pre_get(pre, ai, m, fr));
; #pragma unroll
;         for (int ai = 0; ai < 2; ++ai)
; #pragma unroll
;             for (int m = 0; m < 4; ++m) { float mx = -INFINITY;
; #pragma unroll
;                 for (int bj = 0; bj < 2; ++bj)
; #pragma unroll
;                     for (int n = 0; n < 2; ++n) { const f32x4 a = acc[ai][bj][m][n]; mx = fmaxf(mx, fmaxf(fmaxf(a[0], a[1]), fmaxf(a[2], a[3]))); }
;                 mx *= rs[ai][m];
;                 mx = fmaxf(mx, __shfl_xor(mx, 16)); mx = fmaxf(mx, __shfl_xor(mx, 32));
;                 if (fq == 0) X[(ai * 128 + wr * 64 + m * 16 + fr) * 4 + wc] = mx; }
	s_add_i32 s8, s8, s39
	v_lshl_add_u64 v[148:149], v[148:149], 0, s[60:61]
	s_mov_b32 m0, s8
	s_nop 0
	global_load_lds_dwordx4 v[148:149], off
	v_lshl_add_u64 v[148:149], v[192:193], 0, s[60:61]
	s_add_i32 m0, s8, 0x2000
	s_nop 0
	global_load_lds_dwordx4 v[148:149], off
	s_mov_b32 m0, s67
	v_lshl_add_u64 v[148:149], v[194:195], 0, s[60:61]
	ds_read_b128 v[184:187], v171 offset:49152
	ds_read_b128 v[188:191], v171 offset:50176
	ds_read_b128 v[196:199], v171 offset:51200
	ds_read_b128 v[200:203], v171 offset:52224
	ds_read_b128 v[204:207], v171 offset:53248
	ds_read_b128 v[208:211], v171 offset:54272
	ds_read_b128 v[212:215], v171 offset:55296
	ds_read_b128 v[222:225], v171 offset:56320
	global_load_lds_dwordx4 v[148:149], off
	v_lshl_add_u64 v[148:149], v[216:217], 0, s[60:61]
	s_mov_b32 m0, s2
	s_nop 0
	global_load_lds_dwordx4 v[148:149], off
	s_add_i32 s8, s9, s39
	v_lshl_add_u64 v[148:149], v[242:243], 0, s[60:61]
	s_mov_b32 m0, s8
	s_nop 0
	global_load_lds_dwordx4 v[148:149], off
	v_lshl_add_u64 v[148:149], v[244:245], 0, s[60:61]
	s_add_i32 m0, s8, 0x2000
	s_nop 0
	global_load_lds_dwordx4 v[148:149], off
	s_waitcnt vmcnt(8)
	s_waitcnt lgkmcnt(0)
	v_mfma_f32_16x16x32_bf16 v[62:65], v[144:147], v[184:187], v[62:65]
	v_mfma_f32_16x16x32_bf16 v[58:61], v[176:179], v[184:187], v[58:61]
	s_barrier
	s_setprio 1
	v_mfma_f32_16x16x32_bf16 v[50:53], v[144:147], v[196:199], v[50:53]
	v_mfma_f32_16x16x32_bf16 v[42:45], v[176:179], v[196:199], v[42:45]
	v_mfma_f32_16x16x32_bf16 v[34:37], v[144:147], v[204:207], v[34:37]
	v_mfma_f32_16x16x32_bf16 v[26:29], v[176:179], v[204:207], v[26:29]
	v_mfma_f32_16x16x32_bf16 v[18:21], v[144:147], v[212:215], v[18:21]
	v_mfma_f32_16x16x32_bf16 v[10:13], v[176:179], v[212:215], v[10:13]
	v_mfma_f32_16x16x32_bf16 v[62:65], v[172:175], v[188:191], v[62:65]
	v_mfma_f32_16x16x32_bf16 v[58:61], v[180:183], v[188:191], v[58:61]
	v_mfma_f32_16x16x32_bf16 v[50:53], v[172:175], v[200:203], v[50:53]
	v_mfma_f32_16x16x32_bf16 v[42:45], v[180:183], v[200:203], v[42:45]
	v_mfma_f32_16x16x32_bf16 v[34:37], v[172:175], v[208:211], v[34:37]
	v_mfma_f32_16x16x32_bf16 v[26:29], v[180:183], v[208:211], v[26:29]
	v_mfma_f32_16x16x32_bf16 v[18:21], v[172:175], v[222:225], v[18:21]
	v_mfma_f32_16x16x32_bf16 v[10:13], v[180:183], v[222:225], v[10:13]
	v_mfma_f32_16x16x32_bf16 v[54:57], v[226:229], v[184:187], v[54:57]
	v_mfma_f32_16x16x32_bf16 v[46:49], v[234:237], v[184:187], v[46:49]
	v_mfma_f32_16x16x32_bf16 v[38:41], v[226:229], v[196:199], v[38:41]
	v_mfma_f32_16x16x32_bf16 v[30:33], v[234:237], v[196:199], v[30:33]
	v_mfma_f32_16x16x32_bf16 v[22:25], v[226:229], v[204:207], v[22:25]
	v_mfma_f32_16x16x32_bf16 v[14:17], v[234:237], v[204:207], v[14:17]
	v_mfma_f32_16x16x32_bf16 v[6:9], v[226:229], v[212:215], v[6:9]
	v_mfma_f32_16x16x32_bf16 v[2:5], v[234:237], v[212:215], v[2:5]
	v_mfma_f32_16x16x32_bf16 v[54:57], v[230:233], v[188:191], v[54:57]
	v_mfma_f32_16x16x32_bf16 v[46:49], v[238:241], v[188:191], v[46:49]
	v_mfma_f32_16x16x32_bf16 v[38:41], v[230:233], v[200:203], v[38:41]
	v_mfma_f32_16x16x32_bf16 v[30:33], v[238:241], v[200:203], v[30:33]
	v_mfma_f32_16x16x32_bf16 v[22:25], v[230:233], v[208:211], v[22:25]
	v_mfma_f32_16x16x32_bf16 v[14:17], v[238:241], v[208:211], v[14:17]
	v_mfma_f32_16x16x32_bf16 v[6:9], v[230:233], v[222:225], v[6:9]
	v_mfma_f32_16x16x32_bf16 v[2:5], v[238:241], v[222:225], v[2:5]
	s_setprio 0
	s_add_u32 s92, s92, 0x100
	s_addc_u32 s93, s93, 0
	s_add_u32 s34, s34, 0x100
	s_addc_u32 s35, s35, 0
	s_cmp_ge_u32 s14, s73
	s_mov_b32 s66, s14
	s_barrier
	s_cbranch_scc0 .LBB0_400
	v_and_b32_e32 v144, 64, v220
	v_or_b32_e32 v144, v144, v150
	v_lshlrev_b32_e32 v172, 2, v144
	ds_bpermute_b32 v145, v172, v143
	ds_bpermute_b32 v144, v172, v143 offset:64
	s_mov_b32 s8, 0x3a000000
	v_mov_b32_e32 v232, 0x358637bd
	s_mov_b32 s97, 0x800000
	ds_bpermute_b32 v147, v172, v143 offset:128
	s_waitcnt lgkmcnt(0)
	v_pk_fma_f32 v[148:149], v[144:145], s[8:9], v[232:233] op_sel_hi:[1,0,0]
	ds_bpermute_b32 v146, v172, v143 offset:192
	v_mul_f32_e32 v143, 0x4b800000, v149
	v_cmp_gt_f32_e32 vcc, s97, v149
	v_max_f32_e32 v174, v128, v128
	v_max_f32_e32 v175, v124, v124
	v_cndmask_b32_e32 v143, v149, v143, vcc
	v_rsq_f32_e32 v149, v143
	v_max_f32_e32 v176, v116, v116
	ds_bpermute_b32 v145, v172, v142
	ds_bpermute_b32 v144, v172, v142 offset:64
	v_mul_f32_e32 v173, 0x45800000, v149
	v_cndmask_b32_e32 v149, v149, v173, vcc
	v_max_f32_e32 v173, v129, v129
	v_max_f32_e32 v173, v174, v173
	v_max_f32_e32 v174, v125, v125
	v_max_f32_e32 v174, v175, v174
	v_max3_f32 v173, v126, v127, v173
	v_max3_f32 v174, v122, v123, v174
	v_max3_f32 v173, v173, s72, v174
	v_max_f32_e32 v174, v121, v121
	v_max_f32_e32 v175, v120, v120
	v_max_f32_e32 v174, v175, v174
	v_max_f32_e32 v175, v117, v117
	v_max_f32_e32 v175, v176, v175
	v_cmp_lt_i32_e32 vcc, v221, v247
	v_max3_f32 v174, v118, v119, v174
	v_max3_f32 v175, v114, v115, v175
	v_cndmask_b32_e64 v177, v149, 1.0, s[80:81]
	v_cndmask_b32_e32 v149, v220, v221, vcc
	v_max3_f32 v173, v173, v174, v175
	v_lshlrev_b32_e32 v149, 2, v149
	v_mul_f32_e32 v173, v173, v177
	ds_bpermute_b32 v174, v149, v173
	v_cmp_lt_i32_e32 vcc, v248, v247
	ds_bpermute_b32 v143, v172, v142 offset:128
	ds_bpermute_b32 v142, v172, v142 offset:192
	v_cndmask_b32_e32 v172, v220, v248, vcc
	s_waitcnt lgkmcnt(0)
	v_max_f32_e32 v174, v174, v174
	v_lshlrev_b32_e32 v172, 2, v172
	v_max_f32_e32 v173, v173, v174
	ds_bpermute_b32 v174, v172, v173
	v_cmp_gt_f32_e32 vcc, s97, v148
	v_add_u32_e32 v178, s51, v154
	s_and_saveexec_b64 s[92:93], s[0:1]
	s_cbranch_execz .LBB0_403
	s_waitcnt lgkmcnt(0)
	v_max_f32_e32 v174, v174, v174
	v_max_f32_e32 v173, v173, v173
	v_max_f32_e32 v173, v173, v174
	ds_write_b32 v178, v173

; #define PG8_STAGE(bufoff, gbase, voff) do { _Pragma("unroll") for (int _i = 0; _i < 2; ++_i) \
;         __builtin_amdgcn_global_load_lds((const unsigned*)((const char*)(gbase) + (voff)[_i]), (LAS unsigned*)(lds + (bufoff) + ldsw + _i * 8192), 16, 0, 0); } while (0)
; #define PG8_LDA(dst, b, h) do { _Pragma("unroll") for (int m = 0; m < 4; ++m) _Pragma("unroll") for (int k = 0; k < 2; ++k) dst[m][k] = *(const LAS bf16x8*)(lds + PG8_SA(b, h) + aoff + m * 2048 + k * 1024); } while (0)
; #define PG8_LDB(dst, b, h) do { _Pragma("unroll") for (int n = 0; n < 2; ++n) _Pragma("unroll") for (int k = 0; k < 2; ++k) dst[n][k] = *(const LAS bf16x8*)(lds + PG8_SB(b, h) + boff + n * 2048 + k * 1024); } while (0)
; #define PG8_MMA(ai, bj, At, Bt) do { __builtin_amdgcn_s_setprio(1); _Pragma("unroll") for (int m = 0; m < 4; ++m) _Pragma("unroll") for (int n = 0; n < 2; ++n) _Pragma("unroll") for (int k = 0; k < 2; ++k) \
;         acc[ai][bj][m][n] = __builtin_amdgcn_mfma_f32_16x16x32_bf16(Bt[n][k], At[m][k], acc[ai][bj][m][n], 0, 0, 0); __builtin_amdgcn_s_setprio(0); } while (0)
; #define PG8_WAIT_V(n) asm volatile("s_waitcnt vmcnt(" #n ")" ::: "memory")
; #define PG8_WAIT_L(n) asm volatile("s_waitcnt lgkmcnt(" #n ")" ::: "memory")
; template <class Epi>
; __device__ __forceinline__ void gemm_phase(LAS unsigned char* lds, const Gemm g, const Sched& S, const Epi& E) {
;     ...
;         for (int t = 0; t < nt; t += 2) {
;             const bool last = (t == nt - 2);
;             const char* a1 = cA + (size_t)(t + 1) * kstep;
;             const char* a2 = last ? nA : cA + (size_t)(t + 2) * kstep; const char* b2 = last ? nB : cB + (size_t)(t + 2) * kstep;
;             const char* a3 = a2 + kstep; const char* b3 = b2 + kstep;
;             PG8_LDB(B0, 0, 0); PG8_SCHED; PG8_LDA(At, 0, 0); PG8_STAGE(PG8_SA(1, 1), a1 + hstepA, voffA);
;             PG8_WAIT_L(8); PG8_BAR; PG8_WAIT_L(0); PG8_MMA(0, 0, At, B0); PG8_BAR; PG8_SCHED;
;             PG8_LDB(B1, 0, 1); PG8_STAGE(PG8_SB(0, 0), b2, voffB);
;             PG8_BAR; PG8_WAIT_L(0); PG8_MMA(0, 1, At, B1); PG8_BAR;
;             PG8_LDA(At, 0, 1); PG8_STAGE(PG8_SA(0, 0), a2, voffA);
;             PG8_BAR; PG8_WAIT_L(0); PG8_MMA(1, 0, At, B0); PG8_BAR; PG8_SCHED;
;             PG8_STAGE(PG8_SB(0, 1), b2 + hstepB, voffB);
;             PG8_WAIT_V(6); PG8_BAR; PG8_MMA(1, 1, At, B1); PG8_BAR;
.LBB0_461:
	s_add_i32 s14, s88, 2
	s_add_u32 s8, s4, 0x80
	s_addc_u32 s9, s5, 0
	s_add_i32 s15, 0, 0x10000
	v_add_u32_e32 v114, s15, v211
	ds_read_b128 v[82:85], v114
	ds_read_b128 v[94:97], v114 offset:1024
	ds_read_b128 v[98:101], v114 offset:2048
	ds_read_b128 v[114:117], v114 offset:3072
	s_cmp_eq_u32 s42, s88
	s_cselect_b32 s88, s57, s8
	s_cselect_b32 s89, s71, s9
	s_cselect_b32 s91, s59, s35
	s_cselect_b32 s90, s72, s34
	v_lshl_add_u64 v[178:179], s[4:5], 0, v[202:203]
	s_add_i32 m0, s24, 0xc000
	ds_read_b128 v[122:125], v213
	ds_read_b128 v[130:133], v213 offset:1024
	ds_read_b128 v[146:149], v213 offset:2048
	ds_read_b128 v[150:153], v213 offset:3072
	ds_read_b128 v[162:165], v213 offset:4096
	ds_read_b128 v[166:169], v213 offset:5120
	ds_read_b128 v[170:173], v213 offset:6144
	ds_read_b128 v[174:177], v213 offset:7168
	global_load_lds_dwordx4 v[178:179], off
	v_lshl_add_u64 v[178:179], s[4:5], 0, v[204:205]
	s_add_i32 m0, s24, 0xe000
	s_nop 0
	global_load_lds_dwordx4 v[178:179], off
	s_add_i32 s8, 0, 0x14000
	v_add_u32_e32 v190, s8, v211
	ds_read_b128 v[178:181], v190
	ds_read_b128 v[182:185], v190 offset:1024
	ds_read_b128 v[186:189], v190 offset:2048
	ds_read_b128 v[190:193], v190 offset:3072
	s_waitcnt vmcnt(8)
	s_waitcnt lgkmcnt(0)
	v_mfma_f32_16x16x32_bf16 v[158:161], v[82:85], v[122:125], v[158:161]
	v_mfma_f32_16x16x32_bf16 v[154:157], v[98:101], v[122:125], v[154:157]
	s_barrier
	s_setprio 1
	v_mfma_f32_16x16x32_bf16 v[134:137], v[82:85], v[146:149], v[134:137]
	v_mfma_f32_16x16x32_bf16 v[126:129], v[98:101], v[146:149], v[126:129]
	v_mfma_f32_16x16x32_bf16 v[106:109], v[82:85], v[162:165], v[106:109]
	v_mfma_f32_16x16x32_bf16 v[102:105], v[98:101], v[162:165], v[102:105]
	v_mfma_f32_16x16x32_bf16 v[78:81], v[82:85], v[170:173], v[78:81]
	v_mfma_f32_16x16x32_bf16 v[74:77], v[98:101], v[170:173], v[74:77]
	v_mfma_f32_16x16x32_bf16 v[158:161], v[94:97], v[130:133], v[158:161]
	v_mfma_f32_16x16x32_bf16 v[154:157], v[114:117], v[130:133], v[154:157]
	v_mfma_f32_16x16x32_bf16 v[134:137], v[94:97], v[150:153], v[134:137]
	v_mfma_f32_16x16x32_bf16 v[126:129], v[114:117], v[150:153], v[126:129]
	v_mfma_f32_16x16x32_bf16 v[106:109], v[94:97], v[166:169], v[106:109]
	v_mfma_f32_16x16x32_bf16 v[102:105], v[114:117], v[166:169], v[102:105]
	v_mfma_f32_16x16x32_bf16 v[78:81], v[94:97], v[174:177], v[78:81]
	v_mfma_f32_16x16x32_bf16 v[74:77], v[114:117], v[174:177], v[74:77]
	v_mfma_f32_16x16x32_bf16 v[142:145], v[178:181], v[122:125], v[142:145]
	v_mfma_f32_16x16x32_bf16 v[118:121], v[178:181], v[146:149], v[118:121]
	v_mfma_f32_16x16x32_bf16 v[110:113], v[186:189], v[146:149], v[110:113]
	v_mfma_f32_16x16x32_bf16 v[90:93], v[178:181], v[162:165], v[90:93]
	v_mfma_f32_16x16x32_bf16 v[86:89], v[186:189], v[162:165], v[86:89]
	v_mfma_f32_16x16x32_bf16 v[70:73], v[178:181], v[170:173], v[70:73]
	v_mfma_f32_16x16x32_bf16 v[66:69], v[186:189], v[170:173], v[66:69]
	v_mfma_f32_16x16x32_bf16 v[142:145], v[182:185], v[130:133], v[142:145]
	v_mfma_f32_16x16x32_bf16 v[122:125], v[186:189], v[122:125], v[138:141]
	v_mfma_f32_16x16x32_bf16 v[118:121], v[182:185], v[150:153], v[118:121]
	v_mfma_f32_16x16x32_bf16 v[110:113], v[190:193], v[150:153], v[110:113]
	v_mfma_f32_16x16x32_bf16 v[90:93], v[182:185], v[166:169], v[90:93]
	v_mfma_f32_16x16x32_bf16 v[86:89], v[190:193], v[166:169], v[86:89]
	v_mfma_f32_16x16x32_bf16 v[70:73], v[182:185], v[174:177], v[70:73]
	v_mfma_f32_16x16x32_bf16 v[66:69], v[190:193], v[174:177], v[66:69]
	v_mfma_f32_16x16x32_bf16 v[122:125], v[190:193], v[130:133], v[122:125]
	s_setprio 0
	s_barrier
	s_add_i32 s9, s15, s3
	v_lshl_add_u64 v[194:195], s[90:91], 0, v[0:1]
	s_mov_b32 m0, s9
	s_nop 0
	global_load_lds_dwordx4 v[194:195], off
	v_lshl_add_u64 v[206:207], s[90:91], 0, v[200:201]
	s_add_i32 m0, s9, 0x2000
	s_nop 0
	global_load_lds_dwordx4 v[206:207], off
	s_mov_b32 m0, s24
	v_lshl_add_u64 v[208:209], s[88:89], 0, v[196:197]
	ds_read_b128 v[130:133], v213 offset:16384
	ds_read_b128 v[138:141], v213 offset:17408
	ds_read_b128 v[146:149], v213 offset:18432
	ds_read_b128 v[150:153], v213 offset:19456
	ds_read_b128 v[162:165], v213 offset:20480
	ds_read_b128 v[166:169], v213 offset:21504
	ds_read_b128 v[170:173], v213 offset:22528
	ds_read_b128 v[174:177], v213 offset:23552
	global_load_lds_dwordx4 v[208:209], off
	v_lshl_add_u64 v[214:215], s[88:89], 0, v[198:199]
	s_mov_b32 m0, s33
	s_nop 0
	global_load_lds_dwordx4 v[214:215], off
	s_add_u32 s90, s90, s78
	s_addc_u32 s91, s91, s79
	s_add_i32 s8, s8, s3
	v_lshl_add_u64 v[216:217], s[90:91], 0, v[0:1]
	s_mov_b32 m0, s8
	v_lshl_add_u64 v[222:223], s[90:91], 0, v[200:201]
	global_load_lds_dwordx4 v[216:217], off
	s_add_i32 m0, s8, 0x2000
	s_nop 0
	global_load_lds_dwordx4 v[222:223], off
	s_waitcnt vmcnt(8)
	s_waitcnt lgkmcnt(0)
	v_mfma_f32_16x16x32_bf16 v[62:65], v[82:85], v[130:133], v[62:65]
	v_mfma_f32_16x16x32_bf16 v[58:61], v[98:101], v[130:133], v[58:61]
	s_barrier
; #define PG8_STAGE(bufoff, gbase, voff) do { _Pragma("unroll") for (int _i = 0; _i < 2; ++_i) \
;         __builtin_amdgcn_global_load_lds((const unsigned*)((const char*)(gbase) + (voff)[_i]), (LAS unsigned*)(lds + (bufoff) + ldsw + _i * 8192), 16, 0, 0); } while (0)
; #define PG8_LDA(dst, b, h) do { _Pragma("unroll") for (int m = 0; m < 4; ++m) _Pragma("unroll") for (int k = 0; k < 2; ++k) dst[m][k] = *(const LAS bf16x8*)(lds + PG8_SA(b, h) + aoff + m * 2048 + k * 1024); } while (0)
; #define PG8_LDB(dst, b, h) do { _Pragma("unroll") for (int n = 0; n < 2; ++n) _Pragma("unroll") for (int k = 0; k < 2; ++k) dst[n][k] = *(const LAS bf16x8*)(lds + PG8_SB(b, h) + boff + n * 2048 + k * 1024); } while (0)
; #define PG8_WAIT_V(n) asm volatile("s_waitcnt vmcnt(" #n ")" ::: "memory")
; #define PG8_WAIT_L(n) asm volatile("s_waitcnt lgkmcnt(" #n ")" ::: "memory")
; #define PG8_BAR __builtin_amdgcn_s_barrier()
; #define PG8_SCHED __builtin_amdgcn_sched_barrier(0)
; template <class Epi>
; __device__ __forceinline__ void gemm_phase(LAS unsigned char* lds, const Gemm g, const Sched& S, const Epi& E) {
;     ...
;             PG8_LDB(B0, 0, 0); PG8_SCHED; PG8_LDA(At, 0, 0); PG8_STAGE(PG8_SA(1, 1), a1 + hstepA, voffA);
;             PG8_WAIT_L(8); PG8_BAR; PG8_WAIT_L(0); PG8_MMA(0, 0, At, B0); PG8_BAR; PG8_SCHED;
;             PG8_LDB(B1, 0, 1); PG8_STAGE(PG8_SB(0, 0), b2, voffB);
;             PG8_BAR; PG8_WAIT_L(0); PG8_MMA(0, 1, At, B1); PG8_BAR;
;             PG8_LDA(At, 0, 1); PG8_STAGE(PG8_SA(0, 0), a2, voffA);
;             PG8_BAR; PG8_WAIT_L(0); PG8_MMA(1, 0, At, B0); PG8_BAR; PG8_SCHED;
;             PG8_STAGE(PG8_SB(0, 1), b2 + hstepB, voffB);
;             PG8_WAIT_V(6); PG8_BAR; PG8_MMA(1, 1, At, B1); PG8_BAR;
;             PG8_LDB(B0, 1, 0); PG8_SCHED; PG8_LDA(At, 1, 0); PG8_STAGE(PG8_SA(0, 1), a2 + hstepA, voffA);
;             PG8_WAIT_L(8); PG8_BAR; PG8_WAIT_L(0); PG8_MMA(0, 0, At, B0); PG8_BAR; PG8_SCHED;
;             PG8_LDB(B1, 1, 1); PG8_STAGE(PG8_SB(1, 0), b3, voffB);
;             PG8_BAR; PG8_WAIT_L(0); PG8_MMA(0, 1, At, B1); PG8_BAR;
;             PG8_LDA(At, 1, 1); PG8_STAGE(PG8_SA(1, 0), a3, voffA);
;             PG8_BAR; PG8_WAIT_L(0); PG8_MMA(1, 0, At, B0); PG8_BAR; PG8_SCHED;
;             PG8_STAGE(PG8_SB(1, 1), b3 + hstepB, voffB);
;             PG8_WAIT_V(6); PG8_BAR; PG8_MMA(1, 1, At, B1); PG8_BAR;
	s_setprio 1
	v_mfma_f32_16x16x32_bf16 v[46:49], v[82:85], v[146:149], v[46:49]
	v_mfma_f32_16x16x32_bf16 v[42:45], v[98:101], v[146:149], v[42:45]
	v_mfma_f32_16x16x32_bf16 v[30:33], v[82:85], v[162:165], v[30:33]
	v_mfma_f32_16x16x32_bf16 v[26:29], v[98:101], v[162:165], v[26:29]
	v_mfma_f32_16x16x32_bf16 v[14:17], v[82:85], v[170:173], v[14:17]
	v_mfma_f32_16x16x32_bf16 v[10:13], v[98:101], v[170:173], v[10:13]
	v_mfma_f32_16x16x32_bf16 v[62:65], v[94:97], v[138:141], v[62:65]
	v_mfma_f32_16x16x32_bf16 v[58:61], v[114:117], v[138:141], v[58:61]
	v_mfma_f32_16x16x32_bf16 v[46:49], v[94:97], v[150:153], v[46:49]
	v_mfma_f32_16x16x32_bf16 v[42:45], v[114:117], v[150:153], v[42:45]
	v_mfma_f32_16x16x32_bf16 v[30:33], v[94:97], v[166:169], v[30:33]
	v_mfma_f32_16x16x32_bf16 v[26:29], v[114:117], v[166:169], v[26:29]
	v_mfma_f32_16x16x32_bf16 v[14:17], v[94:97], v[174:177], v[14:17]
	v_mfma_f32_16x16x32_bf16 v[10:13], v[114:117], v[174:177], v[10:13]
	v_mfma_f32_16x16x32_bf16 v[54:57], v[178:181], v[130:133], v[54:57]
	v_mfma_f32_16x16x32_bf16 v[50:53], v[186:189], v[130:133], v[50:53]
	v_mfma_f32_16x16x32_bf16 v[38:41], v[178:181], v[146:149], v[38:41]
	v_mfma_f32_16x16x32_bf16 v[34:37], v[186:189], v[146:149], v[34:37]
	v_mfma_f32_16x16x32_bf16 v[22:25], v[178:181], v[162:165], v[22:25]
	v_mfma_f32_16x16x32_bf16 v[18:21], v[186:189], v[162:165], v[18:21]
	v_mfma_f32_16x16x32_bf16 v[6:9], v[178:181], v[170:173], v[6:9]
	v_mfma_f32_16x16x32_bf16 v[2:5], v[186:189], v[170:173], v[2:5]
	v_mfma_f32_16x16x32_bf16 v[54:57], v[182:185], v[138:141], v[54:57]
	v_mfma_f32_16x16x32_bf16 v[50:53], v[190:193], v[138:141], v[50:53]
	v_mfma_f32_16x16x32_bf16 v[38:41], v[182:185], v[150:153], v[38:41]
	v_mfma_f32_16x16x32_bf16 v[34:37], v[190:193], v[150:153], v[34:37]
	v_mfma_f32_16x16x32_bf16 v[22:25], v[182:185], v[166:169], v[22:25]
	v_mfma_f32_16x16x32_bf16 v[18:21], v[190:193], v[166:169], v[18:21]
	v_mfma_f32_16x16x32_bf16 v[6:9], v[182:185], v[174:177], v[6:9]
	v_mfma_f32_16x16x32_bf16 v[2:5], v[190:193], v[174:177], v[2:5]
	s_setprio 0
	s_barrier
	s_add_i32 s8, 0, 0x18000
	v_add_u32_e32 v114, s8, v211
	ds_read_b128 v[82:85], v114
	ds_read_b128 v[94:97], v114 offset:1024
	ds_read_b128 v[98:101], v114 offset:2048
	ds_read_b128 v[114:117], v114 offset:3072
	s_add_u32 s88, s88, s36
	s_addc_u32 s89, s89, s37
	s_mov_b32 m0, s38
	v_lshl_add_u64 v[178:179], s[88:89], 0, v[196:197]
	ds_read_b128 v[130:133], v213 offset:32768
	ds_read_b128 v[138:141], v213 offset:33792
	ds_read_b128 v[146:149], v213 offset:34816
	ds_read_b128 v[150:153], v213 offset:35840
	ds_read_b128 v[162:165], v213 offset:36864
	ds_read_b128 v[166:169], v213 offset:37888
	ds_read_b128 v[170:173], v213 offset:38912
	ds_read_b128 v[174:177], v213 offset:39936
	global_load_lds_dwordx4 v[178:179], off
	v_lshl_add_u64 v[178:179], s[88:89], 0, v[198:199]
	s_mov_b32 m0, s39
	s_nop 0
	global_load_lds_dwordx4 v[178:179], off
	s_add_i32 s9, 0, 0x1c000
	v_add_u32_e32 v190, s9, v211
	ds_read_b128 v[178:181], v190
	ds_read_b128 v[182:185], v190 offset:1024
	ds_read_b128 v[186:189], v190 offset:2048
	ds_read_b128 v[190:193], v190 offset:3072
	s_waitcnt vmcnt(8)
	s_waitcnt lgkmcnt(0)
	v_mfma_f32_16x16x32_bf16 v[158:161], v[82:85], v[130:133], v[158:161]
	v_mfma_f32_16x16x32_bf16 v[154:157], v[98:101], v[130:133], v[154:157]
	s_barrier
	s_setprio 1
	v_mfma_f32_16x16x32_bf16 v[134:137], v[82:85], v[146:149], v[134:137]
	v_mfma_f32_16x16x32_bf16 v[126:129], v[98:101], v[146:149], v[126:129]
	v_mfma_f32_16x16x32_bf16 v[106:109], v[82:85], v[162:165], v[106:109]
	v_mfma_f32_16x16x32_bf16 v[102:105], v[98:101], v[162:165], v[102:105]
	v_mfma_f32_16x16x32_bf16 v[78:81], v[82:85], v[170:173], v[78:81]
	v_mfma_f32_16x16x32_bf16 v[74:77], v[98:101], v[170:173], v[74:77]
	v_mfma_f32_16x16x32_bf16 v[158:161], v[94:97], v[138:141], v[158:161]
	v_mfma_f32_16x16x32_bf16 v[154:157], v[114:117], v[138:141], v[154:157]
	v_mfma_f32_16x16x32_bf16 v[134:137], v[94:97], v[150:153], v[134:137]
	v_mfma_f32_16x16x32_bf16 v[126:129], v[114:117], v[150:153], v[126:129]
	v_mfma_f32_16x16x32_bf16 v[106:109], v[94:97], v[166:169], v[106:109]
	v_mfma_f32_16x16x32_bf16 v[102:105], v[114:117], v[166:169], v[102:105]
	v_mfma_f32_16x16x32_bf16 v[78:81], v[94:97], v[174:177], v[78:81]
	v_mfma_f32_16x16x32_bf16 v[74:77], v[114:117], v[174:177], v[74:77]
	v_mfma_f32_16x16x32_bf16 v[142:145], v[178:181], v[130:133], v[142:145]
	v_mfma_f32_16x16x32_bf16 v[122:125], v[186:189], v[130:133], v[122:125]
	v_mfma_f32_16x16x32_bf16 v[118:121], v[178:181], v[146:149], v[118:121]
	v_mfma_f32_16x16x32_bf16 v[110:113], v[186:189], v[146:149], v[110:113]
	v_mfma_f32_16x16x32_bf16 v[90:93], v[178:181], v[162:165], v[90:93]
	v_mfma_f32_16x16x32_bf16 v[86:89], v[186:189], v[162:165], v[86:89]
	v_mfma_f32_16x16x32_bf16 v[70:73], v[178:181], v[170:173], v[70:73]
	v_mfma_f32_16x16x32_bf16 v[66:69], v[186:189], v[170:173], v[66:69]
	v_mfma_f32_16x16x32_bf16 v[142:145], v[182:185], v[138:141], v[142:145]
	v_mfma_f32_16x16x32_bf16 v[138:141], v[190:193], v[138:141], v[122:125]
	v_mfma_f32_16x16x32_bf16 v[118:121], v[182:185], v[150:153], v[118:121]
	v_mfma_f32_16x16x32_bf16 v[110:113], v[190:193], v[150:153], v[110:113]
	v_mfma_f32_16x16x32_bf16 v[90:93], v[182:185], v[166:169], v[90:93]
	v_mfma_f32_16x16x32_bf16 v[86:89], v[190:193], v[166:169], v[86:89]
	v_mfma_f32_16x16x32_bf16 v[70:73], v[182:185], v[174:177], v[70:73]
	v_mfma_f32_16x16x32_bf16 v[66:69], v[190:193], v[174:177], v[66:69]
	s_setprio 0
	s_barrier
; #define PG8_STAGE(bufoff, gbase, voff) do { _Pragma("unroll") for (int _i = 0; _i < 2; ++_i) \
;         __builtin_amdgcn_global_load_lds((const unsigned*)((const char*)(gbase) + (voff)[_i]), (LAS unsigned*)(lds + (bufoff) + ldsw + _i * 8192), 16, 0, 0); } while (0)
; #define PG8_LDA(dst, b, h) do { _Pragma("unroll") for (int m = 0; m < 4; ++m) _Pragma("unroll") for (int k = 0; k < 2; ++k) dst[m][k] = *(const LAS bf16x8*)(lds + PG8_SA(b, h) + aoff + m * 2048 + k * 1024); } while (0)
; #define PG8_LDB(dst, b, h) do { _Pragma("unroll") for (int n = 0; n < 2; ++n) _Pragma("unroll") for (int k = 0; k < 2; ++k) dst[n][k] = *(const LAS bf16x8*)(lds + PG8_SB(b, h) + boff + n * 2048 + k * 1024); } while (0)
; #define PG8_WAIT_V(n) asm volatile("s_waitcnt vmcnt(" #n ")" ::: "memory")
; #define PG8_WAIT_L(n) asm volatile("s_waitcnt lgkmcnt(" #n ")" ::: "memory")
; #define PG8_BAR __builtin_amdgcn_s_barrier()
; #define PG8_SCHED __builtin_amdgcn_sched_barrier(0)
; template <class Epi>
; __device__ __forceinline__ void gemm_phase(LAS unsigned char* lds, const Gemm g, const Sched& S, const Epi& E) {
;     ...
;             PG8_LDB(B0, 1, 0); PG8_SCHED; PG8_LDA(At, 1, 0); PG8_STAGE(PG8_SA(0, 1), a2 + hstepA, voffA);
;             PG8_WAIT_L(8); PG8_BAR; PG8_WAIT_L(0); PG8_MMA(0, 0, At, B0); PG8_BAR; PG8_SCHED;
;             PG8_LDB(B1, 1, 1); PG8_STAGE(PG8_SB(1, 0), b3, voffB);
;             PG8_BAR; PG8_WAIT_L(0); PG8_MMA(0, 1, At, B1); PG8_BAR;
;             PG8_LDA(At, 1, 1); PG8_STAGE(PG8_SA(1, 0), a3, voffA);
;             PG8_BAR; PG8_WAIT_L(0); PG8_MMA(1, 0, At, B0); PG8_BAR; PG8_SCHED;
;             PG8_STAGE(PG8_SB(1, 1), b3 + hstepB, voffB);
;             PG8_WAIT_V(6); PG8_BAR; PG8_MMA(1, 1, At, B1); PG8_BAR;
;         }
;     __device__ __forceinline__ void operator()(const Acc& acc, const Unit& u, int wr, int wc, int fr, int fq, const Pre& pre) const {
;         const int row0 = u.pm * 256 + wr * 64 + fr, col0 = u.pn * 256 + wc * 32 + 8 * fq;
; #pragma unroll
;         for (int ai = 0; ai < 2; ++ai) {
;             u32x4 gw[4][2], pw[4][2];
; #pragma unroll
;             for (int m = 0; m < 4; ++m)
; #pragma unroll
;                 for (int bj = 0; bj < 2; ++bj) { const size_t off = (size_t)(row0 + ai * 128 + m * 16) * ldc + col0 + bj * 128;
;                     gw[m][bj] = *(const u32x4*)(gate + off); if (add) pw[m][bj] = *(const u32x4*)(O + off); }
	s_add_i32 s8, s8, s3
	v_lshl_add_u64 v[194:195], v[194:195], 0, s[60:61]
	s_mov_b32 m0, s8
	s_nop 0
	global_load_lds_dwordx4 v[194:195], off
	v_lshl_add_u64 v[194:195], v[206:207], 0, s[60:61]
	s_add_i32 m0, s8, 0x2000
	s_nop 0
	global_load_lds_dwordx4 v[194:195], off
	s_mov_b32 m0, s40
	v_lshl_add_u64 v[194:195], v[208:209], 0, s[60:61]
	ds_read_b128 v[122:125], v213 offset:49152
	ds_read_b128 v[130:133], v213 offset:50176
	ds_read_b128 v[146:149], v213 offset:51200
	ds_read_b128 v[150:153], v213 offset:52224
	ds_read_b128 v[162:165], v213 offset:53248
	ds_read_b128 v[166:169], v213 offset:54272
	ds_read_b128 v[170:173], v213 offset:55296
	ds_read_b128 v[174:177], v213 offset:56320
	global_load_lds_dwordx4 v[194:195], off
	v_lshl_add_u64 v[194:195], v[214:215], 0, s[60:61]
	s_mov_b32 m0, s41
	s_nop 0
	global_load_lds_dwordx4 v[194:195], off
	s_add_i32 s8, s9, s3
	v_lshl_add_u64 v[194:195], v[216:217], 0, s[60:61]
	s_mov_b32 m0, s8
	s_nop 0
	global_load_lds_dwordx4 v[194:195], off
	v_lshl_add_u64 v[194:195], v[222:223], 0, s[60:61]
	s_add_i32 m0, s8, 0x2000
	s_nop 0
	global_load_lds_dwordx4 v[194:195], off
	s_waitcnt vmcnt(8)
	s_waitcnt lgkmcnt(0)
	v_mfma_f32_16x16x32_bf16 v[62:65], v[82:85], v[122:125], v[62:65]
	v_mfma_f32_16x16x32_bf16 v[58:61], v[98:101], v[122:125], v[58:61]
	s_barrier
	s_setprio 1
	v_mfma_f32_16x16x32_bf16 v[46:49], v[82:85], v[146:149], v[46:49]
	v_mfma_f32_16x16x32_bf16 v[42:45], v[98:101], v[146:149], v[42:45]
	v_mfma_f32_16x16x32_bf16 v[30:33], v[82:85], v[162:165], v[30:33]
	v_mfma_f32_16x16x32_bf16 v[26:29], v[98:101], v[162:165], v[26:29]
	v_mfma_f32_16x16x32_bf16 v[14:17], v[82:85], v[170:173], v[14:17]
	v_mfma_f32_16x16x32_bf16 v[10:13], v[98:101], v[170:173], v[10:13]
	v_mfma_f32_16x16x32_bf16 v[62:65], v[94:97], v[130:133], v[62:65]
	v_mfma_f32_16x16x32_bf16 v[58:61], v[114:117], v[130:133], v[58:61]
	v_mfma_f32_16x16x32_bf16 v[46:49], v[94:97], v[150:153], v[46:49]
	v_mfma_f32_16x16x32_bf16 v[42:45], v[114:117], v[150:153], v[42:45]
	v_mfma_f32_16x16x32_bf16 v[30:33], v[94:97], v[166:169], v[30:33]
	v_mfma_f32_16x16x32_bf16 v[26:29], v[114:117], v[166:169], v[26:29]
	v_mfma_f32_16x16x32_bf16 v[14:17], v[94:97], v[174:177], v[14:17]
	v_mfma_f32_16x16x32_bf16 v[10:13], v[114:117], v[174:177], v[10:13]
	v_mfma_f32_16x16x32_bf16 v[54:57], v[178:181], v[122:125], v[54:57]
	v_mfma_f32_16x16x32_bf16 v[50:53], v[186:189], v[122:125], v[50:53]
	v_mfma_f32_16x16x32_bf16 v[38:41], v[178:181], v[146:149], v[38:41]
	v_mfma_f32_16x16x32_bf16 v[34:37], v[186:189], v[146:149], v[34:37]
	v_mfma_f32_16x16x32_bf16 v[22:25], v[178:181], v[162:165], v[22:25]
	v_mfma_f32_16x16x32_bf16 v[18:21], v[186:189], v[162:165], v[18:21]
	v_mfma_f32_16x16x32_bf16 v[6:9], v[178:181], v[170:173], v[6:9]
	v_mfma_f32_16x16x32_bf16 v[2:5], v[186:189], v[170:173], v[2:5]
	v_mfma_f32_16x16x32_bf16 v[54:57], v[182:185], v[130:133], v[54:57]
	v_mfma_f32_16x16x32_bf16 v[50:53], v[190:193], v[130:133], v[50:53]
	v_mfma_f32_16x16x32_bf16 v[38:41], v[182:185], v[150:153], v[38:41]
	v_mfma_f32_16x16x32_bf16 v[34:37], v[190:193], v[150:153], v[34:37]
	v_mfma_f32_16x16x32_bf16 v[22:25], v[182:185], v[166:169], v[22:25]
	v_mfma_f32_16x16x32_bf16 v[18:21], v[190:193], v[166:169], v[18:21]
	v_mfma_f32_16x16x32_bf16 v[6:9], v[182:185], v[174:177], v[6:9]
	v_mfma_f32_16x16x32_bf16 v[2:5], v[190:193], v[174:177], v[2:5]
	s_setprio 0
	s_add_u32 s4, s4, 0x100
	s_addc_u32 s5, s5, 0
	s_add_u32 s34, s34, 0x100
	s_addc_u32 s35, s35, 0
	s_cmp_ge_u32 s14, s73
	s_mov_b32 s88, s14
	s_barrier
	s_cbranch_scc0 .LBB0_461
	v_lshl_add_u32 v214, s67, 8, v210
	v_lshl_or_b32 v206, s55, 8, v212
	v_ashrrev_i32_e32 v207, 31, v206
	v_ashrrev_i32_e32 v82, 31, v214
	v_mul_lo_u32 v215, s12, v82
	v_mul_lo_u32 v238, s13, v214
	v_mad_u64_u32 v[82:83], s[4:5], s12, v214, v[206:207]
	v_add3_u32 v83, v238, v83, v215
	v_lshl_add_u64 v[84:85], v[82:83], 1, s[6:7]
	global_load_dwordx4 v[190:193], v[84:85], off
	v_cndmask_b32_e64 v94, 0, 1, s[76:77]
	v_cmp_ne_u32_e64 s[4:5], 1, v94
	s_andn2_b64 vcc, exec, s[76:77]
	v_lshl_add_u64 v[82:83], v[82:83], 1, s[62:63]
	s_cbranch_vccnz .LBB0_464
	global_load_dwordx4 v[150:153], v[82:83], off

; #define PG8_STAGE(bufoff, gbase, voff) do { _Pragma("unroll") for (int _i = 0; _i < 2; ++_i) \
;         __builtin_amdgcn_global_load_lds((const unsigned*)((const char*)(gbase) + (voff)[_i]), (LAS unsigned*)(lds + (bufoff) + ldsw + _i * 8192), 16, 0, 0); } while (0)
; #define PG8_LDA(dst, b, h) do { _Pragma("unroll") for (int m = 0; m < 4; ++m) _Pragma("unroll") for (int k = 0; k < 2; ++k) dst[m][k] = *(const LAS bf16x8*)(lds + PG8_SA(b, h) + aoff + m * 2048 + k * 1024); } while (0)
; #define PG8_LDB(dst, b, h) do { _Pragma("unroll") for (int n = 0; n < 2; ++n) _Pragma("unroll") for (int k = 0; k < 2; ++k) dst[n][k] = *(const LAS bf16x8*)(lds + PG8_SB(b, h) + boff + n * 2048 + k * 1024); } while (0)
; #define PG8_MMA(ai, bj, At, Bt) do { __builtin_amdgcn_s_setprio(1); _Pragma("unroll") for (int m = 0; m < 4; ++m) _Pragma("unroll") for (int n = 0; n < 2; ++n) _Pragma("unroll") for (int k = 0; k < 2; ++k) \
;         acc[ai][bj][m][n] = __builtin_amdgcn_mfma_f32_16x16x32_bf16(Bt[n][k], At[m][k], acc[ai][bj][m][n], 0, 0, 0); __builtin_amdgcn_s_setprio(0); } while (0)
; #define PG8_WAIT_V(n) asm volatile("s_waitcnt vmcnt(" #n ")" ::: "memory")
; #define PG8_WAIT_L(n) asm volatile("s_waitcnt lgkmcnt(" #n ")" ::: "memory")
; template <class Epi>
; __device__ __forceinline__ void gemm_phase(LAS unsigned char* lds, const Gemm g, const Sched& S, const Epi& E) {
;     ...
;         for (int t = 0; t < nt; t += 2) {
;             const bool last = (t == nt - 2);
;             const char* a1 = cA + (size_t)(t + 1) * kstep;
;             const char* a2 = last ? nA : cA + (size_t)(t + 2) * kstep; const char* b2 = last ? nB : cB + (size_t)(t + 2) * kstep;
;             const char* a3 = a2 + kstep; const char* b3 = b2 + kstep;
;             PG8_LDB(B0, 0, 0); PG8_SCHED; PG8_LDA(At, 0, 0); PG8_STAGE(PG8_SA(1, 1), a1 + hstepA, voffA);
;             PG8_WAIT_L(8); PG8_BAR; PG8_WAIT_L(0); PG8_MMA(0, 0, At, B0); PG8_BAR; PG8_SCHED;
;             PG8_LDB(B1, 0, 1); PG8_STAGE(PG8_SB(0, 0), b2, voffB);
;             PG8_BAR; PG8_WAIT_L(0); PG8_MMA(0, 1, At, B1); PG8_BAR;
;             PG8_LDA(At, 0, 1); PG8_STAGE(PG8_SA(0, 0), a2, voffA);
;             PG8_BAR; PG8_WAIT_L(0); PG8_MMA(1, 0, At, B0); PG8_BAR; PG8_SCHED;
;             PG8_STAGE(PG8_SB(0, 1), b2 + hstepB, voffB);
;             PG8_WAIT_V(6); PG8_BAR; PG8_MMA(1, 1, At, B1); PG8_BAR;
.LBB0_555:
	s_add_i32 s14, s6, 2
	s_add_u32 s8, s4, 0x80
	s_addc_u32 s7, s5, 0
	s_add_i32 s9, 0, 0x10000
	v_add_u32_e32 v160, s9, v156
	ds_read_b128 v[142:145], v160
	ds_read_b128 v[146:149], v160 offset:1024
	ds_read_b128 v[150:153], v160 offset:2048
	ds_read_b128 v[160:163], v160 offset:3072
	s_cmp_eq_u32 s43, s6
	s_cselect_b32 s6, s57, s8
	s_cselect_b32 s7, s55, s7
	s_cselect_b32 s91, s59, s35
	s_cselect_b32 s90, s95, s34
	v_lshl_add_u64 v[192:193], s[4:5], 0, v[136:137]
	s_add_i32 m0, s33, 0xc000
	ds_read_b128 v[164:167], v159
	ds_read_b128 v[168:171], v159 offset:1024
	ds_read_b128 v[172:175], v159 offset:2048
	ds_read_b128 v[176:179], v159 offset:3072
	ds_read_b128 v[180:183], v159 offset:4096
	ds_read_b128 v[184:187], v159 offset:5120
	ds_read_b128 v[188:191], v159 offset:6144
	ds_read_b128 v[196:199], v159 offset:7168
	global_load_lds_dwordx4 v[192:193], off
	v_lshl_add_u64 v[192:193], s[4:5], 0, v[138:139]
	s_add_i32 m0, s33, 0xe000
	s_nop 0
	global_load_lds_dwordx4 v[192:193], off
	s_add_i32 s8, 0, 0x14000
	v_add_u32_e32 v192, s8, v156
	ds_read_b128 v[200:203], v192
	ds_read_b128 v[204:207], v192 offset:1024
	ds_read_b128 v[208:211], v192 offset:2048
	ds_read_b128 v[212:215], v192 offset:3072
	s_waitcnt vmcnt(8)
	s_waitcnt lgkmcnt(0)
	v_mfma_f32_16x16x32_bf16 v[126:129], v[142:145], v[164:167], v[126:129]
	v_mfma_f32_16x16x32_bf16 v[122:125], v[150:153], v[164:167], v[122:125]
	s_barrier
	s_setprio 1
	v_mfma_f32_16x16x32_bf16 v[110:113], v[142:145], v[172:175], v[110:113]
	v_mfma_f32_16x16x32_bf16 v[106:109], v[150:153], v[172:175], v[106:109]
	v_mfma_f32_16x16x32_bf16 v[94:97], v[142:145], v[180:183], v[94:97]
	v_mfma_f32_16x16x32_bf16 v[90:93], v[150:153], v[180:183], v[90:93]
	v_mfma_f32_16x16x32_bf16 v[78:81], v[142:145], v[188:191], v[78:81]
	v_mfma_f32_16x16x32_bf16 v[74:77], v[150:153], v[188:191], v[74:77]
	v_mfma_f32_16x16x32_bf16 v[126:129], v[146:149], v[168:171], v[126:129]
	v_mfma_f32_16x16x32_bf16 v[122:125], v[160:163], v[168:171], v[122:125]
	v_mfma_f32_16x16x32_bf16 v[110:113], v[146:149], v[176:179], v[110:113]
	v_mfma_f32_16x16x32_bf16 v[106:109], v[160:163], v[176:179], v[106:109]
	v_mfma_f32_16x16x32_bf16 v[94:97], v[146:149], v[184:187], v[94:97]
	v_mfma_f32_16x16x32_bf16 v[90:93], v[160:163], v[184:187], v[90:93]
	v_mfma_f32_16x16x32_bf16 v[78:81], v[146:149], v[196:199], v[78:81]
	v_mfma_f32_16x16x32_bf16 v[74:77], v[160:163], v[196:199], v[74:77]
	v_mfma_f32_16x16x32_bf16 v[118:121], v[200:203], v[164:167], v[118:121]
	v_mfma_f32_16x16x32_bf16 v[114:117], v[208:211], v[164:167], v[114:117]
	v_mfma_f32_16x16x32_bf16 v[102:105], v[200:203], v[172:175], v[102:105]
	v_mfma_f32_16x16x32_bf16 v[98:101], v[208:211], v[172:175], v[98:101]
	v_mfma_f32_16x16x32_bf16 v[86:89], v[200:203], v[180:183], v[86:89]
	v_mfma_f32_16x16x32_bf16 v[82:85], v[208:211], v[180:183], v[82:85]
	v_mfma_f32_16x16x32_bf16 v[70:73], v[200:203], v[188:191], v[70:73]
	v_mfma_f32_16x16x32_bf16 v[66:69], v[208:211], v[188:191], v[66:69]
	v_mfma_f32_16x16x32_bf16 v[118:121], v[204:207], v[168:171], v[118:121]
	v_mfma_f32_16x16x32_bf16 v[114:117], v[212:215], v[168:171], v[114:117]
	v_mfma_f32_16x16x32_bf16 v[102:105], v[204:207], v[176:179], v[102:105]
	v_mfma_f32_16x16x32_bf16 v[98:101], v[212:215], v[176:179], v[98:101]
	v_mfma_f32_16x16x32_bf16 v[86:89], v[204:207], v[184:187], v[86:89]
	v_mfma_f32_16x16x32_bf16 v[82:85], v[212:215], v[184:187], v[82:85]
	v_mfma_f32_16x16x32_bf16 v[70:73], v[204:207], v[196:199], v[70:73]
	v_mfma_f32_16x16x32_bf16 v[66:69], v[212:215], v[196:199], v[66:69]
	s_setprio 0
	s_barrier
	s_add_i32 s9, s9, s3
	v_lshl_add_u64 v[192:193], s[90:91], 0, v[0:1]
	s_mov_b32 m0, s9
	v_lshl_add_u64 v[194:195], s[90:91], 0, v[134:135]
	global_load_lds_dwordx4 v[192:193], off
	s_add_i32 m0, s9, 0x2000
	s_nop 0
	global_load_lds_dwordx4 v[194:195], off
	s_mov_b32 m0, s33
	v_lshl_add_u64 v[216:217], s[6:7], 0, v[130:131]
	ds_read_b128 v[164:167], v159 offset:16384
	ds_read_b128 v[168:171], v159 offset:17408
	ds_read_b128 v[172:175], v159 offset:18432
	ds_read_b128 v[176:179], v159 offset:19456
	ds_read_b128 v[180:183], v159 offset:20480
	ds_read_b128 v[184:187], v159 offset:21504
	ds_read_b128 v[188:191], v159 offset:22528
	ds_read_b128 v[196:199], v159 offset:23552
	global_load_lds_dwordx4 v[216:217], off
	v_lshl_add_u64 v[222:223], s[6:7], 0, v[132:133]
	s_mov_b32 m0, s38
	s_nop 0
	global_load_lds_dwordx4 v[222:223], off
	s_add_u32 s90, s90, s76
	s_addc_u32 s91, s91, s77
	s_add_i32 s8, s8, s3
	v_lshl_add_u64 v[224:225], s[90:91], 0, v[0:1]
	s_mov_b32 m0, s8
	v_lshl_add_u64 v[226:227], s[90:91], 0, v[134:135]
	global_load_lds_dwordx4 v[224:225], off
	s_add_i32 m0, s8, 0x2000
	s_nop 0
	global_load_lds_dwordx4 v[226:227], off
	s_waitcnt vmcnt(8)
	s_waitcnt lgkmcnt(0)
	v_mfma_f32_16x16x32_bf16 v[62:65], v[142:145], v[164:167], v[62:65]
	v_mfma_f32_16x16x32_bf16 v[58:61], v[150:153], v[164:167], v[58:61]
	s_barrier
; #define PG8_STAGE(bufoff, gbase, voff) do { _Pragma("unroll") for (int _i = 0; _i < 2; ++_i) \
;         __builtin_amdgcn_global_load_lds((const unsigned*)((const char*)(gbase) + (voff)[_i]), (LAS unsigned*)(lds + (bufoff) + ldsw + _i * 8192), 16, 0, 0); } while (0)
; #define PG8_LDA(dst, b, h) do { _Pragma("unroll") for (int m = 0; m < 4; ++m) _Pragma("unroll") for (int k = 0; k < 2; ++k) dst[m][k] = *(const LAS bf16x8*)(lds + PG8_SA(b, h) + aoff + m * 2048 + k * 1024); } while (0)
; #define PG8_LDB(dst, b, h) do { _Pragma("unroll") for (int n = 0; n < 2; ++n) _Pragma("unroll") for (int k = 0; k < 2; ++k) dst[n][k] = *(const LAS bf16x8*)(lds + PG8_SB(b, h) + boff + n * 2048 + k * 1024); } while (0)
; #define PG8_MMA(ai, bj, At, Bt) do { __builtin_amdgcn_s_setprio(1); _Pragma("unroll") for (int m = 0; m < 4; ++m) _Pragma("unroll") for (int n = 0; n < 2; ++n) _Pragma("unroll") for (int k = 0; k < 2; ++k) \
;         acc[ai][bj][m][n] = __builtin_amdgcn_mfma_f32_16x16x32_bf16(Bt[n][k], At[m][k], acc[ai][bj][m][n], 0, 0, 0); __builtin_amdgcn_s_setprio(0); } while (0)
; #define PG8_WAIT_V(n) asm volatile("s_waitcnt vmcnt(" #n ")" ::: "memory")
; #define PG8_BAR __builtin_amdgcn_s_barrier()
; template <class Epi>
; __device__ __forceinline__ void gemm_phase(LAS unsigned char* lds, const Gemm g, const Sched& S, const Epi& E) {
;     ...
;             PG8_LDB(B1, 0, 1); PG8_STAGE(PG8_SB(0, 0), b2, voffB);
;             PG8_BAR; PG8_WAIT_L(0); PG8_MMA(0, 1, At, B1); PG8_BAR;
;             PG8_LDA(At, 0, 1); PG8_STAGE(PG8_SA(0, 0), a2, voffA);
;             PG8_BAR; PG8_WAIT_L(0); PG8_MMA(1, 0, At, B0); PG8_BAR; PG8_SCHED;
;             PG8_STAGE(PG8_SB(0, 1), b2 + hstepB, voffB);
;             PG8_WAIT_V(6); PG8_BAR; PG8_MMA(1, 1, At, B1); PG8_BAR;
;             PG8_LDB(B0, 1, 0); PG8_SCHED; PG8_LDA(At, 1, 0); PG8_STAGE(PG8_SA(0, 1), a2 + hstepA, voffA);
;             PG8_WAIT_L(8); PG8_BAR; PG8_WAIT_L(0); PG8_MMA(0, 0, At, B0); PG8_BAR; PG8_SCHED;
;             PG8_LDB(B1, 1, 1); PG8_STAGE(PG8_SB(1, 0), b3, voffB);
;             PG8_BAR; PG8_WAIT_L(0); PG8_MMA(0, 1, At, B1); PG8_BAR;
;             PG8_LDA(At, 1, 1); PG8_STAGE(PG8_SA(1, 0), a3, voffA);
;             PG8_BAR; PG8_WAIT_L(0); PG8_MMA(1, 0, At, B0); PG8_BAR; PG8_SCHED;
;             PG8_STAGE(PG8_SB(1, 1), b3 + hstepB, voffB);
;             PG8_WAIT_V(6); PG8_BAR; PG8_MMA(1, 1, At, B1); PG8_BAR;
	s_setprio 1
	v_mfma_f32_16x16x32_bf16 v[46:49], v[142:145], v[172:175], v[46:49]
	v_mfma_f32_16x16x32_bf16 v[42:45], v[150:153], v[172:175], v[42:45]
	v_mfma_f32_16x16x32_bf16 v[30:33], v[142:145], v[180:183], v[30:33]
	v_mfma_f32_16x16x32_bf16 v[26:29], v[150:153], v[180:183], v[26:29]
	v_mfma_f32_16x16x32_bf16 v[14:17], v[142:145], v[188:191], v[14:17]
	v_mfma_f32_16x16x32_bf16 v[10:13], v[150:153], v[188:191], v[10:13]
	v_mfma_f32_16x16x32_bf16 v[62:65], v[146:149], v[168:171], v[62:65]
	v_mfma_f32_16x16x32_bf16 v[58:61], v[160:163], v[168:171], v[58:61]
	v_mfma_f32_16x16x32_bf16 v[46:49], v[146:149], v[176:179], v[46:49]
	v_mfma_f32_16x16x32_bf16 v[42:45], v[160:163], v[176:179], v[42:45]
	v_mfma_f32_16x16x32_bf16 v[30:33], v[146:149], v[184:187], v[30:33]
	v_mfma_f32_16x16x32_bf16 v[26:29], v[160:163], v[184:187], v[26:29]
	v_mfma_f32_16x16x32_bf16 v[14:17], v[146:149], v[196:199], v[14:17]
	v_mfma_f32_16x16x32_bf16 v[10:13], v[160:163], v[196:199], v[10:13]
	v_mfma_f32_16x16x32_bf16 v[54:57], v[200:203], v[164:167], v[54:57]
	v_mfma_f32_16x16x32_bf16 v[50:53], v[208:211], v[164:167], v[50:53]
	v_mfma_f32_16x16x32_bf16 v[38:41], v[200:203], v[172:175], v[38:41]
	v_mfma_f32_16x16x32_bf16 v[34:37], v[208:211], v[172:175], v[34:37]
	v_mfma_f32_16x16x32_bf16 v[22:25], v[200:203], v[180:183], v[22:25]
	v_mfma_f32_16x16x32_bf16 v[18:21], v[208:211], v[180:183], v[18:21]
	v_mfma_f32_16x16x32_bf16 v[6:9], v[200:203], v[188:191], v[6:9]
	v_mfma_f32_16x16x32_bf16 v[2:5], v[208:211], v[188:191], v[2:5]
	v_mfma_f32_16x16x32_bf16 v[54:57], v[204:207], v[168:171], v[54:57]
	v_mfma_f32_16x16x32_bf16 v[50:53], v[212:215], v[168:171], v[50:53]
	v_mfma_f32_16x16x32_bf16 v[38:41], v[204:207], v[176:179], v[38:41]
	v_mfma_f32_16x16x32_bf16 v[34:37], v[212:215], v[176:179], v[34:37]
	v_mfma_f32_16x16x32_bf16 v[22:25], v[204:207], v[184:187], v[22:25]
	v_mfma_f32_16x16x32_bf16 v[18:21], v[212:215], v[184:187], v[18:21]
	v_mfma_f32_16x16x32_bf16 v[6:9], v[204:207], v[196:199], v[6:9]
	v_mfma_f32_16x16x32_bf16 v[2:5], v[212:215], v[196:199], v[2:5]
	s_setprio 0
	s_barrier
	s_add_i32 s8, 0, 0x18000
	v_add_u32_e32 v160, s8, v156
	ds_read_b128 v[142:145], v160
	ds_read_b128 v[146:149], v160 offset:1024
	ds_read_b128 v[150:153], v160 offset:2048
	ds_read_b128 v[160:163], v160 offset:3072
	s_add_u32 s6, s6, s36
	s_addc_u32 s7, s7, s37
	s_mov_b32 m0, s39
	v_lshl_add_u64 v[200:201], s[6:7], 0, v[130:131]
	ds_read_b128 v[164:167], v159 offset:32768
	ds_read_b128 v[168:171], v159 offset:33792
	ds_read_b128 v[172:175], v159 offset:34816
	ds_read_b128 v[176:179], v159 offset:35840
	ds_read_b128 v[180:183], v159 offset:36864
	ds_read_b128 v[184:187], v159 offset:37888
	ds_read_b128 v[188:191], v159 offset:38912
	ds_read_b128 v[196:199], v159 offset:39936
	global_load_lds_dwordx4 v[200:201], off
	v_lshl_add_u64 v[200:201], s[6:7], 0, v[132:133]
	s_mov_b32 m0, s40
	s_nop 0
	global_load_lds_dwordx4 v[200:201], off
	s_add_i32 s6, 0, 0x1c000
	v_add_u32_e32 v212, s6, v156
	ds_read_b128 v[200:203], v212
	ds_read_b128 v[204:207], v212 offset:1024
	ds_read_b128 v[208:211], v212 offset:2048
	ds_read_b128 v[212:215], v212 offset:3072
	s_waitcnt vmcnt(8)
	s_waitcnt lgkmcnt(0)
	v_mfma_f32_16x16x32_bf16 v[126:129], v[142:145], v[164:167], v[126:129]
	v_mfma_f32_16x16x32_bf16 v[122:125], v[150:153], v[164:167], v[122:125]
	s_barrier
	s_setprio 1
	v_mfma_f32_16x16x32_bf16 v[110:113], v[142:145], v[172:175], v[110:113]
	v_mfma_f32_16x16x32_bf16 v[106:109], v[150:153], v[172:175], v[106:109]
	v_mfma_f32_16x16x32_bf16 v[94:97], v[142:145], v[180:183], v[94:97]
	v_mfma_f32_16x16x32_bf16 v[90:93], v[150:153], v[180:183], v[90:93]
	v_mfma_f32_16x16x32_bf16 v[78:81], v[142:145], v[188:191], v[78:81]
	v_mfma_f32_16x16x32_bf16 v[74:77], v[150:153], v[188:191], v[74:77]
	v_mfma_f32_16x16x32_bf16 v[126:129], v[146:149], v[168:171], v[126:129]
	v_mfma_f32_16x16x32_bf16 v[122:125], v[160:163], v[168:171], v[122:125]
	v_mfma_f32_16x16x32_bf16 v[110:113], v[146:149], v[176:179], v[110:113]
	v_mfma_f32_16x16x32_bf16 v[106:109], v[160:163], v[176:179], v[106:109]
	v_mfma_f32_16x16x32_bf16 v[94:97], v[146:149], v[184:187], v[94:97]
	v_mfma_f32_16x16x32_bf16 v[90:93], v[160:163], v[184:187], v[90:93]
	v_mfma_f32_16x16x32_bf16 v[78:81], v[146:149], v[196:199], v[78:81]
	v_mfma_f32_16x16x32_bf16 v[74:77], v[160:163], v[196:199], v[74:77]
	v_mfma_f32_16x16x32_bf16 v[118:121], v[200:203], v[164:167], v[118:121]
	v_mfma_f32_16x16x32_bf16 v[114:117], v[208:211], v[164:167], v[114:117]
	v_mfma_f32_16x16x32_bf16 v[102:105], v[200:203], v[172:175], v[102:105]
	v_mfma_f32_16x16x32_bf16 v[98:101], v[208:211], v[172:175], v[98:101]
	v_mfma_f32_16x16x32_bf16 v[86:89], v[200:203], v[180:183], v[86:89]
	v_mfma_f32_16x16x32_bf16 v[82:85], v[208:211], v[180:183], v[82:85]
	v_mfma_f32_16x16x32_bf16 v[70:73], v[200:203], v[188:191], v[70:73]
	v_mfma_f32_16x16x32_bf16 v[66:69], v[208:211], v[188:191], v[66:69]
	v_mfma_f32_16x16x32_bf16 v[118:121], v[204:207], v[168:171], v[118:121]
	v_mfma_f32_16x16x32_bf16 v[114:117], v[212:215], v[168:171], v[114:117]
	v_mfma_f32_16x16x32_bf16 v[102:105], v[204:207], v[176:179], v[102:105]
	v_mfma_f32_16x16x32_bf16 v[98:101], v[212:215], v[176:179], v[98:101]
	v_mfma_f32_16x16x32_bf16 v[86:89], v[204:207], v[184:187], v[86:89]
	v_mfma_f32_16x16x32_bf16 v[82:85], v[212:215], v[184:187], v[82:85]
	v_mfma_f32_16x16x32_bf16 v[70:73], v[204:207], v[196:199], v[70:73]
	v_mfma_f32_16x16x32_bf16 v[66:69], v[212:215], v[196:199], v[66:69]
	s_setprio 0
	s_barrier
; __device__ __forceinline__ float sigm_f(float x) { return __builtin_amdgcn_rcpf(1.f + __builtin_amdgcn_exp2f(-LOG2E * x)); }
; __device__ __forceinline__ u32x4 pk8(const f32x4 a, const f32x4 b) { u32x4 w; w.x = pk2(a[0], a[1]); w.y = pk2(a[2], a[3]); w.z = pk2(b[0], b[1]); w.w = pk2(b[2], b[3]); return w; }
; __device__ __forceinline__ float pre_get(const Pre& p, int ai, int m, int fr) { return __shfl(p.v[ai], m * 16 + fr); }
; __device__ __forceinline__ float rstd_pre(const float* ss, float v) { return ss ? rsqrtf(v * (1.0f / 2048.0f) + 1e-6f) : 1.0f; }
; #define PG8_STAGE(bufoff, gbase, voff) do { _Pragma("unroll") for (int _i = 0; _i < 2; ++_i) \
;         __builtin_amdgcn_global_load_lds((const unsigned*)((const char*)(gbase) + (voff)[_i]), (LAS unsigned*)(lds + (bufoff) + ldsw + _i * 8192), 16, 0, 0); } while (0)
; template <class Epi>
; __device__ __forceinline__ void gemm_phase(LAS unsigned char* lds, const Gemm g, const Sched& S, const Epi& E) {
;     ...
;             PG8_LDB(B0, 1, 0); PG8_SCHED; PG8_LDA(At, 1, 0); PG8_STAGE(PG8_SA(0, 1), a2 + hstepA, voffA);
;             PG8_WAIT_L(8); PG8_BAR; PG8_WAIT_L(0); PG8_MMA(0, 0, At, B0); PG8_BAR; PG8_SCHED;
;             PG8_LDB(B1, 1, 1); PG8_STAGE(PG8_SB(1, 0), b3, voffB);
;             PG8_BAR; PG8_WAIT_L(0); PG8_MMA(0, 1, At, B1); PG8_BAR;
;             PG8_LDA(At, 1, 1); PG8_STAGE(PG8_SA(1, 0), a3, voffA);
;             PG8_BAR; PG8_WAIT_L(0); PG8_MMA(1, 0, At, B0); PG8_BAR; PG8_SCHED;
;             PG8_STAGE(PG8_SB(1, 1), b3 + hstepB, voffB);
;             PG8_WAIT_V(6); PG8_BAR; PG8_MMA(1, 1, At, B1); PG8_BAR;
;         }
;     __device__ __forceinline__ void operator()(const Acc& acc, const Unit& u, int wr, int wc, int fr, int fq, const Pre& pre) const {
;     ...
;             for (int m = 0; m < 4; ++m) rsq[ai][m] = rstd_pre(ss, pre_get(pre, ai, m, fr));
; #pragma unroll
;         for (int ai = 0; ai < 2; ++ai)
; #pragma unroll
;             for (int m = 0; m < 4; ++m) { const float rs = scale * rsq[ai][m];
; #pragma unroll
;                 for (int bj = 0; bj < 2; ++bj) { f32x4 v0 = acc[ai][bj][m][0] * rs, v1 = acc[ai][bj][m][1] * rs;
;                     if (act == 1) {
; #pragma unroll
;                         for (int e = 0; e < 4; ++e) { v0[e] = sigm_f(v0[e]); v1[e] = sigm_f(v1[e]); } }
;                     *(u32x4*)(Oz + (size_t)(row0 + ai * 128 + m * 16) * ldc + col0 + bj * 128) = pk8(v0, v1); } }
	s_add_i32 s7, s8, s3
	v_lshl_add_u64 v[192:193], v[192:193], 0, s[60:61]
	s_mov_b32 m0, s7
	s_nop 0
	global_load_lds_dwordx4 v[192:193], off
	v_lshl_add_u64 v[192:193], v[194:195], 0, s[60:61]
	s_add_i32 m0, s7, 0x2000
	s_nop 0
	global_load_lds_dwordx4 v[192:193], off
	s_mov_b32 m0, s41
	v_lshl_add_u64 v[192:193], v[216:217], 0, s[60:61]
	ds_read_b128 v[164:167], v159 offset:49152
	ds_read_b128 v[168:171], v159 offset:50176
	ds_read_b128 v[172:175], v159 offset:51200
	ds_read_b128 v[176:179], v159 offset:52224
	ds_read_b128 v[180:183], v159 offset:53248
	ds_read_b128 v[184:187], v159 offset:54272
	ds_read_b128 v[188:191], v159 offset:55296
	ds_read_b128 v[196:199], v159 offset:56320
	global_load_lds_dwordx4 v[192:193], off
	v_lshl_add_u64 v[192:193], v[222:223], 0, s[60:61]
	s_mov_b32 m0, s42
	s_nop 0
	global_load_lds_dwordx4 v[192:193], off
	s_add_i32 s6, s6, s3
	v_lshl_add_u64 v[192:193], v[224:225], 0, s[60:61]
	s_mov_b32 m0, s6
	s_nop 0
	global_load_lds_dwordx4 v[192:193], off
	v_lshl_add_u64 v[192:193], v[226:227], 0, s[60:61]
	s_add_i32 m0, s6, 0x2000
	s_nop 0
	global_load_lds_dwordx4 v[192:193], off
	s_waitcnt vmcnt(8)
	s_waitcnt lgkmcnt(0)
	v_mfma_f32_16x16x32_bf16 v[62:65], v[142:145], v[164:167], v[62:65]
	v_mfma_f32_16x16x32_bf16 v[58:61], v[150:153], v[164:167], v[58:61]
	s_barrier
	s_setprio 1
	v_mfma_f32_16x16x32_bf16 v[46:49], v[142:145], v[172:175], v[46:49]
	v_mfma_f32_16x16x32_bf16 v[42:45], v[150:153], v[172:175], v[42:45]
	v_mfma_f32_16x16x32_bf16 v[30:33], v[142:145], v[180:183], v[30:33]
	v_mfma_f32_16x16x32_bf16 v[26:29], v[150:153], v[180:183], v[26:29]
	v_mfma_f32_16x16x32_bf16 v[14:17], v[142:145], v[188:191], v[14:17]
	v_mfma_f32_16x16x32_bf16 v[10:13], v[150:153], v[188:191], v[10:13]
	v_mfma_f32_16x16x32_bf16 v[62:65], v[146:149], v[168:171], v[62:65]
	v_mfma_f32_16x16x32_bf16 v[58:61], v[160:163], v[168:171], v[58:61]
	v_mfma_f32_16x16x32_bf16 v[46:49], v[146:149], v[176:179], v[46:49]
	v_mfma_f32_16x16x32_bf16 v[42:45], v[160:163], v[176:179], v[42:45]
	v_mfma_f32_16x16x32_bf16 v[30:33], v[146:149], v[184:187], v[30:33]
	v_mfma_f32_16x16x32_bf16 v[26:29], v[160:163], v[184:187], v[26:29]
	v_mfma_f32_16x16x32_bf16 v[14:17], v[146:149], v[196:199], v[14:17]
	v_mfma_f32_16x16x32_bf16 v[10:13], v[160:163], v[196:199], v[10:13]
	v_mfma_f32_16x16x32_bf16 v[54:57], v[200:203], v[164:167], v[54:57]
	v_mfma_f32_16x16x32_bf16 v[50:53], v[208:211], v[164:167], v[50:53]
	v_mfma_f32_16x16x32_bf16 v[38:41], v[200:203], v[172:175], v[38:41]
	v_mfma_f32_16x16x32_bf16 v[34:37], v[208:211], v[172:175], v[34:37]
	v_mfma_f32_16x16x32_bf16 v[22:25], v[200:203], v[180:183], v[22:25]
	v_mfma_f32_16x16x32_bf16 v[18:21], v[208:211], v[180:183], v[18:21]
	v_mfma_f32_16x16x32_bf16 v[6:9], v[200:203], v[188:191], v[6:9]
	v_mfma_f32_16x16x32_bf16 v[2:5], v[208:211], v[188:191], v[2:5]
	v_mfma_f32_16x16x32_bf16 v[54:57], v[204:207], v[168:171], v[54:57]
	v_mfma_f32_16x16x32_bf16 v[50:53], v[212:215], v[168:171], v[50:53]
	v_mfma_f32_16x16x32_bf16 v[38:41], v[204:207], v[176:179], v[38:41]
	v_mfma_f32_16x16x32_bf16 v[34:37], v[212:215], v[176:179], v[34:37]
	v_mfma_f32_16x16x32_bf16 v[22:25], v[204:207], v[184:187], v[22:25]
	v_mfma_f32_16x16x32_bf16 v[18:21], v[212:215], v[184:187], v[18:21]
	v_mfma_f32_16x16x32_bf16 v[6:9], v[204:207], v[196:199], v[6:9]
	v_mfma_f32_16x16x32_bf16 v[2:5], v[212:215], v[196:199], v[2:5]
	s_setprio 0
	s_add_u32 s4, s4, 0x100
	s_addc_u32 s5, s5, 0
	s_add_u32 s34, s34, 0x100
	s_addc_u32 s35, s35, 0
	s_cmp_ge_u32 s14, s73
	s_mov_b32 s6, s14
	s_barrier
	s_cbranch_scc0 .LBB0_555
	v_and_or_b32 v142, v220, 64, v154
	v_lshlrev_b32_e32 v148, 2, v142
	ds_bpermute_b32 v143, v148, v141
	ds_bpermute_b32 v142, v148, v141 offset:64
	s_mov_b32 s4, 0x3a000000
	ds_bpermute_b32 v145, v148, v141 offset:128
	ds_bpermute_b32 v144, v148, v141 offset:192
	v_readlane_b32 s8, v254, 29
	s_waitcnt lgkmcnt(0)
	v_pk_fma_f32 v[146:147], v[142:143], s[4:5], v[232:233] op_sel_hi:[1,0,0]
	ds_bpermute_b32 v143, v148, v140
	v_mul_f32_e32 v141, 0x4b800000, v147
	v_cmp_gt_f32_e32 vcc, s97, v147
	ds_bpermute_b32 v142, v148, v140 offset:64
	v_readlane_b32 s9, v254, 30
	v_cndmask_b32_e32 v141, v147, v141, vcc
	v_rsq_f32_e32 v141, v141
	v_cmp_gt_f32_e64 s[4:5], s97, v146
	s_mov_b64 s[90:91], -1
	v_mul_f32_e32 v147, 0x45800000, v141
	v_cndmask_b32_e32 v141, v141, v147, vcc
	v_cndmask_b32_e64 v147, v141, 1.0, s[78:79]
	ds_bpermute_b32 v141, v148, v140 offset:128
	ds_bpermute_b32 v140, v148, v140 offset:192
	v_mul_f32_e32 v148, s70, v147
	v_pk_mul_f32 v[152:153], v[122:123], v[148:149] op_sel_hi:[1,0]
	v_cndmask_b32_e64 v122, 0, 1, s[8:9]
	v_pk_mul_f32 v[128:129], v[128:129], v[148:149] op_sel_hi:[1,0]
	v_pk_mul_f32 v[150:151], v[126:127], v[148:149] op_sel_hi:[1,0]
	v_pk_mul_f32 v[126:127], v[124:125], v[148:149] op_sel_hi:[1,0]
	v_cmp_ne_u32_e64 s[6:7], 1, v122
	s_andn2_b64 vcc, exec, s[8:9]
	s_cbranch_vccnz .LBB0_558
	s_mov_b64 s[90:91], 0

; #define PG8_STAGE(bufoff, gbase, voff) do { _Pragma("unroll") for (int _i = 0; _i < 2; ++_i) \
;         __builtin_amdgcn_global_load_lds((const unsigned*)((const char*)(gbase) + (voff)[_i]), (LAS unsigned*)(lds + (bufoff) + ldsw + _i * 8192), 16, 0, 0); } while (0)
; #define PG8_LDA(dst, b, h) do { _Pragma("unroll") for (int m = 0; m < 4; ++m) _Pragma("unroll") for (int k = 0; k < 2; ++k) dst[m][k] = *(const LAS bf16x8*)(lds + PG8_SA(b, h) + aoff + m * 2048 + k * 1024); } while (0)
; #define PG8_LDB(dst, b, h) do { _Pragma("unroll") for (int n = 0; n < 2; ++n) _Pragma("unroll") for (int k = 0; k < 2; ++k) dst[n][k] = *(const LAS bf16x8*)(lds + PG8_SB(b, h) + boff + n * 2048 + k * 1024); } while (0)
; #define PG8_MMA(ai, bj, At, Bt) do { __builtin_amdgcn_s_setprio(1); _Pragma("unroll") for (int m = 0; m < 4; ++m) _Pragma("unroll") for (int n = 0; n < 2; ++n) _Pragma("unroll") for (int k = 0; k < 2; ++k) \
;         acc[ai][bj][m][n] = __builtin_amdgcn_mfma_f32_16x16x32_bf16(Bt[n][k], At[m][k], acc[ai][bj][m][n], 0, 0, 0); __builtin_amdgcn_s_setprio(0); } while (0)
; #define PG8_WAIT_V(n) asm volatile("s_waitcnt vmcnt(" #n ")" ::: "memory")
; #define PG8_WAIT_L(n) asm volatile("s_waitcnt lgkmcnt(" #n ")" ::: "memory")
; template <class Epi>
; __device__ __forceinline__ void gemm_phase(LAS unsigned char* lds, const Gemm g, const Sched& S, const Epi& E) {
;     ...
;         for (int t = 0; t < nt; t += 2) {
;             const bool last = (t == nt - 2);
;             const char* a1 = cA + (size_t)(t + 1) * kstep;
;             const char* a2 = last ? nA : cA + (size_t)(t + 2) * kstep; const char* b2 = last ? nB : cB + (size_t)(t + 2) * kstep;
;             const char* a3 = a2 + kstep; const char* b3 = b2 + kstep;
;             PG8_LDB(B0, 0, 0); PG8_SCHED; PG8_LDA(At, 0, 0); PG8_STAGE(PG8_SA(1, 1), a1 + hstepA, voffA);
;             PG8_WAIT_L(8); PG8_BAR; PG8_WAIT_L(0); PG8_MMA(0, 0, At, B0); PG8_BAR; PG8_SCHED;
;             PG8_LDB(B1, 0, 1); PG8_STAGE(PG8_SB(0, 0), b2, voffB);
;             PG8_BAR; PG8_WAIT_L(0); PG8_MMA(0, 1, At, B1); PG8_BAR;
;             PG8_LDA(At, 0, 1); PG8_STAGE(PG8_SA(0, 0), a2, voffA);
;             PG8_BAR; PG8_WAIT_L(0); PG8_MMA(1, 0, At, B0); PG8_BAR; PG8_SCHED;
;             PG8_STAGE(PG8_SB(0, 1), b2 + hstepB, voffB);
;             PG8_WAIT_V(6); PG8_BAR; PG8_MMA(1, 1, At, B1); PG8_BAR;
.LBB0_649:
	s_add_i32 s14, s4, 2
	s_add_u32 s8, s0, 0x80
	s_addc_u32 s5, s1, 0
	s_add_i32 s9, 0, 0x10000
	v_add_u32_e32 v144, s9, v236
	ds_read_b128 v[132:135], v144
	ds_read_b128 v[136:139], v144 offset:1024
	ds_read_b128 v[140:143], v144 offset:2048
	ds_read_b128 v[144:147], v144 offset:3072
	s_cmp_eq_u32 s95, s4
	s_cselect_b32 s4, s48, s8
	s_cselect_b32 s5, s33, s5
	s_cselect_b32 s87, s51, s35
	s_cselect_b32 s86, s55, s34
	v_lshl_add_u64 v[176:177], s[0:1], 0, v[188:189]
	s_add_i32 m0, s89, 0xc000
	ds_read_b128 v[148:151], v239
	ds_read_b128 v[152:155], v239 offset:1024
	ds_read_b128 v[156:159], v239 offset:2048
	ds_read_b128 v[160:163], v239 offset:3072
	ds_read_b128 v[164:167], v239 offset:4096
	ds_read_b128 v[168:171], v239 offset:5120
	ds_read_b128 v[172:175], v239 offset:6144
	ds_read_b128 v[196:199], v239 offset:7168
	global_load_lds_dwordx4 v[176:177], off
	v_lshl_add_u64 v[176:177], s[0:1], 0, v[190:191]
	s_add_i32 m0, s89, 0xe000
	s_nop 0
	global_load_lds_dwordx4 v[176:177], off
	s_add_i32 s8, 0, 0x14000
	v_add_u32_e32 v176, s8, v236
	ds_read_b128 v[200:203], v176
	ds_read_b128 v[204:207], v176 offset:1024
	ds_read_b128 v[208:211], v176 offset:2048
	ds_read_b128 v[212:215], v176 offset:3072
	s_waitcnt vmcnt(8)
	s_waitcnt lgkmcnt(0)
	v_mfma_f32_16x16x32_bf16 v[126:129], v[132:135], v[148:151], v[126:129]
	v_mfma_f32_16x16x32_bf16 v[122:125], v[140:143], v[148:151], v[122:125]
	s_barrier
	s_setprio 1
	v_mfma_f32_16x16x32_bf16 v[110:113], v[132:135], v[156:159], v[110:113]
	v_mfma_f32_16x16x32_bf16 v[106:109], v[140:143], v[156:159], v[106:109]
	v_mfma_f32_16x16x32_bf16 v[94:97], v[132:135], v[164:167], v[94:97]
	v_mfma_f32_16x16x32_bf16 v[90:93], v[140:143], v[164:167], v[90:93]
	v_mfma_f32_16x16x32_bf16 v[78:81], v[132:135], v[172:175], v[78:81]
	v_mfma_f32_16x16x32_bf16 v[74:77], v[140:143], v[172:175], v[74:77]
	v_mfma_f32_16x16x32_bf16 v[126:129], v[136:139], v[152:155], v[126:129]
	v_mfma_f32_16x16x32_bf16 v[122:125], v[144:147], v[152:155], v[122:125]
	v_mfma_f32_16x16x32_bf16 v[110:113], v[136:139], v[160:163], v[110:113]
	v_mfma_f32_16x16x32_bf16 v[106:109], v[144:147], v[160:163], v[106:109]
	v_mfma_f32_16x16x32_bf16 v[94:97], v[136:139], v[168:171], v[94:97]
	v_mfma_f32_16x16x32_bf16 v[90:93], v[144:147], v[168:171], v[90:93]
	v_mfma_f32_16x16x32_bf16 v[78:81], v[136:139], v[196:199], v[78:81]
	v_mfma_f32_16x16x32_bf16 v[74:77], v[144:147], v[196:199], v[74:77]
	v_mfma_f32_16x16x32_bf16 v[118:121], v[200:203], v[148:151], v[118:121]
	v_mfma_f32_16x16x32_bf16 v[114:117], v[208:211], v[148:151], v[114:117]
	v_mfma_f32_16x16x32_bf16 v[102:105], v[200:203], v[156:159], v[102:105]
	v_mfma_f32_16x16x32_bf16 v[98:101], v[208:211], v[156:159], v[98:101]
	v_mfma_f32_16x16x32_bf16 v[86:89], v[200:203], v[164:167], v[86:89]
	v_mfma_f32_16x16x32_bf16 v[82:85], v[208:211], v[164:167], v[82:85]
	v_mfma_f32_16x16x32_bf16 v[70:73], v[200:203], v[172:175], v[70:73]
	v_mfma_f32_16x16x32_bf16 v[66:69], v[208:211], v[172:175], v[66:69]
	v_mfma_f32_16x16x32_bf16 v[118:121], v[204:207], v[152:155], v[118:121]
	v_mfma_f32_16x16x32_bf16 v[114:117], v[212:215], v[152:155], v[114:117]
	v_mfma_f32_16x16x32_bf16 v[102:105], v[204:207], v[160:163], v[102:105]
	v_mfma_f32_16x16x32_bf16 v[98:101], v[212:215], v[160:163], v[98:101]
	v_mfma_f32_16x16x32_bf16 v[86:89], v[204:207], v[168:171], v[86:89]
	v_mfma_f32_16x16x32_bf16 v[82:85], v[212:215], v[168:171], v[82:85]
	v_mfma_f32_16x16x32_bf16 v[70:73], v[204:207], v[196:199], v[70:73]
	v_mfma_f32_16x16x32_bf16 v[66:69], v[212:215], v[196:199], v[66:69]
	s_setprio 0
	s_barrier
	s_add_i32 s9, s9, s88
	v_lshl_add_u64 v[176:177], s[86:87], 0, v[180:181]
	s_mov_b32 m0, s9
	v_lshl_add_u64 v[192:193], s[86:87], 0, v[184:185]
	global_load_lds_dwordx4 v[176:177], off
	s_add_i32 m0, s9, 0x2000
	s_nop 0
	global_load_lds_dwordx4 v[192:193], off
	s_mov_b32 m0, s89
	v_lshl_add_u64 v[194:195], s[4:5], 0, v[178:179]
	ds_read_b128 v[148:151], v239 offset:16384
	ds_read_b128 v[152:155], v239 offset:17408
	ds_read_b128 v[156:159], v239 offset:18432
	ds_read_b128 v[160:163], v239 offset:19456
	ds_read_b128 v[164:167], v239 offset:20480
	ds_read_b128 v[168:171], v239 offset:21504
	ds_read_b128 v[172:175], v239 offset:22528
	ds_read_b128 v[196:199], v239 offset:23552
	global_load_lds_dwordx4 v[194:195], off
	v_lshl_add_u64 v[216:217], s[4:5], 0, v[182:183]
	s_mov_b32 m0, s90
	s_nop 0
	global_load_lds_dwordx4 v[216:217], off
	s_add_u32 s56, s86, s36
	s_addc_u32 s57, s87, s37
	s_add_i32 s8, s8, s88
	v_lshl_add_u64 v[222:223], s[56:57], 0, v[180:181]
	s_mov_b32 m0, s8
	v_lshl_add_u64 v[224:225], s[56:57], 0, v[184:185]
	global_load_lds_dwordx4 v[222:223], off
	s_add_i32 m0, s8, 0x2000
	s_nop 0
	global_load_lds_dwordx4 v[224:225], off
	s_waitcnt vmcnt(8)
	s_waitcnt lgkmcnt(0)
	v_mfma_f32_16x16x32_bf16 v[62:65], v[132:135], v[148:151], v[62:65]
	v_mfma_f32_16x16x32_bf16 v[58:61], v[140:143], v[148:151], v[58:61]
	s_barrier
; #define PG8_STAGE(bufoff, gbase, voff) do { _Pragma("unroll") for (int _i = 0; _i < 2; ++_i) \
;         __builtin_amdgcn_global_load_lds((const unsigned*)((const char*)(gbase) + (voff)[_i]), (LAS unsigned*)(lds + (bufoff) + ldsw + _i * 8192), 16, 0, 0); } while (0)
; #define PG8_LDA(dst, b, h) do { _Pragma("unroll") for (int m = 0; m < 4; ++m) _Pragma("unroll") for (int k = 0; k < 2; ++k) dst[m][k] = *(const LAS bf16x8*)(lds + PG8_SA(b, h) + aoff + m * 2048 + k * 1024); } while (0)
; #define PG8_LDB(dst, b, h) do { _Pragma("unroll") for (int n = 0; n < 2; ++n) _Pragma("unroll") for (int k = 0; k < 2; ++k) dst[n][k] = *(const LAS bf16x8*)(lds + PG8_SB(b, h) + boff + n * 2048 + k * 1024); } while (0)
; #define PG8_MMA(ai, bj, At, Bt) do { __builtin_amdgcn_s_setprio(1); _Pragma("unroll") for (int m = 0; m < 4; ++m) _Pragma("unroll") for (int n = 0; n < 2; ++n) _Pragma("unroll") for (int k = 0; k < 2; ++k) \
;         acc[ai][bj][m][n] = __builtin_amdgcn_mfma_f32_16x16x32_bf16(Bt[n][k], At[m][k], acc[ai][bj][m][n], 0, 0, 0); __builtin_amdgcn_s_setprio(0); } while (0)
; #define PG8_WAIT_V(n) asm volatile("s_waitcnt vmcnt(" #n ")" ::: "memory")
; #define PG8_BAR __builtin_amdgcn_s_barrier()
; template <class Epi>
; __device__ __forceinline__ void gemm_phase(LAS unsigned char* lds, const Gemm g, const Sched& S, const Epi& E) {
;     ...
;             PG8_LDB(B1, 0, 1); PG8_STAGE(PG8_SB(0, 0), b2, voffB);
;             PG8_BAR; PG8_WAIT_L(0); PG8_MMA(0, 1, At, B1); PG8_BAR;
;             PG8_LDA(At, 0, 1); PG8_STAGE(PG8_SA(0, 0), a2, voffA);
;             PG8_BAR; PG8_WAIT_L(0); PG8_MMA(1, 0, At, B0); PG8_BAR; PG8_SCHED;
;             PG8_STAGE(PG8_SB(0, 1), b2 + hstepB, voffB);
;             PG8_WAIT_V(6); PG8_BAR; PG8_MMA(1, 1, At, B1); PG8_BAR;
;             PG8_LDB(B0, 1, 0); PG8_SCHED; PG8_LDA(At, 1, 0); PG8_STAGE(PG8_SA(0, 1), a2 + hstepA, voffA);
;             PG8_WAIT_L(8); PG8_BAR; PG8_WAIT_L(0); PG8_MMA(0, 0, At, B0); PG8_BAR; PG8_SCHED;
;             PG8_LDB(B1, 1, 1); PG8_STAGE(PG8_SB(1, 0), b3, voffB);
;             PG8_BAR; PG8_WAIT_L(0); PG8_MMA(0, 1, At, B1); PG8_BAR;
;             PG8_LDA(At, 1, 1); PG8_STAGE(PG8_SA(1, 0), a3, voffA);
;             PG8_BAR; PG8_WAIT_L(0); PG8_MMA(1, 0, At, B0); PG8_BAR; PG8_SCHED;
;             PG8_STAGE(PG8_SB(1, 1), b3 + hstepB, voffB);
;             PG8_WAIT_V(6); PG8_BAR; PG8_MMA(1, 1, At, B1); PG8_BAR;
	s_setprio 1
	v_mfma_f32_16x16x32_bf16 v[46:49], v[132:135], v[156:159], v[46:49]
	v_mfma_f32_16x16x32_bf16 v[42:45], v[140:143], v[156:159], v[42:45]
	v_mfma_f32_16x16x32_bf16 v[30:33], v[132:135], v[164:167], v[30:33]
	v_mfma_f32_16x16x32_bf16 v[26:29], v[140:143], v[164:167], v[26:29]
	v_mfma_f32_16x16x32_bf16 v[14:17], v[132:135], v[172:175], v[14:17]
	v_mfma_f32_16x16x32_bf16 v[10:13], v[140:143], v[172:175], v[10:13]
	v_mfma_f32_16x16x32_bf16 v[62:65], v[136:139], v[152:155], v[62:65]
	v_mfma_f32_16x16x32_bf16 v[58:61], v[144:147], v[152:155], v[58:61]
	v_mfma_f32_16x16x32_bf16 v[46:49], v[136:139], v[160:163], v[46:49]
	v_mfma_f32_16x16x32_bf16 v[42:45], v[144:147], v[160:163], v[42:45]
	v_mfma_f32_16x16x32_bf16 v[30:33], v[136:139], v[168:171], v[30:33]
	v_mfma_f32_16x16x32_bf16 v[26:29], v[144:147], v[168:171], v[26:29]
	v_mfma_f32_16x16x32_bf16 v[14:17], v[136:139], v[196:199], v[14:17]
	v_mfma_f32_16x16x32_bf16 v[10:13], v[144:147], v[196:199], v[10:13]
	v_mfma_f32_16x16x32_bf16 v[54:57], v[200:203], v[148:151], v[54:57]
	v_mfma_f32_16x16x32_bf16 v[50:53], v[208:211], v[148:151], v[50:53]
	v_mfma_f32_16x16x32_bf16 v[38:41], v[200:203], v[156:159], v[38:41]
	v_mfma_f32_16x16x32_bf16 v[34:37], v[208:211], v[156:159], v[34:37]
	v_mfma_f32_16x16x32_bf16 v[22:25], v[200:203], v[164:167], v[22:25]
	v_mfma_f32_16x16x32_bf16 v[18:21], v[208:211], v[164:167], v[18:21]
	v_mfma_f32_16x16x32_bf16 v[6:9], v[200:203], v[172:175], v[6:9]
	v_mfma_f32_16x16x32_bf16 v[2:5], v[208:211], v[172:175], v[2:5]
	v_mfma_f32_16x16x32_bf16 v[54:57], v[204:207], v[152:155], v[54:57]
	v_mfma_f32_16x16x32_bf16 v[50:53], v[212:215], v[152:155], v[50:53]
	v_mfma_f32_16x16x32_bf16 v[38:41], v[204:207], v[160:163], v[38:41]
	v_mfma_f32_16x16x32_bf16 v[34:37], v[212:215], v[160:163], v[34:37]
	v_mfma_f32_16x16x32_bf16 v[22:25], v[204:207], v[168:171], v[22:25]
	v_mfma_f32_16x16x32_bf16 v[18:21], v[212:215], v[168:171], v[18:21]
	v_mfma_f32_16x16x32_bf16 v[6:9], v[204:207], v[196:199], v[6:9]
	v_mfma_f32_16x16x32_bf16 v[2:5], v[212:215], v[196:199], v[2:5]
	s_setprio 0
	s_barrier
	s_add_i32 s8, 0, 0x18000
	v_add_u32_e32 v144, s8, v236
	ds_read_b128 v[132:135], v144
	ds_read_b128 v[136:139], v144 offset:1024
	ds_read_b128 v[140:143], v144 offset:2048
	ds_read_b128 v[144:147], v144 offset:3072
	s_add_u32 s4, s4, s6
	s_addc_u32 s5, s5, s7
	s_mov_b32 m0, s91
	v_lshl_add_u64 v[200:201], s[4:5], 0, v[178:179]
	ds_read_b128 v[148:151], v239 offset:32768
	ds_read_b128 v[152:155], v239 offset:33792
	ds_read_b128 v[156:159], v239 offset:34816
	ds_read_b128 v[160:163], v239 offset:35840
	ds_read_b128 v[164:167], v239 offset:36864
	ds_read_b128 v[168:171], v239 offset:37888
	ds_read_b128 v[172:175], v239 offset:38912
	ds_read_b128 v[196:199], v239 offset:39936
	global_load_lds_dwordx4 v[200:201], off
	v_lshl_add_u64 v[200:201], s[4:5], 0, v[182:183]
	s_mov_b32 m0, s92
	s_nop 0
	global_load_lds_dwordx4 v[200:201], off
	s_add_i32 s4, 0, 0x1c000
	v_add_u32_e32 v212, s4, v236
	ds_read_b128 v[200:203], v212
	ds_read_b128 v[204:207], v212 offset:1024
	ds_read_b128 v[208:211], v212 offset:2048
	ds_read_b128 v[212:215], v212 offset:3072
	s_waitcnt vmcnt(8)
	s_waitcnt lgkmcnt(0)
	v_mfma_f32_16x16x32_bf16 v[126:129], v[132:135], v[148:151], v[126:129]
	v_mfma_f32_16x16x32_bf16 v[122:125], v[140:143], v[148:151], v[122:125]
	s_barrier
	s_setprio 1
	v_mfma_f32_16x16x32_bf16 v[110:113], v[132:135], v[156:159], v[110:113]
	v_mfma_f32_16x16x32_bf16 v[106:109], v[140:143], v[156:159], v[106:109]
	v_mfma_f32_16x16x32_bf16 v[94:97], v[132:135], v[164:167], v[94:97]
	v_mfma_f32_16x16x32_bf16 v[90:93], v[140:143], v[164:167], v[90:93]
	v_mfma_f32_16x16x32_bf16 v[78:81], v[132:135], v[172:175], v[78:81]
	v_mfma_f32_16x16x32_bf16 v[74:77], v[140:143], v[172:175], v[74:77]
	v_mfma_f32_16x16x32_bf16 v[126:129], v[136:139], v[152:155], v[126:129]
	v_mfma_f32_16x16x32_bf16 v[122:125], v[144:147], v[152:155], v[122:125]
	v_mfma_f32_16x16x32_bf16 v[110:113], v[136:139], v[160:163], v[110:113]
	v_mfma_f32_16x16x32_bf16 v[106:109], v[144:147], v[160:163], v[106:109]
	v_mfma_f32_16x16x32_bf16 v[94:97], v[136:139], v[168:171], v[94:97]
	v_mfma_f32_16x16x32_bf16 v[90:93], v[144:147], v[168:171], v[90:93]
	v_mfma_f32_16x16x32_bf16 v[78:81], v[136:139], v[196:199], v[78:81]
	v_mfma_f32_16x16x32_bf16 v[74:77], v[144:147], v[196:199], v[74:77]
	v_mfma_f32_16x16x32_bf16 v[118:121], v[200:203], v[148:151], v[118:121]
	v_mfma_f32_16x16x32_bf16 v[114:117], v[208:211], v[148:151], v[114:117]
	v_mfma_f32_16x16x32_bf16 v[102:105], v[200:203], v[156:159], v[102:105]
	v_mfma_f32_16x16x32_bf16 v[98:101], v[208:211], v[156:159], v[98:101]
	v_mfma_f32_16x16x32_bf16 v[86:89], v[200:203], v[164:167], v[86:89]
	v_mfma_f32_16x16x32_bf16 v[82:85], v[208:211], v[164:167], v[82:85]
	v_mfma_f32_16x16x32_bf16 v[70:73], v[200:203], v[172:175], v[70:73]
	v_mfma_f32_16x16x32_bf16 v[66:69], v[208:211], v[172:175], v[66:69]
	v_mfma_f32_16x16x32_bf16 v[118:121], v[204:207], v[152:155], v[118:121]
	v_mfma_f32_16x16x32_bf16 v[114:117], v[212:215], v[152:155], v[114:117]
	v_mfma_f32_16x16x32_bf16 v[102:105], v[204:207], v[160:163], v[102:105]
	v_mfma_f32_16x16x32_bf16 v[98:101], v[212:215], v[160:163], v[98:101]
	v_mfma_f32_16x16x32_bf16 v[86:89], v[204:207], v[168:171], v[86:89]
	v_mfma_f32_16x16x32_bf16 v[82:85], v[212:215], v[168:171], v[82:85]
	v_mfma_f32_16x16x32_bf16 v[70:73], v[204:207], v[196:199], v[70:73]
	v_mfma_f32_16x16x32_bf16 v[66:69], v[212:215], v[196:199], v[66:69]
	s_setprio 0
	s_barrier
; #define PG8_STAGE(bufoff, gbase, voff) do { _Pragma("unroll") for (int _i = 0; _i < 2; ++_i) \
;         __builtin_amdgcn_global_load_lds((const unsigned*)((const char*)(gbase) + (voff)[_i]), (LAS unsigned*)(lds + (bufoff) + ldsw + _i * 8192), 16, 0, 0); } while (0)
; #define PG8_LDA(dst, b, h) do { _Pragma("unroll") for (int m = 0; m < 4; ++m) _Pragma("unroll") for (int k = 0; k < 2; ++k) dst[m][k] = *(const LAS bf16x8*)(lds + PG8_SA(b, h) + aoff + m * 2048 + k * 1024); } while (0)
; #define PG8_LDB(dst, b, h) do { _Pragma("unroll") for (int n = 0; n < 2; ++n) _Pragma("unroll") for (int k = 0; k < 2; ++k) dst[n][k] = *(const LAS bf16x8*)(lds + PG8_SB(b, h) + boff + n * 2048 + k * 1024); } while (0)
; #define PG8_MMA(ai, bj, At, Bt) do { __builtin_amdgcn_s_setprio(1); _Pragma("unroll") for (int m = 0; m < 4; ++m) _Pragma("unroll") for (int n = 0; n < 2; ++n) _Pragma("unroll") for (int k = 0; k < 2; ++k) \
;         acc[ai][bj][m][n] = __builtin_amdgcn_mfma_f32_16x16x32_bf16(Bt[n][k], At[m][k], acc[ai][bj][m][n], 0, 0, 0); __builtin_amdgcn_s_setprio(0); } while (0)
; template <class Epi>
; __device__ __forceinline__ void gemm_phase(LAS unsigned char* lds, const Gemm g, const Sched& S, const Epi& E) {
;     ...
;             PG8_LDB(B0, 1, 0); PG8_SCHED; PG8_LDA(At, 1, 0); PG8_STAGE(PG8_SA(0, 1), a2 + hstepA, voffA);
;             PG8_WAIT_L(8); PG8_BAR; PG8_WAIT_L(0); PG8_MMA(0, 0, At, B0); PG8_BAR; PG8_SCHED;
;             PG8_LDB(B1, 1, 1); PG8_STAGE(PG8_SB(1, 0), b3, voffB);
;             PG8_BAR; PG8_WAIT_L(0); PG8_MMA(0, 1, At, B1); PG8_BAR;
;             PG8_LDA(At, 1, 1); PG8_STAGE(PG8_SA(1, 0), a3, voffA);
;             PG8_BAR; PG8_WAIT_L(0); PG8_MMA(1, 0, At, B0); PG8_BAR; PG8_SCHED;
;             PG8_STAGE(PG8_SB(1, 1), b3 + hstepB, voffB);
;             PG8_WAIT_V(6); PG8_BAR; PG8_MMA(1, 1, At, B1); PG8_BAR;
;         }
;     __device__ __forceinline__ void operator()(const Acc& acc, const Unit& u, int wr, int wc, int fr, int fq, const Pre& pre) const {
;         const int tile = u.pn; int mode = 0; float scale0 = 1.f;
;         if (tile < 36) { const int tg = tile % 12; if (tg < 4) { mode = 1; scale0 = 0.08838834764831845f * LOG2E; } else if (tg < 8) mode = 1; }
;         else if (tile < 40) mode = 1;
;         else if (tile < 44) { mode = 1; scale0 = 0.08838834764831845f; }
;         else if (tile >= 52) mode = 2;
	s_add_i32 s5, s8, s88
	v_lshl_add_u64 v[176:177], v[176:177], 0, s[60:61]
	s_mov_b32 m0, s5
	s_nop 0
	global_load_lds_dwordx4 v[176:177], off
	v_lshl_add_u64 v[176:177], v[192:193], 0, s[60:61]
	s_add_i32 m0, s5, 0x2000
	s_nop 0
	global_load_lds_dwordx4 v[176:177], off
	s_mov_b32 m0, s93
	v_lshl_add_u64 v[176:177], v[194:195], 0, s[60:61]
	ds_read_b128 v[148:151], v239 offset:49152
	ds_read_b128 v[152:155], v239 offset:50176
	ds_read_b128 v[156:159], v239 offset:51200
	ds_read_b128 v[160:163], v239 offset:52224
	ds_read_b128 v[164:167], v239 offset:53248
	ds_read_b128 v[168:171], v239 offset:54272
	ds_read_b128 v[172:175], v239 offset:55296
	ds_read_b128 v[196:199], v239 offset:56320
	global_load_lds_dwordx4 v[176:177], off
	v_lshl_add_u64 v[176:177], v[216:217], 0, s[60:61]
	s_mov_b32 m0, s94
	s_nop 0
	global_load_lds_dwordx4 v[176:177], off
	s_add_i32 s4, s4, s88
	v_lshl_add_u64 v[176:177], v[222:223], 0, s[60:61]
	s_mov_b32 m0, s4
	s_nop 0
	global_load_lds_dwordx4 v[176:177], off
	v_lshl_add_u64 v[176:177], v[224:225], 0, s[60:61]
	s_add_i32 m0, s4, 0x2000
	s_nop 0
	global_load_lds_dwordx4 v[176:177], off
	s_waitcnt vmcnt(8)
	s_waitcnt lgkmcnt(0)
	v_mfma_f32_16x16x32_bf16 v[62:65], v[132:135], v[148:151], v[62:65]
	v_mfma_f32_16x16x32_bf16 v[58:61], v[140:143], v[148:151], v[58:61]
	s_barrier
	s_setprio 1
	v_mfma_f32_16x16x32_bf16 v[46:49], v[132:135], v[156:159], v[46:49]
	v_mfma_f32_16x16x32_bf16 v[42:45], v[140:143], v[156:159], v[42:45]
	v_mfma_f32_16x16x32_bf16 v[30:33], v[132:135], v[164:167], v[30:33]
	v_mfma_f32_16x16x32_bf16 v[26:29], v[140:143], v[164:167], v[26:29]
	v_mfma_f32_16x16x32_bf16 v[14:17], v[132:135], v[172:175], v[14:17]
	v_mfma_f32_16x16x32_bf16 v[10:13], v[140:143], v[172:175], v[10:13]
	v_mfma_f32_16x16x32_bf16 v[62:65], v[136:139], v[152:155], v[62:65]
	v_mfma_f32_16x16x32_bf16 v[58:61], v[144:147], v[152:155], v[58:61]
	v_mfma_f32_16x16x32_bf16 v[46:49], v[136:139], v[160:163], v[46:49]
	v_mfma_f32_16x16x32_bf16 v[42:45], v[144:147], v[160:163], v[42:45]
	v_mfma_f32_16x16x32_bf16 v[30:33], v[136:139], v[168:171], v[30:33]
	v_mfma_f32_16x16x32_bf16 v[26:29], v[144:147], v[168:171], v[26:29]
	v_mfma_f32_16x16x32_bf16 v[14:17], v[136:139], v[196:199], v[14:17]
	v_mfma_f32_16x16x32_bf16 v[10:13], v[144:147], v[196:199], v[10:13]
	v_mfma_f32_16x16x32_bf16 v[54:57], v[200:203], v[148:151], v[54:57]
	v_mfma_f32_16x16x32_bf16 v[50:53], v[208:211], v[148:151], v[50:53]
	v_mfma_f32_16x16x32_bf16 v[38:41], v[200:203], v[156:159], v[38:41]
	v_mfma_f32_16x16x32_bf16 v[34:37], v[208:211], v[156:159], v[34:37]
	v_mfma_f32_16x16x32_bf16 v[22:25], v[200:203], v[164:167], v[22:25]
	v_mfma_f32_16x16x32_bf16 v[18:21], v[208:211], v[164:167], v[18:21]
	v_mfma_f32_16x16x32_bf16 v[6:9], v[200:203], v[172:175], v[6:9]
	v_mfma_f32_16x16x32_bf16 v[2:5], v[208:211], v[172:175], v[2:5]
	v_mfma_f32_16x16x32_bf16 v[54:57], v[204:207], v[152:155], v[54:57]
	v_mfma_f32_16x16x32_bf16 v[50:53], v[212:215], v[152:155], v[50:53]
	v_mfma_f32_16x16x32_bf16 v[38:41], v[204:207], v[160:163], v[38:41]
	v_mfma_f32_16x16x32_bf16 v[34:37], v[212:215], v[160:163], v[34:37]
	v_mfma_f32_16x16x32_bf16 v[22:25], v[204:207], v[168:171], v[22:25]
	v_mfma_f32_16x16x32_bf16 v[18:21], v[212:215], v[168:171], v[18:21]
	v_mfma_f32_16x16x32_bf16 v[6:9], v[204:207], v[196:199], v[6:9]
	v_mfma_f32_16x16x32_bf16 v[2:5], v[212:215], v[196:199], v[2:5]
	s_setprio 0
	s_add_u32 s0, s0, 0x100
	s_addc_u32 s1, s1, 0
	s_add_u32 s34, s34, 0x100
	s_addc_u32 s35, s35, 0
	s_cmp_ge_u32 s14, s73
	s_mov_b32 s4, s14
	s_barrier
	s_cbranch_scc0 .LBB0_649
	s_cmp_gt_i32 s3, 35
	s_cbranch_scc0 .LBB0_652
	s_cmp_gt_u32 s3, 51
	s_cselect_b32 s8, 2, 0
	s_cmp_gt_u32 s3, 39
	s_cselect_b64 s[0:1], -1, 0
	s_cmp_lt_u32 s3, 44
	s_cselect_b64 s[14:15], -1, 0
	s_and_b64 s[4:5], s[14:15], exec
	s_cselect_b32 s4, 1, s8
	s_and_b64 vcc, s[0:1], s[14:15]
	v_mov_b32_e32 v132, 0x3db504f3
	v_cndmask_b32_e32 v240, 1.0, v132, vcc
	v_mov_b32_e32 v132, s4
	s_cbranch_execz .LBB0_653
	s_branch .LBB0_654

; #define PG8_STAGE(bufoff, gbase, voff) do { _Pragma("unroll") for (int _i = 0; _i < 2; ++_i) \
;         __builtin_amdgcn_global_load_lds((const unsigned*)((const char*)(gbase) + (voff)[_i]), (LAS unsigned*)(lds + (bufoff) + ldsw + _i * 8192), 16, 0, 0); } while (0)
; #define PG8_LDA(dst, b, h) do { _Pragma("unroll") for (int m = 0; m < 4; ++m) _Pragma("unroll") for (int k = 0; k < 2; ++k) dst[m][k] = *(const LAS bf16x8*)(lds + PG8_SA(b, h) + aoff + m * 2048 + k * 1024); } while (0)
; #define PG8_LDB(dst, b, h) do { _Pragma("unroll") for (int n = 0; n < 2; ++n) _Pragma("unroll") for (int k = 0; k < 2; ++k) dst[n][k] = *(const LAS bf16x8*)(lds + PG8_SB(b, h) + boff + n * 2048 + k * 1024); } while (0)
; #define PG8_WAIT_V(n) asm volatile("s_waitcnt vmcnt(" #n ")" ::: "memory")
; #define PG8_WAIT_L(n) asm volatile("s_waitcnt lgkmcnt(" #n ")" ::: "memory")
; #define PG8_BAR __builtin_amdgcn_s_barrier()
; #define PG8_SCHED __builtin_amdgcn_sched_barrier(0)
; template <class Epi>
; __device__ __forceinline__ void gemm_phase(LAS unsigned char* lds, const Gemm g, const Sched& S, const Epi& E) {
;     ...
;         for (int t = 0; t < nt; t += 2) {
;             const bool last = (t == nt - 2);
;             const char* a1 = cA + (size_t)(t + 1) * kstep;
;             const char* a2 = last ? nA : cA + (size_t)(t + 2) * kstep; const char* b2 = last ? nB : cB + (size_t)(t + 2) * kstep;
;             const char* a3 = a2 + kstep; const char* b3 = b2 + kstep;
;             PG8_LDB(B0, 0, 0); PG8_SCHED; PG8_LDA(At, 0, 0); PG8_STAGE(PG8_SA(1, 1), a1 + hstepA, voffA);
;             PG8_WAIT_L(8); PG8_BAR; PG8_WAIT_L(0); PG8_MMA(0, 0, At, B0); PG8_BAR; PG8_SCHED;
;             PG8_LDB(B1, 0, 1); PG8_STAGE(PG8_SB(0, 0), b2, voffB);
;             PG8_BAR; PG8_WAIT_L(0); PG8_MMA(0, 1, At, B1); PG8_BAR;
;             PG8_LDA(At, 0, 1); PG8_STAGE(PG8_SA(0, 0), a2, voffA);
;             PG8_BAR; PG8_WAIT_L(0); PG8_MMA(1, 0, At, B0); PG8_BAR; PG8_SCHED;
;             PG8_STAGE(PG8_SB(0, 1), b2 + hstepB, voffB);
;             PG8_WAIT_V(6); PG8_BAR; PG8_MMA(1, 1, At, B1); PG8_BAR;
;             PG8_LDB(B0, 1, 0); PG8_SCHED; PG8_LDA(At, 1, 0); PG8_STAGE(PG8_SA(0, 1), a2 + hstepA, voffA);
;             PG8_WAIT_L(8); PG8_BAR; PG8_WAIT_L(0); PG8_MMA(0, 0, At, B0); PG8_BAR; PG8_SCHED;
.LBB0_719:
	s_add_i32 s14, s4, 2
	s_add_u32 s15, s0, 0x80
	s_addc_u32 s5, s1, 0
	s_add_i32 s8, 0, 0x10000
	v_add_u32_e32 v118, s8, v217
	ds_read_b128 v[106:109], v118
	ds_read_b128 v[110:113], v118 offset:1024
	ds_read_b128 v[114:117], v118 offset:2048
	ds_read_b128 v[118:121], v118 offset:3072
	s_cmp_eq_u32 s48, s4
	s_cselect_b32 s4, s59, s15
	s_cselect_b32 s5, s57, s5
	s_cselect_b32 s95, vcc_lo, s35
	s_cselect_b32 s94, vcc_hi, s34
	v_lshl_add_u64 v[154:155], s[0:1], 0, v[202:203]
	s_add_i32 m0, s52, 0xc000
	ds_read_b128 v[122:125], v235
	ds_read_b128 v[126:129], v235 offset:1024
	ds_read_b128 v[130:133], v235 offset:2048
	ds_read_b128 v[134:137], v235 offset:3072
	ds_read_b128 v[138:141], v235 offset:4096
	ds_read_b128 v[142:145], v235 offset:5120
	ds_read_b128 v[146:149], v235 offset:6144
	ds_read_b128 v[150:153], v235 offset:7168
	global_load_lds_dwordx4 v[154:155], off
	v_lshl_add_u64 v[154:155], s[0:1], 0, v[204:205]
	s_add_i32 m0, s52, 0xe000
	s_nop 0
	global_load_lds_dwordx4 v[154:155], off
	s_waitcnt lgkmcnt(8)
	s_waitcnt lgkmcnt(0)
	v_mfma_f32_16x16x32_bf16 v[162:165], v[114:117], v[130:133], v[162:165]
	v_mfma_f32_16x16x32_bf16 v[94:97], v[106:109], v[138:141], v[94:97]
	s_barrier
	s_waitcnt lgkmcnt(0)
	s_setprio 1
	s_waitcnt lgkmcnt(0)
	v_mfma_f32_16x16x32_bf16 v[90:93], v[114:117], v[138:141], v[90:93]
	v_mfma_f32_16x16x32_bf16 v[78:81], v[106:109], v[146:149], v[78:81]
	v_mfma_f32_16x16x32_bf16 v[74:77], v[114:117], v[146:149], v[74:77]
	v_mfma_f32_16x16x32_bf16 v[154:157], v[106:109], v[122:125], v[190:193]
	v_mfma_f32_16x16x32_bf16 v[158:161], v[114:117], v[122:125], v[186:189]
	v_mfma_f32_16x16x32_bf16 v[166:169], v[106:109], v[130:133], v[174:177]
	v_mfma_f32_16x16x32_bf16 v[162:165], v[118:121], v[134:137], v[162:165]
	v_mfma_f32_16x16x32_bf16 v[94:97], v[110:113], v[142:145], v[94:97]
	v_mfma_f32_16x16x32_bf16 v[90:93], v[118:121], v[142:145], v[90:93]
	v_mfma_f32_16x16x32_bf16 v[78:81], v[110:113], v[150:153], v[78:81]
	v_mfma_f32_16x16x32_bf16 v[74:77], v[118:121], v[150:153], v[74:77]
	v_mfma_f32_16x16x32_bf16 v[154:157], v[110:113], v[126:129], v[154:157]
	v_mfma_f32_16x16x32_bf16 v[158:161], v[118:121], v[126:129], v[158:161]
	v_mfma_f32_16x16x32_bf16 v[166:169], v[110:113], v[134:137], v[166:169]
	s_setprio 0
	s_barrier
	s_add_i32 s9, 0, 0x14000
	s_add_i32 s8, s8, s43
	v_add_u32_e32 v190, s9, v217
	v_lshl_add_u64 v[210:211], s[94:95], 0, v[0:1]
	s_mov_b32 m0, s8
	ds_read_b128 v[170:173], v190
	ds_read_b128 v[174:177], v190 offset:1024
	ds_read_b128 v[186:189], v190 offset:2048
	ds_read_b128 v[190:193], v190 offset:3072
	global_load_lds_dwordx4 v[210:211], off
	v_lshl_add_u64 v[212:213], s[94:95], 0, v[200:201]
	s_add_i32 m0, s8, 0x2000
	s_nop 0
	global_load_lds_dwordx4 v[212:213], off
	s_waitcnt lgkmcnt(0)
	v_mfma_f32_16x16x32_bf16 v[182:185], v[170:173], v[122:125], v[182:185]
	v_mfma_f32_16x16x32_bf16 v[102:105], v[170:173], v[130:133], v[102:105]
	s_barrier
	s_waitcnt lgkmcnt(0)
	s_setprio 1
	s_waitcnt lgkmcnt(0)
	v_mfma_f32_16x16x32_bf16 v[98:101], v[186:189], v[130:133], v[98:101]
	v_mfma_f32_16x16x32_bf16 v[86:89], v[170:173], v[138:141], v[86:89]
	v_mfma_f32_16x16x32_bf16 v[82:85], v[186:189], v[138:141], v[82:85]
	v_mfma_f32_16x16x32_bf16 v[70:73], v[170:173], v[146:149], v[70:73]
	v_mfma_f32_16x16x32_bf16 v[66:69], v[186:189], v[146:149], v[66:69]
	v_mfma_f32_16x16x32_bf16 v[182:185], v[174:177], v[126:129], v[182:185]
	v_mfma_f32_16x16x32_bf16 v[122:125], v[186:189], v[122:125], v[178:181]
	v_mfma_f32_16x16x32_bf16 v[102:105], v[174:177], v[134:137], v[102:105]
	v_mfma_f32_16x16x32_bf16 v[98:101], v[190:193], v[134:137], v[98:101]
	v_mfma_f32_16x16x32_bf16 v[86:89], v[174:177], v[142:145], v[86:89]
	v_mfma_f32_16x16x32_bf16 v[82:85], v[190:193], v[142:145], v[82:85]
	v_mfma_f32_16x16x32_bf16 v[70:73], v[174:177], v[150:153], v[70:73]
	v_mfma_f32_16x16x32_bf16 v[66:69], v[190:193], v[150:153], v[66:69]
	v_mfma_f32_16x16x32_bf16 v[122:125], v[190:193], v[126:129], v[122:125]
	s_setprio 0
	s_mov_b32 m0, s52
	v_lshl_add_u64 v[214:215], s[4:5], 0, v[196:197]
	s_barrier
	ds_read_b128 v[126:129], v235 offset:16384
	ds_read_b128 v[130:133], v235 offset:17408
	ds_read_b128 v[134:137], v235 offset:18432
	ds_read_b128 v[138:141], v235 offset:19456
	ds_read_b128 v[142:145], v235 offset:20480
	ds_read_b128 v[146:149], v235 offset:21504
	ds_read_b128 v[150:153], v235 offset:22528
	ds_read_b128 v[178:181], v235 offset:23552
	global_load_lds_dwordx4 v[214:215], off
	v_lshl_add_u64 v[222:223], s[4:5], 0, v[198:199]
	s_mov_b32 m0, s53
	s_nop 0
	global_load_lds_dwordx4 v[222:223], off
	s_waitcnt lgkmcnt(0)
	v_mfma_f32_16x16x32_bf16 v[62:65], v[106:109], v[126:129], v[62:65]
	v_mfma_f32_16x16x32_bf16 v[58:61], v[114:117], v[126:129], v[58:61]
	s_barrier
	s_waitcnt lgkmcnt(0)
	s_setprio 1
	s_waitcnt lgkmcnt(0)
	v_mfma_f32_16x16x32_bf16 v[46:49], v[106:109], v[134:137], v[46:49]
	v_mfma_f32_16x16x32_bf16 v[42:45], v[114:117], v[134:137], v[42:45]
	v_mfma_f32_16x16x32_bf16 v[30:33], v[106:109], v[142:145], v[30:33]
	v_mfma_f32_16x16x32_bf16 v[26:29], v[114:117], v[142:145], v[26:29]
	v_mfma_f32_16x16x32_bf16 v[14:17], v[106:109], v[150:153], v[14:17]
	v_mfma_f32_16x16x32_bf16 v[10:13], v[114:117], v[150:153], v[10:13]
	v_mfma_f32_16x16x32_bf16 v[62:65], v[110:113], v[130:133], v[62:65]
	v_mfma_f32_16x16x32_bf16 v[58:61], v[118:121], v[130:133], v[58:61]
	v_mfma_f32_16x16x32_bf16 v[46:49], v[110:113], v[138:141], v[46:49]
	v_mfma_f32_16x16x32_bf16 v[42:45], v[118:121], v[138:141], v[42:45]
	v_mfma_f32_16x16x32_bf16 v[30:33], v[110:113], v[146:149], v[30:33]
	v_mfma_f32_16x16x32_bf16 v[26:29], v[118:121], v[146:149], v[26:29]
	v_mfma_f32_16x16x32_bf16 v[14:17], v[110:113], v[178:181], v[14:17]
	v_mfma_f32_16x16x32_bf16 v[10:13], v[118:121], v[178:181], v[10:13]
	s_setprio 0
	s_barrier
; #define PG8_STAGE(bufoff, gbase, voff) do { _Pragma("unroll") for (int _i = 0; _i < 2; ++_i) \
;         __builtin_amdgcn_global_load_lds((const unsigned*)((const char*)(gbase) + (voff)[_i]), (LAS unsigned*)(lds + (bufoff) + ldsw + _i * 8192), 16, 0, 0); } while (0)
; #define PG8_LDA(dst, b, h) do { _Pragma("unroll") for (int m = 0; m < 4; ++m) _Pragma("unroll") for (int k = 0; k < 2; ++k) dst[m][k] = *(const LAS bf16x8*)(lds + PG8_SA(b, h) + aoff + m * 2048 + k * 1024); } while (0)
; #define PG8_LDB(dst, b, h) do { _Pragma("unroll") for (int n = 0; n < 2; ++n) _Pragma("unroll") for (int k = 0; k < 2; ++k) dst[n][k] = *(const LAS bf16x8*)(lds + PG8_SB(b, h) + boff + n * 2048 + k * 1024); } while (0)
; #define PG8_MMA(ai, bj, At, Bt) do { __builtin_amdgcn_s_setprio(1); _Pragma("unroll") for (int m = 0; m < 4; ++m) _Pragma("unroll") for (int n = 0; n < 2; ++n) _Pragma("unroll") for (int k = 0; k < 2; ++k) \
;         acc[ai][bj][m][n] = __builtin_amdgcn_mfma_f32_16x16x32_bf16(Bt[n][k], At[m][k], acc[ai][bj][m][n], 0, 0, 0); __builtin_amdgcn_s_setprio(0); } while (0)
; #define PG8_WAIT_V(n) asm volatile("s_waitcnt vmcnt(" #n ")" ::: "memory")
; #define PG8_WAIT_L(n) asm volatile("s_waitcnt lgkmcnt(" #n ")" ::: "memory")
; #define PG8_BAR __builtin_amdgcn_s_barrier()
; #define PG8_SCHED __builtin_amdgcn_sched_barrier(0)
; template <class Epi>
; __device__ __forceinline__ void gemm_phase(LAS unsigned char* lds, const Gemm g, const Sched& S, const Epi& E) {
;     ...
;             PG8_LDB(B0, 1, 0); PG8_SCHED; PG8_LDA(At, 1, 0); PG8_STAGE(PG8_SA(0, 1), a2 + hstepA, voffA);
;             PG8_WAIT_L(8); PG8_BAR; PG8_WAIT_L(0); PG8_MMA(0, 0, At, B0); PG8_BAR; PG8_SCHED;
;             PG8_LDB(B1, 1, 1); PG8_STAGE(PG8_SB(1, 0), b3, voffB);
;             PG8_BAR; PG8_WAIT_L(0); PG8_MMA(0, 1, At, B1); PG8_BAR;
;             PG8_LDA(At, 1, 1); PG8_STAGE(PG8_SA(1, 0), a3, voffA);
;             PG8_BAR; PG8_WAIT_L(0); PG8_MMA(1, 0, At, B0); PG8_BAR; PG8_SCHED;
;             PG8_STAGE(PG8_SB(1, 1), b3 + hstepB, voffB);
;             PG8_WAIT_V(6); PG8_BAR; PG8_MMA(1, 1, At, B1); PG8_BAR;
	s_add_u32 s94, s94, s76
	s_addc_u32 s95, s95, s77
	s_add_i32 s8, s9, s43
	v_lshl_add_u64 v[224:225], s[94:95], 0, v[0:1]
	s_mov_b32 m0, s8
	v_lshl_add_u64 v[226:227], s[94:95], 0, v[200:201]
	global_load_lds_dwordx4 v[224:225], off
	s_add_i32 m0, s8, 0x2000
	s_nop 0
	global_load_lds_dwordx4 v[226:227], off
	s_waitcnt vmcnt(6)
	s_waitcnt lgkmcnt(0)
	v_mfma_f32_16x16x32_bf16 v[54:57], v[170:173], v[126:129], v[54:57]
	v_mfma_f32_16x16x32_bf16 v[50:53], v[186:189], v[126:129], v[50:53]
	s_barrier
	s_setprio 1
	v_mfma_f32_16x16x32_bf16 v[38:41], v[170:173], v[134:137], v[38:41]
	v_mfma_f32_16x16x32_bf16 v[34:37], v[186:189], v[134:137], v[34:37]
	v_mfma_f32_16x16x32_bf16 v[22:25], v[170:173], v[142:145], v[22:25]
	v_mfma_f32_16x16x32_bf16 v[18:21], v[186:189], v[142:145], v[18:21]
	v_mfma_f32_16x16x32_bf16 v[6:9], v[170:173], v[150:153], v[6:9]
	v_mfma_f32_16x16x32_bf16 v[2:5], v[186:189], v[150:153], v[2:5]
	v_mfma_f32_16x16x32_bf16 v[54:57], v[174:177], v[130:133], v[54:57]
	v_mfma_f32_16x16x32_bf16 v[50:53], v[190:193], v[130:133], v[50:53]
	v_mfma_f32_16x16x32_bf16 v[38:41], v[174:177], v[138:141], v[38:41]
	v_mfma_f32_16x16x32_bf16 v[34:37], v[190:193], v[138:141], v[34:37]
	v_mfma_f32_16x16x32_bf16 v[22:25], v[174:177], v[146:149], v[22:25]
	v_mfma_f32_16x16x32_bf16 v[18:21], v[190:193], v[146:149], v[18:21]
	v_mfma_f32_16x16x32_bf16 v[6:9], v[174:177], v[178:181], v[6:9]
	v_mfma_f32_16x16x32_bf16 v[2:5], v[190:193], v[178:181], v[2:5]
	s_setprio 0
	s_add_i32 s8, 0, 0x18000
	v_add_u32_e32 v118, s8, v217
	s_barrier
	ds_read_b128 v[106:109], v118
	ds_read_b128 v[110:113], v118 offset:1024
	ds_read_b128 v[114:117], v118 offset:2048
	ds_read_b128 v[118:121], v118 offset:3072
	s_add_u32 s4, s4, s40
	s_addc_u32 s5, s5, s41
	s_mov_b32 m0, s56
	v_lshl_add_u64 v[174:175], s[4:5], 0, v[196:197]
	ds_read_b128 v[126:129], v235 offset:32768
	ds_read_b128 v[130:133], v235 offset:33792
	ds_read_b128 v[134:137], v235 offset:34816
	ds_read_b128 v[138:141], v235 offset:35840
	ds_read_b128 v[142:145], v235 offset:36864
	ds_read_b128 v[146:149], v235 offset:37888
	ds_read_b128 v[150:153], v235 offset:38912
	ds_read_b128 v[170:173], v235 offset:39936
	global_load_lds_dwordx4 v[174:175], off
	v_lshl_add_u64 v[174:175], s[4:5], 0, v[198:199]
	s_mov_b32 m0, s67
	s_nop 0
	global_load_lds_dwordx4 v[174:175], off
	s_waitcnt lgkmcnt(8)
	s_waitcnt lgkmcnt(0)
	v_mfma_f32_16x16x32_bf16 v[154:157], v[106:109], v[126:129], v[154:157]
	v_mfma_f32_16x16x32_bf16 v[190:193], v[110:113], v[130:133], v[154:157]
	s_barrier
	s_waitcnt lgkmcnt(0)
	s_setprio 1
	s_waitcnt lgkmcnt(0)
	v_mfma_f32_16x16x32_bf16 v[154:157], v[114:117], v[126:129], v[158:161]
	v_mfma_f32_16x16x32_bf16 v[186:189], v[118:121], v[130:133], v[154:157]
	v_mfma_f32_16x16x32_bf16 v[154:157], v[106:109], v[134:137], v[166:169]
	v_mfma_f32_16x16x32_bf16 v[174:177], v[110:113], v[138:141], v[154:157]
	v_mfma_f32_16x16x32_bf16 v[154:157], v[114:117], v[134:137], v[162:165]
	v_mfma_f32_16x16x32_bf16 v[94:97], v[106:109], v[142:145], v[94:97]
	v_mfma_f32_16x16x32_bf16 v[90:93], v[114:117], v[142:145], v[90:93]
	v_mfma_f32_16x16x32_bf16 v[78:81], v[106:109], v[150:153], v[78:81]
	v_mfma_f32_16x16x32_bf16 v[74:77], v[114:117], v[150:153], v[74:77]
	v_mfma_f32_16x16x32_bf16 v[162:165], v[118:121], v[138:141], v[154:157]
	v_mfma_f32_16x16x32_bf16 v[94:97], v[110:113], v[146:149], v[94:97]
	v_mfma_f32_16x16x32_bf16 v[90:93], v[118:121], v[146:149], v[90:93]
	v_mfma_f32_16x16x32_bf16 v[78:81], v[110:113], v[170:173], v[78:81]
	v_mfma_f32_16x16x32_bf16 v[74:77], v[118:121], v[170:173], v[74:77]
	s_setprio 0
	s_barrier
	s_add_i32 s4, 0, 0x1c000
	v_add_u32_e32 v178, s4, v217
	s_add_i32 s5, s8, s43
	ds_read_b128 v[154:157], v178
	ds_read_b128 v[158:161], v178 offset:1024
	ds_read_b128 v[166:169], v178 offset:2048
	ds_read_b128 v[206:209], v178 offset:3072
	v_lshl_add_u64 v[178:179], v[210:211], 0, s[60:61]
	s_mov_b32 m0, s5
	s_nop 0
	global_load_lds_dwordx4 v[178:179], off
	v_lshl_add_u64 v[178:179], v[212:213], 0, s[60:61]
	s_add_i32 m0, s5, 0x2000
	s_nop 0
	global_load_lds_dwordx4 v[178:179], off
	s_waitcnt lgkmcnt(0)
	v_mfma_f32_16x16x32_bf16 v[178:181], v[154:157], v[126:129], v[182:185]
	v_mfma_f32_16x16x32_bf16 v[122:125], v[166:169], v[126:129], v[122:125]
	s_barrier
	s_waitcnt lgkmcnt(0)
	s_setprio 1
	s_waitcnt lgkmcnt(0)
	v_mfma_f32_16x16x32_bf16 v[102:105], v[154:157], v[134:137], v[102:105]
	v_mfma_f32_16x16x32_bf16 v[98:101], v[166:169], v[134:137], v[98:101]
	v_mfma_f32_16x16x32_bf16 v[86:89], v[154:157], v[142:145], v[86:89]
	v_mfma_f32_16x16x32_bf16 v[82:85], v[166:169], v[142:145], v[82:85]
	v_mfma_f32_16x16x32_bf16 v[70:73], v[154:157], v[150:153], v[70:73]
	v_mfma_f32_16x16x32_bf16 v[66:69], v[166:169], v[150:153], v[66:69]
	v_mfma_f32_16x16x32_bf16 v[182:185], v[158:161], v[130:133], v[178:181]
	v_mfma_f32_16x16x32_bf16 v[178:181], v[206:209], v[130:133], v[122:125]
	v_mfma_f32_16x16x32_bf16 v[102:105], v[158:161], v[138:141], v[102:105]
	v_mfma_f32_16x16x32_bf16 v[98:101], v[206:209], v[138:141], v[98:101]
	v_mfma_f32_16x16x32_bf16 v[86:89], v[158:161], v[146:149], v[86:89]
	v_mfma_f32_16x16x32_bf16 v[82:85], v[206:209], v[146:149], v[82:85]
	v_mfma_f32_16x16x32_bf16 v[70:73], v[158:161], v[170:173], v[70:73]
	v_mfma_f32_16x16x32_bf16 v[66:69], v[206:209], v[170:173], v[66:69]
	s_setprio 0
	s_mov_b32 m0, s51
	v_lshl_add_u64 v[170:171], v[214:215], 0, s[60:61]
	s_barrier
; #define PG8_STAGE(bufoff, gbase, voff) do { _Pragma("unroll") for (int _i = 0; _i < 2; ++_i) \
;         __builtin_amdgcn_global_load_lds((const unsigned*)((const char*)(gbase) + (voff)[_i]), (LAS unsigned*)(lds + (bufoff) + ldsw + _i * 8192), 16, 0, 0); } while (0)
; #define PG8_LDA(dst, b, h) do { _Pragma("unroll") for (int m = 0; m < 4; ++m) _Pragma("unroll") for (int k = 0; k < 2; ++k) dst[m][k] = *(const LAS bf16x8*)(lds + PG8_SA(b, h) + aoff + m * 2048 + k * 1024); } while (0)
; #define PG8_LDB(dst, b, h) do { _Pragma("unroll") for (int n = 0; n < 2; ++n) _Pragma("unroll") for (int k = 0; k < 2; ++k) dst[n][k] = *(const LAS bf16x8*)(lds + PG8_SB(b, h) + boff + n * 2048 + k * 1024); } while (0)
; #define PG8_MMA(ai, bj, At, Bt) do { __builtin_amdgcn_s_setprio(1); _Pragma("unroll") for (int m = 0; m < 4; ++m) _Pragma("unroll") for (int n = 0; n < 2; ++n) _Pragma("unroll") for (int k = 0; k < 2; ++k) \
;         acc[ai][bj][m][n] = __builtin_amdgcn_mfma_f32_16x16x32_bf16(Bt[n][k], At[m][k], acc[ai][bj][m][n], 0, 0, 0); __builtin_amdgcn_s_setprio(0); } while (0)
; template <class Epi>
; __device__ __forceinline__ void gemm_phase(LAS unsigned char* lds, const Gemm g, const Sched& S, const Epi& E) {
;     ...
;             PG8_LDB(B0, 1, 0); PG8_SCHED; PG8_LDA(At, 1, 0); PG8_STAGE(PG8_SA(0, 1), a2 + hstepA, voffA);
;             PG8_WAIT_L(8); PG8_BAR; PG8_WAIT_L(0); PG8_MMA(0, 0, At, B0); PG8_BAR; PG8_SCHED;
;             PG8_LDB(B1, 1, 1); PG8_STAGE(PG8_SB(1, 0), b3, voffB);
;             PG8_BAR; PG8_WAIT_L(0); PG8_MMA(0, 1, At, B1); PG8_BAR;
;             PG8_LDA(At, 1, 1); PG8_STAGE(PG8_SA(1, 0), a3, voffA);
;             PG8_BAR; PG8_WAIT_L(0); PG8_MMA(1, 0, At, B0); PG8_BAR; PG8_SCHED;
;             PG8_STAGE(PG8_SB(1, 1), b3 + hstepB, voffB);
;             PG8_WAIT_V(6); PG8_BAR; PG8_MMA(1, 1, At, B1); PG8_BAR;
;         }
;     __device__ __forceinline__ void operator()(const Acc& acc, const Unit& u, int wr, int wc, int fr, int fq, const Pre& pre) const {
;     ...
;             if (base) {
; #pragma unroll
;                 for (int m = 0; m < 4; ++m) { const size_t off = zo + (size_t)(row0 + ai * 128 + m * 16) * ldc + col0;
; #pragma unroll
;                     for (int bj = 0; bj < 2; ++bj)
; #pragma unroll
;                         for (int n = 0; n < 2; ++n) bv[m][bj][n] = *(const f32x4*)(base + off + bj * 128 + n * 4); }
	ds_read_b128 v[122:125], v235 offset:49152
	ds_read_b128 v[126:129], v235 offset:50176
	ds_read_b128 v[130:133], v235 offset:51200
	ds_read_b128 v[134:137], v235 offset:52224
	ds_read_b128 v[138:141], v235 offset:53248
	ds_read_b128 v[142:145], v235 offset:54272
	ds_read_b128 v[146:149], v235 offset:55296
	ds_read_b128 v[150:153], v235 offset:56320
	global_load_lds_dwordx4 v[170:171], off
	v_lshl_add_u64 v[170:171], v[222:223], 0, s[60:61]
	s_mov_b32 m0, s2
	s_nop 0
	global_load_lds_dwordx4 v[170:171], off
	s_waitcnt lgkmcnt(0)
	v_mfma_f32_16x16x32_bf16 v[62:65], v[106:109], v[122:125], v[62:65]
	v_mfma_f32_16x16x32_bf16 v[58:61], v[114:117], v[122:125], v[58:61]
	s_barrier
	s_waitcnt lgkmcnt(0)
	s_setprio 1
	s_waitcnt lgkmcnt(0)
	v_mfma_f32_16x16x32_bf16 v[46:49], v[106:109], v[130:133], v[46:49]
	v_mfma_f32_16x16x32_bf16 v[42:45], v[114:117], v[130:133], v[42:45]
	v_mfma_f32_16x16x32_bf16 v[30:33], v[106:109], v[138:141], v[30:33]
	v_mfma_f32_16x16x32_bf16 v[26:29], v[114:117], v[138:141], v[26:29]
	v_mfma_f32_16x16x32_bf16 v[14:17], v[106:109], v[146:149], v[14:17]
	v_mfma_f32_16x16x32_bf16 v[10:13], v[114:117], v[146:149], v[10:13]
	v_mfma_f32_16x16x32_bf16 v[62:65], v[110:113], v[126:129], v[62:65]
	v_mfma_f32_16x16x32_bf16 v[58:61], v[118:121], v[126:129], v[58:61]
	v_mfma_f32_16x16x32_bf16 v[46:49], v[110:113], v[134:137], v[46:49]
	v_mfma_f32_16x16x32_bf16 v[42:45], v[118:121], v[134:137], v[42:45]
	v_mfma_f32_16x16x32_bf16 v[30:33], v[110:113], v[142:145], v[30:33]
	v_mfma_f32_16x16x32_bf16 v[26:29], v[118:121], v[142:145], v[26:29]
	v_mfma_f32_16x16x32_bf16 v[14:17], v[110:113], v[150:153], v[14:17]
	v_mfma_f32_16x16x32_bf16 v[10:13], v[118:121], v[150:153], v[10:13]
	s_setprio 0
	s_barrier
	s_add_i32 s4, s4, s43
	v_lshl_add_u64 v[106:107], v[224:225], 0, s[60:61]
	s_mov_b32 m0, s4
	s_nop 0
	global_load_lds_dwordx4 v[106:107], off
	v_lshl_add_u64 v[106:107], v[226:227], 0, s[60:61]
	s_add_i32 m0, s4, 0x2000
	s_nop 0
	global_load_lds_dwordx4 v[106:107], off
	s_waitcnt vmcnt(6)
	s_waitcnt lgkmcnt(0)
	v_mfma_f32_16x16x32_bf16 v[54:57], v[154:157], v[122:125], v[54:57]
	v_mfma_f32_16x16x32_bf16 v[50:53], v[166:169], v[122:125], v[50:53]
	s_barrier
	s_setprio 1
	v_mfma_f32_16x16x32_bf16 v[38:41], v[154:157], v[130:133], v[38:41]
	v_mfma_f32_16x16x32_bf16 v[34:37], v[166:169], v[130:133], v[34:37]
	v_mfma_f32_16x16x32_bf16 v[22:25], v[154:157], v[138:141], v[22:25]
	v_mfma_f32_16x16x32_bf16 v[18:21], v[166:169], v[138:141], v[18:21]
	v_mfma_f32_16x16x32_bf16 v[6:9], v[154:157], v[146:149], v[6:9]
	v_mfma_f32_16x16x32_bf16 v[2:5], v[166:169], v[146:149], v[2:5]
	v_mfma_f32_16x16x32_bf16 v[54:57], v[158:161], v[126:129], v[54:57]
	v_mfma_f32_16x16x32_bf16 v[50:53], v[206:209], v[126:129], v[50:53]
	v_mfma_f32_16x16x32_bf16 v[38:41], v[158:161], v[134:137], v[38:41]
	v_mfma_f32_16x16x32_bf16 v[34:37], v[206:209], v[134:137], v[34:37]
	v_mfma_f32_16x16x32_bf16 v[22:25], v[158:161], v[142:145], v[22:25]
	v_mfma_f32_16x16x32_bf16 v[18:21], v[206:209], v[142:145], v[18:21]
	v_mfma_f32_16x16x32_bf16 v[6:9], v[158:161], v[150:153], v[6:9]
	v_mfma_f32_16x16x32_bf16 v[2:5], v[206:209], v[150:153], v[2:5]
	s_setprio 0
	s_add_u32 s0, s0, 0x100
	s_addc_u32 s1, s1, 0
	s_add_u32 s34, s34, 0x100
	s_addc_u32 s35, s35, 0
	s_cmp_ge_u32 s14, s73
	s_mov_b32 s4, s14
	s_barrier
	s_cbranch_scc0 .LBB0_719
	s_ashr_i32 s0, s42, 31
	s_ashr_i32 s4, s24, 31
	v_readlane_b32 s8, v253, 59
	s_mul_hi_u32 s1, s74, s42
	s_mul_i32 s0, s74, s0
	v_readlane_b32 s9, v253, 60
	s_mul_hi_u32 s5, s8, s24
	s_mul_i32 s4, s8, s4
	s_add_i32 s0, s1, s0
	s_mul_i32 s1, s75, s42
	s_add_i32 s4, s5, s4
	s_mul_i32 s5, s9, s24
	v_lshl_add_u32 v206, s97, 8, v216
	s_add_i32 s0, s0, s1
	s_mul_i32 s1, s74, s42
	s_add_i32 s4, s4, s5
	s_mul_i32 s5, s8, s24
	v_lshl_or_b32 v210, s96, 8, v234
	s_add_u32 s94, s1, s5
	v_ashrrev_i32_e32 v207, 31, v206
	s_addc_u32 s95, s0, s4
	v_ashrrev_i32_e32 v211, 31, v210
	s_mov_b64 s[0:1], -1
	s_and_b64 vcc, exec, s[78:79]
	v_mul_lo_u32 v208, s13, v206
	v_mul_lo_u32 v236, s12, v207
	v_or_b32_e32 v239, 16, v206
	v_or_b32_e32 v238, 32, v206
	v_or_b32_e32 v237, 48, v206
	s_cbranch_vccz .LBB0_722
	s_lshl_b64 s[0:1], s[94:95], 2
	v_readlane_b32 s4, v254, 7
	v_readlane_b32 s5, v254, 8
	s_add_u32 s0, s4, s0
	s_addc_u32 s1, s5, s1
	v_lshl_add_u64 v[154:155], v[210:211], 2, s[0:1]
	v_mad_u64_u32 v[212:213], s[0:1], s12, v206, 0
	v_mul_lo_u32 v124, s13, v239
	v_mad_u64_u32 v[122:123], s[0:1], s12, v239, 0
	v_mul_lo_u32 v140, s13, v238
	v_mad_u64_u32 v[138:139], s[0:1], s12, v238, 0
	v_mul_lo_u32 v158, s13, v237
	v_mad_u64_u32 v[156:157], s[0:1], s12, v237, 0
	v_add3_u32 v213, v213, v236, v208
	v_add3_u32 v123, v123, v236, v124
	v_add3_u32 v139, v139, v236, v140
	v_add3_u32 v157, v157, v236, v158
	v_lshl_add_u64 v[118:119], v[212:213], 2, v[154:155]
	v_lshl_add_u64 v[134:135], v[122:123], 2, v[154:155]
	v_lshl_add_u64 v[150:151], v[138:139], 2, v[154:155]
	v_lshl_add_u64 v[170:171], v[156:157], 2, v[154:155]
	flat_load_dwordx4 v[106:109], v[118:119]
	flat_load_dwordx4 v[110:113], v[118:119] offset:16
	flat_load_dwordx4 v[114:117], v[118:119] offset:512
	s_nop 0
	flat_load_dwordx4 v[118:121], v[118:119] offset:528
	s_nop 0
	flat_load_dwordx4 v[122:125], v[134:135]
	flat_load_dwordx4 v[126:129], v[134:135] offset:16
	flat_load_dwordx4 v[130:133], v[134:135] offset:512
	s_nop 0
	flat_load_dwordx4 v[134:137], v[134:135] offset:528
	s_nop 0
	flat_load_dwordx4 v[138:141], v[150:151]
	flat_load_dwordx4 v[142:145], v[150:151] offset:16
	flat_load_dwordx4 v[146:149], v[150:151] offset:512
	s_nop 0
	flat_load_dwordx4 v[150:153], v[150:151] offset:528
	s_nop 0
	flat_load_dwordx4 v[154:157], v[170:171]
	flat_load_dwordx4 v[158:161], v[170:171] offset:16
	flat_load_dwordx4 v[166:169], v[170:171] offset:512
	s_nop 0
	flat_load_dwordx4 v[170:173], v[170:171] offset:528
	s_mov_b64 s[0:1], 0

; #define PG8_STAGE(bufoff, gbase, voff) do { _Pragma("unroll") for (int _i = 0; _i < 2; ++_i) \
;         __builtin_amdgcn_global_load_lds((const unsigned*)((const char*)(gbase) + (voff)[_i]), (LAS unsigned*)(lds + (bufoff) + ldsw + _i * 8192), 16, 0, 0); } while (0)
; #define PG8_LDA(dst, b, h) do { _Pragma("unroll") for (int m = 0; m < 4; ++m) _Pragma("unroll") for (int k = 0; k < 2; ++k) dst[m][k] = *(const LAS bf16x8*)(lds + PG8_SA(b, h) + aoff + m * 2048 + k * 1024); } while (0)
; #define PG8_LDB(dst, b, h) do { _Pragma("unroll") for (int n = 0; n < 2; ++n) _Pragma("unroll") for (int k = 0; k < 2; ++k) dst[n][k] = *(const LAS bf16x8*)(lds + PG8_SB(b, h) + boff + n * 2048 + k * 1024); } while (0)
; #define PG8_MMA(ai, bj, At, Bt) do { __builtin_amdgcn_s_setprio(1); _Pragma("unroll") for (int m = 0; m < 4; ++m) _Pragma("unroll") for (int n = 0; n < 2; ++n) _Pragma("unroll") for (int k = 0; k < 2; ++k) \
;         acc[ai][bj][m][n] = __builtin_amdgcn_mfma_f32_16x16x32_bf16(Bt[n][k], At[m][k], acc[ai][bj][m][n], 0, 0, 0); __builtin_amdgcn_s_setprio(0); } while (0)
; #define PG8_WAIT_V(n) asm volatile("s_waitcnt vmcnt(" #n ")" ::: "memory")
; #define PG8_WAIT_L(n) asm volatile("s_waitcnt lgkmcnt(" #n ")" ::: "memory")
; template <class Epi>
; __device__ __forceinline__ void gemm_phase(LAS unsigned char* lds, const Gemm g, const Sched& S, const Epi& E) {
;     ...
;         for (int t = 0; t < nt; t += 2) {
;             const bool last = (t == nt - 2);
;             const char* a1 = cA + (size_t)(t + 1) * kstep;
;             const char* a2 = last ? nA : cA + (size_t)(t + 2) * kstep; const char* b2 = last ? nB : cB + (size_t)(t + 2) * kstep;
;             const char* a3 = a2 + kstep; const char* b3 = b2 + kstep;
;             PG8_LDB(B0, 0, 0); PG8_SCHED; PG8_LDA(At, 0, 0); PG8_STAGE(PG8_SA(1, 1), a1 + hstepA, voffA);
;             PG8_WAIT_L(8); PG8_BAR; PG8_WAIT_L(0); PG8_MMA(0, 0, At, B0); PG8_BAR; PG8_SCHED;
;             PG8_LDB(B1, 0, 1); PG8_STAGE(PG8_SB(0, 0), b2, voffB);
;             PG8_BAR; PG8_WAIT_L(0); PG8_MMA(0, 1, At, B1); PG8_BAR;
;             PG8_LDA(At, 0, 1); PG8_STAGE(PG8_SA(0, 0), a2, voffA);
;             PG8_BAR; PG8_WAIT_L(0); PG8_MMA(1, 0, At, B0); PG8_BAR; PG8_SCHED;
;             PG8_STAGE(PG8_SB(0, 1), b2 + hstepB, voffB);
;             PG8_WAIT_V(6); PG8_BAR; PG8_MMA(1, 1, At, B1); PG8_BAR;
.LBB0_825:
	s_add_i32 s86, s68, 2
	s_add_u32 s70, s4, 0x80
	s_addc_u32 s69, s5, 0
	s_add_i32 s87, 0, 0x10000
	v_add_u32_e32 v144, s87, v145
	ds_read_b128 v[152:155], v144
	ds_read_b128 v[156:159], v144 offset:1024
	ds_read_b128 v[160:163], v144 offset:2048
	ds_read_b128 v[164:167], v144 offset:3072
	s_cmp_eq_u32 s77, s68
	s_cselect_b32 s68, s59, s70
	s_cselect_b32 s69, s57, s69
	s_cselect_b32 s71, s82, s85
	s_cselect_b32 s70, s83, s84
	v_lshl_add_u64 v[192:193], s[4:5], 0, v[136:137]
	s_add_i32 m0, s33, 0xc000
	ds_read_b128 v[168:171], v151
	ds_read_b128 v[172:175], v151 offset:1024
	ds_read_b128 v[176:179], v151 offset:2048
	ds_read_b128 v[180:183], v151 offset:3072
	ds_read_b128 v[184:187], v151 offset:4096
	ds_read_b128 v[188:191], v151 offset:5120
	ds_read_b128 v[196:199], v151 offset:6144
	ds_read_b128 v[200:203], v151 offset:7168
	global_load_lds_dwordx4 v[192:193], off
	v_lshl_add_u64 v[192:193], s[4:5], 0, v[138:139]
	s_add_i32 m0, s33, 0xe000
	s_nop 0
	global_load_lds_dwordx4 v[192:193], off
	s_add_i32 s88, 0, 0x14000
	v_add_u32_e32 v144, s88, v145
	ds_read_b128 v[204:207], v144
	ds_read_b128 v[208:211], v144 offset:1024
	ds_read_b128 v[212:215], v144 offset:2048
	ds_read_b128 v[234:237], v144 offset:3072
	s_waitcnt vmcnt(8)
	s_waitcnt lgkmcnt(0)
	v_mfma_f32_16x16x32_bf16 v[126:129], v[152:155], v[168:171], v[126:129]
	v_mfma_f32_16x16x32_bf16 v[122:125], v[160:163], v[168:171], v[122:125]
	s_barrier
	s_setprio 1
	v_mfma_f32_16x16x32_bf16 v[110:113], v[152:155], v[176:179], v[110:113]
	v_mfma_f32_16x16x32_bf16 v[106:109], v[160:163], v[176:179], v[106:109]
	v_mfma_f32_16x16x32_bf16 v[94:97], v[152:155], v[184:187], v[94:97]
	v_mfma_f32_16x16x32_bf16 v[90:93], v[160:163], v[184:187], v[90:93]
	v_mfma_f32_16x16x32_bf16 v[78:81], v[152:155], v[196:199], v[78:81]
	v_mfma_f32_16x16x32_bf16 v[74:77], v[160:163], v[196:199], v[74:77]
	v_mfma_f32_16x16x32_bf16 v[126:129], v[156:159], v[172:175], v[126:129]
	v_mfma_f32_16x16x32_bf16 v[122:125], v[164:167], v[172:175], v[122:125]
	v_mfma_f32_16x16x32_bf16 v[110:113], v[156:159], v[180:183], v[110:113]
	v_mfma_f32_16x16x32_bf16 v[106:109], v[164:167], v[180:183], v[106:109]
	v_mfma_f32_16x16x32_bf16 v[94:97], v[156:159], v[188:191], v[94:97]
	v_mfma_f32_16x16x32_bf16 v[90:93], v[164:167], v[188:191], v[90:93]
	v_mfma_f32_16x16x32_bf16 v[78:81], v[156:159], v[200:203], v[78:81]
	v_mfma_f32_16x16x32_bf16 v[74:77], v[164:167], v[200:203], v[74:77]
	v_mfma_f32_16x16x32_bf16 v[118:121], v[204:207], v[168:171], v[118:121]
	v_mfma_f32_16x16x32_bf16 v[114:117], v[212:215], v[168:171], v[114:117]
	v_mfma_f32_16x16x32_bf16 v[102:105], v[204:207], v[176:179], v[102:105]
	v_mfma_f32_16x16x32_bf16 v[98:101], v[212:215], v[176:179], v[98:101]
	v_mfma_f32_16x16x32_bf16 v[86:89], v[204:207], v[184:187], v[86:89]
	v_mfma_f32_16x16x32_bf16 v[82:85], v[212:215], v[184:187], v[82:85]
	v_mfma_f32_16x16x32_bf16 v[70:73], v[204:207], v[196:199], v[70:73]
	v_mfma_f32_16x16x32_bf16 v[66:69], v[212:215], v[196:199], v[66:69]
	v_mfma_f32_16x16x32_bf16 v[118:121], v[208:211], v[172:175], v[118:121]
	v_mfma_f32_16x16x32_bf16 v[114:117], v[234:237], v[172:175], v[114:117]
	v_mfma_f32_16x16x32_bf16 v[102:105], v[208:211], v[180:183], v[102:105]
	v_mfma_f32_16x16x32_bf16 v[98:101], v[234:237], v[180:183], v[98:101]
	v_mfma_f32_16x16x32_bf16 v[86:89], v[208:211], v[188:191], v[86:89]
	v_mfma_f32_16x16x32_bf16 v[82:85], v[234:237], v[188:191], v[82:85]
	v_mfma_f32_16x16x32_bf16 v[70:73], v[208:211], v[200:203], v[70:73]
	v_mfma_f32_16x16x32_bf16 v[66:69], v[234:237], v[200:203], v[66:69]
	s_setprio 0
	s_barrier
	s_add_i32 s87, s87, s51
	v_lshl_add_u64 v[192:193], s[70:71], 0, v[0:1]
	s_mov_b32 m0, s87
	s_nop 0
	global_load_lds_dwordx4 v[192:193], off
	v_lshl_add_u64 v[216:217], s[70:71], 0, v[134:135]
	s_add_i32 m0, s87, 0x2000
	s_nop 0
	global_load_lds_dwordx4 v[216:217], off
	s_mov_b32 m0, s33
	v_lshl_add_u64 v[222:223], s[68:69], 0, v[130:131]
	ds_read_b128 v[168:171], v151 offset:16384
	ds_read_b128 v[172:175], v151 offset:17408
	ds_read_b128 v[176:179], v151 offset:18432
	ds_read_b128 v[180:183], v151 offset:19456
	ds_read_b128 v[184:187], v151 offset:20480
	ds_read_b128 v[188:191], v151 offset:21504
	ds_read_b128 v[196:199], v151 offset:22528
	ds_read_b128 v[200:203], v151 offset:23552
	global_load_lds_dwordx4 v[222:223], off
	v_lshl_add_u64 v[224:225], s[68:69], 0, v[132:133]
	s_mov_b32 m0, s48
	s_nop 0
	global_load_lds_dwordx4 v[224:225], off
	s_add_u32 s70, s70, s14
	s_addc_u32 s71, s71, s15
	s_add_i32 s87, s88, s51
	v_lshl_add_u64 v[226:227], s[70:71], 0, v[0:1]
	s_mov_b32 m0, s87
	v_lshl_add_u64 v[228:229], s[70:71], 0, v[134:135]
	global_load_lds_dwordx4 v[226:227], off
	s_add_i32 m0, s87, 0x2000
	s_nop 0
	global_load_lds_dwordx4 v[228:229], off
	s_waitcnt vmcnt(8)
	s_waitcnt lgkmcnt(0)
	v_mfma_f32_16x16x32_bf16 v[62:65], v[152:155], v[168:171], v[62:65]
	v_mfma_f32_16x16x32_bf16 v[58:61], v[160:163], v[168:171], v[58:61]
	s_barrier
; #define PG8_STAGE(bufoff, gbase, voff) do { _Pragma("unroll") for (int _i = 0; _i < 2; ++_i) \
;         __builtin_amdgcn_global_load_lds((const unsigned*)((const char*)(gbase) + (voff)[_i]), (LAS unsigned*)(lds + (bufoff) + ldsw + _i * 8192), 16, 0, 0); } while (0)
; #define PG8_LDA(dst, b, h) do { _Pragma("unroll") for (int m = 0; m < 4; ++m) _Pragma("unroll") for (int k = 0; k < 2; ++k) dst[m][k] = *(const LAS bf16x8*)(lds + PG8_SA(b, h) + aoff + m * 2048 + k * 1024); } while (0)
; #define PG8_LDB(dst, b, h) do { _Pragma("unroll") for (int n = 0; n < 2; ++n) _Pragma("unroll") for (int k = 0; k < 2; ++k) dst[n][k] = *(const LAS bf16x8*)(lds + PG8_SB(b, h) + boff + n * 2048 + k * 1024); } while (0)
; #define PG8_MMA(ai, bj, At, Bt) do { __builtin_amdgcn_s_setprio(1); _Pragma("unroll") for (int m = 0; m < 4; ++m) _Pragma("unroll") for (int n = 0; n < 2; ++n) _Pragma("unroll") for (int k = 0; k < 2; ++k) \
;         acc[ai][bj][m][n] = __builtin_amdgcn_mfma_f32_16x16x32_bf16(Bt[n][k], At[m][k], acc[ai][bj][m][n], 0, 0, 0); __builtin_amdgcn_s_setprio(0); } while (0)
; #define PG8_WAIT_V(n) asm volatile("s_waitcnt vmcnt(" #n ")" ::: "memory")
; #define PG8_BAR __builtin_amdgcn_s_barrier()
; template <class Epi>
; __device__ __forceinline__ void gemm_phase(LAS unsigned char* lds, const Gemm g, const Sched& S, const Epi& E) {
;     ...
;             PG8_LDB(B1, 0, 1); PG8_STAGE(PG8_SB(0, 0), b2, voffB);
;             PG8_BAR; PG8_WAIT_L(0); PG8_MMA(0, 1, At, B1); PG8_BAR;
;             PG8_LDA(At, 0, 1); PG8_STAGE(PG8_SA(0, 0), a2, voffA);
;             PG8_BAR; PG8_WAIT_L(0); PG8_MMA(1, 0, At, B0); PG8_BAR; PG8_SCHED;
;             PG8_STAGE(PG8_SB(0, 1), b2 + hstepB, voffB);
;             PG8_WAIT_V(6); PG8_BAR; PG8_MMA(1, 1, At, B1); PG8_BAR;
;             PG8_LDB(B0, 1, 0); PG8_SCHED; PG8_LDA(At, 1, 0); PG8_STAGE(PG8_SA(0, 1), a2 + hstepA, voffA);
;             PG8_WAIT_L(8); PG8_BAR; PG8_WAIT_L(0); PG8_MMA(0, 0, At, B0); PG8_BAR; PG8_SCHED;
;             PG8_LDB(B1, 1, 1); PG8_STAGE(PG8_SB(1, 0), b3, voffB);
;             PG8_BAR; PG8_WAIT_L(0); PG8_MMA(0, 1, At, B1); PG8_BAR;
;             PG8_LDA(At, 1, 1); PG8_STAGE(PG8_SA(1, 0), a3, voffA);
;             PG8_BAR; PG8_WAIT_L(0); PG8_MMA(1, 0, At, B0); PG8_BAR; PG8_SCHED;
;             PG8_STAGE(PG8_SB(1, 1), b3 + hstepB, voffB);
;             PG8_WAIT_V(6); PG8_BAR; PG8_MMA(1, 1, At, B1); PG8_BAR;
	s_setprio 1
	v_mfma_f32_16x16x32_bf16 v[46:49], v[152:155], v[176:179], v[46:49]
	v_mfma_f32_16x16x32_bf16 v[42:45], v[160:163], v[176:179], v[42:45]
	v_mfma_f32_16x16x32_bf16 v[30:33], v[152:155], v[184:187], v[30:33]
	v_mfma_f32_16x16x32_bf16 v[26:29], v[160:163], v[184:187], v[26:29]
	v_mfma_f32_16x16x32_bf16 v[14:17], v[152:155], v[196:199], v[14:17]
	v_mfma_f32_16x16x32_bf16 v[10:13], v[160:163], v[196:199], v[10:13]
	v_mfma_f32_16x16x32_bf16 v[62:65], v[156:159], v[172:175], v[62:65]
	v_mfma_f32_16x16x32_bf16 v[58:61], v[164:167], v[172:175], v[58:61]
	v_mfma_f32_16x16x32_bf16 v[46:49], v[156:159], v[180:183], v[46:49]
	v_mfma_f32_16x16x32_bf16 v[42:45], v[164:167], v[180:183], v[42:45]
	v_mfma_f32_16x16x32_bf16 v[30:33], v[156:159], v[188:191], v[30:33]
	v_mfma_f32_16x16x32_bf16 v[26:29], v[164:167], v[188:191], v[26:29]
	v_mfma_f32_16x16x32_bf16 v[14:17], v[156:159], v[200:203], v[14:17]
	v_mfma_f32_16x16x32_bf16 v[10:13], v[164:167], v[200:203], v[10:13]
	v_mfma_f32_16x16x32_bf16 v[54:57], v[204:207], v[168:171], v[54:57]
	v_mfma_f32_16x16x32_bf16 v[50:53], v[212:215], v[168:171], v[50:53]
	v_mfma_f32_16x16x32_bf16 v[38:41], v[204:207], v[176:179], v[38:41]
	v_mfma_f32_16x16x32_bf16 v[34:37], v[212:215], v[176:179], v[34:37]
	v_mfma_f32_16x16x32_bf16 v[22:25], v[204:207], v[184:187], v[22:25]
	v_mfma_f32_16x16x32_bf16 v[18:21], v[212:215], v[184:187], v[18:21]
	v_mfma_f32_16x16x32_bf16 v[6:9], v[204:207], v[196:199], v[6:9]
	v_mfma_f32_16x16x32_bf16 v[2:5], v[212:215], v[196:199], v[2:5]
	v_mfma_f32_16x16x32_bf16 v[54:57], v[208:211], v[172:175], v[54:57]
	v_mfma_f32_16x16x32_bf16 v[50:53], v[234:237], v[172:175], v[50:53]
	v_mfma_f32_16x16x32_bf16 v[38:41], v[208:211], v[180:183], v[38:41]
	v_mfma_f32_16x16x32_bf16 v[34:37], v[234:237], v[180:183], v[34:37]
	v_mfma_f32_16x16x32_bf16 v[22:25], v[208:211], v[188:191], v[22:25]
	v_mfma_f32_16x16x32_bf16 v[18:21], v[234:237], v[188:191], v[18:21]
	v_mfma_f32_16x16x32_bf16 v[6:9], v[208:211], v[200:203], v[6:9]
	v_mfma_f32_16x16x32_bf16 v[2:5], v[234:237], v[200:203], v[2:5]
	s_setprio 0
	s_barrier
	s_add_i32 s70, 0, 0x18000
	v_add_u32_e32 v144, s70, v145
	ds_read_b128 v[152:155], v144
	ds_read_b128 v[156:159], v144 offset:1024
	ds_read_b128 v[160:163], v144 offset:2048
	ds_read_b128 v[164:167], v144 offset:3072
	s_add_u32 s68, s68, s6
	s_addc_u32 s69, s69, s7
	s_mov_b32 m0, s58
	v_lshl_add_u64 v[204:205], s[68:69], 0, v[130:131]
	ds_read_b128 v[168:171], v151 offset:32768
	ds_read_b128 v[172:175], v151 offset:33792
	ds_read_b128 v[176:179], v151 offset:34816
	ds_read_b128 v[180:183], v151 offset:35840
	ds_read_b128 v[184:187], v151 offset:36864
	ds_read_b128 v[188:191], v151 offset:37888
	ds_read_b128 v[196:199], v151 offset:38912
	ds_read_b128 v[200:203], v151 offset:39936
	global_load_lds_dwordx4 v[204:205], off
	v_lshl_add_u64 v[204:205], s[68:69], 0, v[132:133]
	s_mov_b32 m0, s72
	s_nop 0
	global_load_lds_dwordx4 v[204:205], off
	s_add_i32 s68, 0, 0x1c000
	v_add_u32_e32 v144, s68, v145
	ds_read_b128 v[204:207], v144
	ds_read_b128 v[208:211], v144 offset:1024
	ds_read_b128 v[212:215], v144 offset:2048
	ds_read_b128 v[234:237], v144 offset:3072
	s_waitcnt vmcnt(8)
	s_waitcnt lgkmcnt(0)
	v_mfma_f32_16x16x32_bf16 v[126:129], v[152:155], v[168:171], v[126:129]
	v_mfma_f32_16x16x32_bf16 v[122:125], v[160:163], v[168:171], v[122:125]
	s_barrier
	s_setprio 1
	v_mfma_f32_16x16x32_bf16 v[110:113], v[152:155], v[176:179], v[110:113]
	v_mfma_f32_16x16x32_bf16 v[106:109], v[160:163], v[176:179], v[106:109]
	v_mfma_f32_16x16x32_bf16 v[94:97], v[152:155], v[184:187], v[94:97]
	v_mfma_f32_16x16x32_bf16 v[90:93], v[160:163], v[184:187], v[90:93]
	v_mfma_f32_16x16x32_bf16 v[78:81], v[152:155], v[196:199], v[78:81]
	v_mfma_f32_16x16x32_bf16 v[74:77], v[160:163], v[196:199], v[74:77]
	v_mfma_f32_16x16x32_bf16 v[126:129], v[156:159], v[172:175], v[126:129]
	v_mfma_f32_16x16x32_bf16 v[122:125], v[164:167], v[172:175], v[122:125]
	v_mfma_f32_16x16x32_bf16 v[110:113], v[156:159], v[180:183], v[110:113]
	v_mfma_f32_16x16x32_bf16 v[106:109], v[164:167], v[180:183], v[106:109]
	v_mfma_f32_16x16x32_bf16 v[94:97], v[156:159], v[188:191], v[94:97]
	v_mfma_f32_16x16x32_bf16 v[90:93], v[164:167], v[188:191], v[90:93]
	v_mfma_f32_16x16x32_bf16 v[78:81], v[156:159], v[200:203], v[78:81]
	v_mfma_f32_16x16x32_bf16 v[74:77], v[164:167], v[200:203], v[74:77]
	v_mfma_f32_16x16x32_bf16 v[118:121], v[204:207], v[168:171], v[118:121]
	v_mfma_f32_16x16x32_bf16 v[114:117], v[212:215], v[168:171], v[114:117]
	v_mfma_f32_16x16x32_bf16 v[102:105], v[204:207], v[176:179], v[102:105]
	v_mfma_f32_16x16x32_bf16 v[98:101], v[212:215], v[176:179], v[98:101]
	v_mfma_f32_16x16x32_bf16 v[86:89], v[204:207], v[184:187], v[86:89]
	v_mfma_f32_16x16x32_bf16 v[82:85], v[212:215], v[184:187], v[82:85]
	v_mfma_f32_16x16x32_bf16 v[70:73], v[204:207], v[196:199], v[70:73]
	v_mfma_f32_16x16x32_bf16 v[66:69], v[212:215], v[196:199], v[66:69]
	v_mfma_f32_16x16x32_bf16 v[118:121], v[208:211], v[172:175], v[118:121]
	v_mfma_f32_16x16x32_bf16 v[114:117], v[234:237], v[172:175], v[114:117]
	v_mfma_f32_16x16x32_bf16 v[102:105], v[208:211], v[180:183], v[102:105]
	v_mfma_f32_16x16x32_bf16 v[98:101], v[234:237], v[180:183], v[98:101]
	v_mfma_f32_16x16x32_bf16 v[86:89], v[208:211], v[188:191], v[86:89]
	v_mfma_f32_16x16x32_bf16 v[82:85], v[234:237], v[188:191], v[82:85]
	v_mfma_f32_16x16x32_bf16 v[70:73], v[208:211], v[200:203], v[70:73]
	v_mfma_f32_16x16x32_bf16 v[66:69], v[234:237], v[200:203], v[66:69]
	s_setprio 0
	s_barrier
; __device__ __forceinline__ float pre_get(const Pre& p, int ai, int m, int fr) { return __shfl(p.v[ai], m * 16 + fr); }
; __device__ __forceinline__ float rstd_pre(const float* ss, float v) { return ss ? rsqrtf(v * (1.0f / 2048.0f) + 1e-6f) : 1.0f; }
; #define PG8_STAGE(bufoff, gbase, voff) do { _Pragma("unroll") for (int _i = 0; _i < 2; ++_i) \
;         __builtin_amdgcn_global_load_lds((const unsigned*)((const char*)(gbase) + (voff)[_i]), (LAS unsigned*)(lds + (bufoff) + ldsw + _i * 8192), 16, 0, 0); } while (0)
; #define PG8_LDA(dst, b, h) do { _Pragma("unroll") for (int m = 0; m < 4; ++m) _Pragma("unroll") for (int k = 0; k < 2; ++k) dst[m][k] = *(const LAS bf16x8*)(lds + PG8_SA(b, h) + aoff + m * 2048 + k * 1024); } while (0)
; #define PG8_LDB(dst, b, h) do { _Pragma("unroll") for (int n = 0; n < 2; ++n) _Pragma("unroll") for (int k = 0; k < 2; ++k) dst[n][k] = *(const LAS bf16x8*)(lds + PG8_SB(b, h) + boff + n * 2048 + k * 1024); } while (0)
; #define PG8_WAIT_V(n) asm volatile("s_waitcnt vmcnt(" #n ")" ::: "memory")
; #define PG8_WAIT_L(n) asm volatile("s_waitcnt lgkmcnt(" #n ")" ::: "memory")
; #define PG8_BAR __builtin_amdgcn_s_barrier()
; template <class Epi>
; __device__ __forceinline__ void gemm_phase(LAS unsigned char* lds, const Gemm g, const Sched& S, const Epi& E) {
;     ...
;             PG8_LDB(B0, 1, 0); PG8_SCHED; PG8_LDA(At, 1, 0); PG8_STAGE(PG8_SA(0, 1), a2 + hstepA, voffA);
;             PG8_WAIT_L(8); PG8_BAR; PG8_WAIT_L(0); PG8_MMA(0, 0, At, B0); PG8_BAR; PG8_SCHED;
;             PG8_LDB(B1, 1, 1); PG8_STAGE(PG8_SB(1, 0), b3, voffB);
;             PG8_BAR; PG8_WAIT_L(0); PG8_MMA(0, 1, At, B1); PG8_BAR;
;             PG8_LDA(At, 1, 1); PG8_STAGE(PG8_SA(1, 0), a3, voffA);
;             PG8_BAR; PG8_WAIT_L(0); PG8_MMA(1, 0, At, B0); PG8_BAR; PG8_SCHED;
;             PG8_STAGE(PG8_SB(1, 1), b3 + hstepB, voffB);
;             PG8_WAIT_V(6); PG8_BAR; PG8_MMA(1, 1, At, B1); PG8_BAR;
;         }
;     __device__ __forceinline__ void operator()(const Acc& acc, const Unit& u, int wr, int wc, int fr, int fq, const Pre& pre) const {
;         const int row0 = u.pm * 256 + wr * 64 + fr, col0 = u.pn * 128 + wc * 32 + 8 * fq;
;         float rsq[2][4];
; #pragma unroll
;         for (int ai = 0; ai < 2; ++ai)
; #pragma unroll
;             for (int m = 0; m < 4; ++m) rsq[ai][m] = rstd_pre(ss, pre_get(pre, ai, m, fr));
	s_add_i32 s69, s70, s51
	v_lshl_add_u64 v[192:193], v[192:193], 0, s[60:61]
	s_mov_b32 m0, s69
	s_nop 0
	global_load_lds_dwordx4 v[192:193], off
	v_lshl_add_u64 v[192:193], v[216:217], 0, s[60:61]
	s_add_i32 m0, s69, 0x2000
	s_nop 0
	global_load_lds_dwordx4 v[192:193], off
	s_mov_b32 m0, s75
	v_lshl_add_u64 v[192:193], v[222:223], 0, s[60:61]
	ds_read_b128 v[168:171], v151 offset:49152
	ds_read_b128 v[172:175], v151 offset:50176
	ds_read_b128 v[176:179], v151 offset:51200
	ds_read_b128 v[180:183], v151 offset:52224
	ds_read_b128 v[184:187], v151 offset:53248
	ds_read_b128 v[188:191], v151 offset:54272
	ds_read_b128 v[196:199], v151 offset:55296
	ds_read_b128 v[200:203], v151 offset:56320
	global_load_lds_dwordx4 v[192:193], off
	v_lshl_add_u64 v[192:193], v[224:225], 0, s[60:61]
	s_mov_b32 m0, s76
	s_nop 0
	global_load_lds_dwordx4 v[192:193], off
	s_add_i32 s68, s68, s51
	v_lshl_add_u64 v[192:193], v[226:227], 0, s[60:61]
	s_mov_b32 m0, s68
	s_nop 0
	global_load_lds_dwordx4 v[192:193], off
	v_lshl_add_u64 v[192:193], v[228:229], 0, s[60:61]
	s_add_i32 m0, s68, 0x2000
	s_nop 0
	global_load_lds_dwordx4 v[192:193], off
	s_waitcnt vmcnt(8)
	s_waitcnt lgkmcnt(0)
	v_mfma_f32_16x16x32_bf16 v[62:65], v[152:155], v[168:171], v[62:65]
	v_mfma_f32_16x16x32_bf16 v[58:61], v[160:163], v[168:171], v[58:61]
	s_barrier
	s_setprio 1
	v_mfma_f32_16x16x32_bf16 v[46:49], v[152:155], v[176:179], v[46:49]
	v_mfma_f32_16x16x32_bf16 v[42:45], v[160:163], v[176:179], v[42:45]
	v_mfma_f32_16x16x32_bf16 v[30:33], v[152:155], v[184:187], v[30:33]
	v_mfma_f32_16x16x32_bf16 v[26:29], v[160:163], v[184:187], v[26:29]
	v_mfma_f32_16x16x32_bf16 v[14:17], v[152:155], v[196:199], v[14:17]
	v_mfma_f32_16x16x32_bf16 v[10:13], v[160:163], v[196:199], v[10:13]
	v_mfma_f32_16x16x32_bf16 v[62:65], v[156:159], v[172:175], v[62:65]
	v_mfma_f32_16x16x32_bf16 v[58:61], v[164:167], v[172:175], v[58:61]
	v_mfma_f32_16x16x32_bf16 v[46:49], v[156:159], v[180:183], v[46:49]
	v_mfma_f32_16x16x32_bf16 v[42:45], v[164:167], v[180:183], v[42:45]
	v_mfma_f32_16x16x32_bf16 v[30:33], v[156:159], v[188:191], v[30:33]
	v_mfma_f32_16x16x32_bf16 v[26:29], v[164:167], v[188:191], v[26:29]
	v_mfma_f32_16x16x32_bf16 v[14:17], v[156:159], v[200:203], v[14:17]
	v_mfma_f32_16x16x32_bf16 v[10:13], v[164:167], v[200:203], v[10:13]
	v_mfma_f32_16x16x32_bf16 v[54:57], v[204:207], v[168:171], v[54:57]
	v_mfma_f32_16x16x32_bf16 v[50:53], v[212:215], v[168:171], v[50:53]
	v_mfma_f32_16x16x32_bf16 v[38:41], v[204:207], v[176:179], v[38:41]
	v_mfma_f32_16x16x32_bf16 v[34:37], v[212:215], v[176:179], v[34:37]
	v_mfma_f32_16x16x32_bf16 v[22:25], v[204:207], v[184:187], v[22:25]
	v_mfma_f32_16x16x32_bf16 v[18:21], v[212:215], v[184:187], v[18:21]
	v_mfma_f32_16x16x32_bf16 v[6:9], v[204:207], v[196:199], v[6:9]
	v_mfma_f32_16x16x32_bf16 v[2:5], v[212:215], v[196:199], v[2:5]
	v_mfma_f32_16x16x32_bf16 v[54:57], v[208:211], v[172:175], v[54:57]
	v_mfma_f32_16x16x32_bf16 v[50:53], v[234:237], v[172:175], v[50:53]
	v_mfma_f32_16x16x32_bf16 v[38:41], v[208:211], v[180:183], v[38:41]
	v_mfma_f32_16x16x32_bf16 v[34:37], v[234:237], v[180:183], v[34:37]
	v_mfma_f32_16x16x32_bf16 v[22:25], v[208:211], v[188:191], v[22:25]
	v_mfma_f32_16x16x32_bf16 v[18:21], v[234:237], v[188:191], v[18:21]
	v_mfma_f32_16x16x32_bf16 v[6:9], v[208:211], v[200:203], v[6:9]
	v_mfma_f32_16x16x32_bf16 v[2:5], v[234:237], v[200:203], v[2:5]
	s_setprio 0
	s_add_u32 s4, s4, 0x100
	s_addc_u32 s5, s5, 0
	s_add_u32 s84, s84, 0x100
	s_addc_u32 s85, s85, 0
	s_cmp_ge_u32 s86, s73
	s_mov_b32 s68, s86
	s_barrier
	s_cbranch_scc0 .LBB0_825
	v_and_or_b32 v144, v220, 64, v141
	v_lshlrev_b32_e32 v160, 2, v144
	ds_bpermute_b32 v155, v160, v142
	ds_bpermute_b32 v154, v160, v142 offset:64
	s_mov_b32 s4, 0x358637bd
	v_mov_b64_e32 v[156:157], s[4:5]
	s_mov_b32 s8, 0x3a000000
	v_lshl_add_u32 v153, s81, 8, v143
	s_waitcnt lgkmcnt(0)
	v_pk_fma_f32 v[158:159], v[154:155], s[8:9], v[156:157] op_sel_hi:[1,0,0]
	s_mov_b32 s81, s80
	v_mul_f32_e32 v144, 0x4b800000, v159
	v_cmp_gt_f32_e64 s[4:5], s97, v159
	v_cmp_gt_f32_e32 vcc, s97, v158
	s_mov_b64 s[68:69], s[66:67]
	v_cndmask_b32_e64 v144, v159, v144, s[4:5]
	v_rsq_f32_e32 v144, v144
	ds_bpermute_b32 v159, v160, v142 offset:128
	v_mul_f32_e32 v146, 0x45800000, v144
	v_cndmask_b32_e64 v144, v144, v146, s[4:5]
	v_cndmask_b32_e64 v154, v144, 1.0, s[34:35]
	v_mul_f32_e32 v144, 0x4b800000, v158
	v_cndmask_b32_e32 v144, v158, v144, vcc
	ds_bpermute_b32 v158, v160, v142 offset:192
	v_rsq_f32_e32 v144, v144
	s_waitcnt lgkmcnt(0)
	v_pk_fma_f32 v[158:159], v[158:159], s[8:9], v[156:157] op_sel_hi:[1,0,0]
	s_nop 0
	v_mul_f32_e32 v142, 0x4b800000, v159
	v_cmp_gt_f32_e64 s[4:5], s97, v159
	v_mul_f32_e32 v146, 0x45800000, v144
	v_cndmask_b32_e32 v144, v144, v146, vcc
	v_cndmask_b32_e64 v142, v159, v142, s[4:5]
	v_rsq_f32_e32 v142, v142
	v_cndmask_b32_e64 v152, v144, 1.0, s[34:35]
	v_cmp_gt_f32_e32 vcc, s97, v158
	ds_bpermute_b32 v159, v160, v140
	v_mul_f32_e32 v144, 0x45800000, v142
	v_cndmask_b32_e64 v142, v142, v144, s[4:5]
	v_cndmask_b32_e64 v150, v142, 1.0, s[34:35]
	v_mul_f32_e32 v142, 0x4b800000, v158
	v_cndmask_b32_e32 v142, v158, v142, vcc
	v_rsq_f32_e32 v142, v142
	ds_bpermute_b32 v158, v160, v140 offset:64
	v_pk_mul_f32 v[110:111], v[110:111], v[152:153] op_sel_hi:[1,0]
	v_pk_mul_f32 v[102:103], v[102:103], v[152:153] op_sel_hi:[1,0]
	v_mul_f32_e32 v144, 0x45800000, v142
	v_cndmask_b32_e32 v142, v142, v144, vcc
	s_waitcnt lgkmcnt(0)
; __device__ __forceinline__ float silu_f(float x) { return x * __builtin_amdgcn_rcpf(1.f + __builtin_amdgcn_exp2f(-LOG2E * x)); }
; __device__ __forceinline__ u32x4 pk8(const f32x4 a, const f32x4 b) { u32x4 w; w.x = pk2(a[0], a[1]); w.y = pk2(a[2], a[3]); w.z = pk2(b[0], b[1]); w.w = pk2(b[2], b[3]); return w; }
; __device__ __forceinline__ float pre_get(const Pre& p, int ai, int m, int fr) { return __shfl(p.v[ai], m * 16 + fr); }
; __device__ __forceinline__ float rstd_pre(const float* ss, float v) { return ss ? rsqrtf(v * (1.0f / 2048.0f) + 1e-6f) : 1.0f; }
;     __device__ __forceinline__ void operator()(const Acc& acc, const Unit& u, int wr, int wc, int fr, int fq, const Pre& pre) const {
;         const int row0 = u.pm * 256 + wr * 64 + fr, col0 = u.pn * 128 + wc * 32 + 8 * fq;
;         float rsq[2][4];
; #pragma unroll
;         for (int ai = 0; ai < 2; ++ai)
; #pragma unroll
;             for (int m = 0; m < 4; ++m) rsq[ai][m] = rstd_pre(ss, pre_get(pre, ai, m, fr));
; #pragma unroll
;         for (int ai = 0; ai < 2; ++ai)
; #pragma unroll
;             for (int m = 0; m < 4; ++m) {
;                 f32x4 v0, v1; const float rs = rsq[ai][m];
; #pragma unroll
;                 for (int e = 0; e < 4; ++e) { v0[e] = silu_f(acc[ai][0][m][0][e] * rs) * (acc[ai][1][m][0][e] * rs); v1[e] = silu_f(acc[ai][0][m][1][e] * rs) * (acc[ai][1][m][1][e] * rs); }
;                 *(u32x4*)(O + (size_t)(row0 + ai * 128 + m * 16) * ldc + col0) = pk8(v0, v1);
	v_pk_fma_f32 v[158:159], v[158:159], s[8:9], v[156:157] op_sel_hi:[1,0,0]
	v_cndmask_b32_e64 v148, v142, 1.0, s[34:35]
	v_mul_f32_e32 v142, 0x4b800000, v159
	v_cmp_gt_f32_e64 s[4:5], s97, v159
	v_cmp_gt_f32_e32 vcc, s97, v158
	v_pk_mul_f32 v[106:107], v[106:107], v[152:153] op_sel_hi:[1,0]
	v_cndmask_b32_e64 v142, v159, v142, s[4:5]
	v_rsq_f32_e32 v142, v142
	ds_bpermute_b32 v159, v160, v140 offset:128
	v_pk_mul_f32 v[98:99], v[98:99], v[152:153] op_sel_hi:[1,0]
	v_pk_mul_f32 v[104:105], v[104:105], v[152:153] op_sel_hi:[1,0]
	v_mul_f32_e32 v144, 0x45800000, v142
	v_cndmask_b32_e64 v142, v142, v144, s[4:5]
	v_cndmask_b32_e64 v146, v142, 1.0, s[34:35]
	v_mul_f32_e32 v142, 0x4b800000, v158
	v_cndmask_b32_e32 v142, v158, v142, vcc
	ds_bpermute_b32 v158, v160, v140 offset:192
	v_rsq_f32_e32 v142, v142
	v_pk_mul_f32 v[100:101], v[100:101], v[152:153] op_sel_hi:[1,0]
	v_pk_mul_f32 v[94:95], v[94:95], v[150:151] op_sel_hi:[1,0]
	v_pk_mul_f32 v[86:87], v[86:87], v[150:151] op_sel_hi:[1,0]
	s_waitcnt lgkmcnt(0)
	v_pk_fma_f32 v[156:157], v[158:159], s[8:9], v[156:157] op_sel_hi:[1,0,0]
	v_mul_f32_e32 v144, 0x45800000, v142
	v_mul_f32_e32 v140, 0x4b800000, v157
	v_cmp_gt_f32_e64 s[4:5], s97, v157
	v_cndmask_b32_e32 v142, v142, v144, vcc
	v_cndmask_b32_e64 v144, v142, 1.0, s[34:35]
	v_cndmask_b32_e64 v140, v157, v140, s[4:5]
	v_rsq_f32_e32 v140, v140
	v_cmp_gt_f32_e32 vcc, s97, v156
	v_pk_mul_f32 v[90:91], v[90:91], v[150:151] op_sel_hi:[1,0]
	v_pk_mul_f32 v[82:83], v[82:83], v[150:151] op_sel_hi:[1,0]
	v_mul_f32_e32 v142, 0x45800000, v140
	v_cndmask_b32_e64 v140, v140, v142, s[4:5]
	v_cndmask_b32_e64 v142, v140, 1.0, s[34:35]
	v_mul_f32_e32 v140, 0x4b800000, v156
	v_cndmask_b32_e32 v140, v156, v140, vcc
	v_rsq_f32_e32 v140, v140
	v_lshl_or_b32 v156, s55, 7, v149
	v_ashrrev_i32_e32 v157, 31, v156
	v_pk_mul_f32 v[88:89], v[88:89], v[150:151] op_sel_hi:[1,0]
	v_mul_f32_e32 v155, 0x45800000, v140
	v_pk_mul_f32 v[126:127], v[126:127], v[154:155] op_sel_hi:[1,0]
	v_cndmask_b32_e32 v140, v140, v155, vcc
	v_mul_f32_e32 v155, 0xbfb8aa3b, v126
	v_exp_f32_e32 v155, v155
	v_pk_mul_f32 v[84:85], v[84:85], v[150:151] op_sel_hi:[1,0]
	v_pk_mul_f32 v[78:79], v[78:79], v[148:149] op_sel_hi:[1,0]
	v_pk_mul_f32 v[70:71], v[70:71], v[148:149] op_sel_hi:[1,0]
	v_add_f32_e32 v155, 1.0, v155
	v_rcp_f32_e32 v158, v155
	v_mul_f32_e32 v155, 0xbfb8aa3b, v127
	v_exp_f32_e32 v155, v155
	v_pk_mul_f32 v[74:75], v[74:75], v[148:149] op_sel_hi:[1,0]
	v_pk_mul_f32 v[66:67], v[66:67], v[148:149] op_sel_hi:[1,0]
	v_pk_mul_f32 v[72:73], v[72:73], v[148:149] op_sel_hi:[1,0]
	v_add_f32_e32 v155, 1.0, v155
	v_rcp_f32_e32 v159, v155
	v_pk_mul_f32 v[118:119], v[118:119], v[154:155] op_sel_hi:[1,0]
	v_pk_mul_f32 v[122:123], v[122:123], v[154:155] op_sel_hi:[1,0]
	v_pk_mul_f32 v[114:115], v[114:115], v[154:155] op_sel_hi:[1,0]
	v_pk_mul_f32 v[126:127], v[126:127], v[158:159]
	v_pk_mul_f32 v[120:121], v[120:121], v[154:155] op_sel_hi:[1,0]
	v_pk_mul_f32 v[118:119], v[118:119], v[126:127]
	v_mul_f32_e32 v126, 0xbfb8aa3b, v122
	v_mul_f32_e32 v127, 0xbfb8aa3b, v123
	v_exp_f32_e32 v126, v126
	v_exp_f32_e32 v127, v127
	v_pk_mul_f32 v[116:117], v[116:117], v[154:155] op_sel_hi:[1,0]
	v_cvt_pk_bf16_f32 v118, v118, v119
	v_add_f32_e32 v126, 1.0, v126
	v_add_f32_e32 v127, 1.0, v127
	v_rcp_f32_e32 v126, v126
	v_rcp_f32_e32 v127, v127
	v_pk_mul_f32 v[68:69], v[68:69], v[148:149] op_sel_hi:[1,0]
	v_pk_mul_f32 v[62:63], v[62:63], v[146:147] op_sel_hi:[1,0]
	v_pk_mul_f32 v[54:55], v[54:55], v[146:147] op_sel_hi:[1,0]
	v_pk_mul_f32 v[122:123], v[122:123], v[126:127]
	v_pk_mul_f32 v[58:59], v[58:59], v[146:147] op_sel_hi:[1,0]
	v_pk_mul_f32 v[114:115], v[114:115], v[122:123]
	v_pk_mul_f32 v[122:123], v[128:129], v[154:155] op_sel_hi:[1,0]
	v_pk_mul_f32 v[50:51], v[50:51], v[146:147] op_sel_hi:[1,0]
	v_mul_f32_e32 v126, 0xbfb8aa3b, v122
	v_mul_f32_e32 v127, 0xbfb8aa3b, v123
	v_exp_f32_e32 v126, v126
	v_exp_f32_e32 v127, v127
	v_pk_mul_f32 v[56:57], v[56:57], v[146:147] op_sel_hi:[1,0]
	v_pk_mul_f32 v[52:53], v[52:53], v[146:147] op_sel_hi:[1,0]
	v_add_f32_e32 v126, 1.0, v126
	v_add_f32_e32 v127, 1.0, v127
	v_rcp_f32_e32 v126, v126
	v_rcp_f32_e32 v127, v127
	v_pk_mul_f32 v[46:47], v[46:47], v[144:145] op_sel_hi:[1,0]
	v_pk_mul_f32 v[38:39], v[38:39], v[144:145] op_sel_hi:[1,0]
	v_pk_mul_f32 v[42:43], v[42:43], v[144:145] op_sel_hi:[1,0]
	v_pk_mul_f32 v[122:123], v[122:123], v[126:127]
	v_pk_mul_f32 v[34:35], v[34:35], v[144:145] op_sel_hi:[1,0]
	v_pk_mul_f32 v[120:121], v[120:121], v[122:123]
	v_pk_mul_f32 v[122:123], v[124:125], v[154:155] op_sel_hi:[1,0]
	v_cvt_pk_bf16_f32 v119, v120, v121
	v_mul_f32_e32 v124, 0xbfb8aa3b, v122
	v_mul_f32_e32 v125, 0xbfb8aa3b, v123
	v_exp_f32_e32 v124, v124
	v_exp_f32_e32 v125, v125
	v_cvt_pk_bf16_f32 v120, v114, v115
	v_ashrrev_i32_e32 v114, 31, v153
	v_add_f32_e32 v124, 1.0, v124
	v_add_f32_e32 v125, 1.0, v125
	v_rcp_f32_e32 v124, v124
	v_rcp_f32_e32 v125, v125
	v_pk_mul_f32 v[40:41], v[40:41], v[144:145] op_sel_hi:[1,0]
	v_pk_mul_f32 v[36:37], v[36:37], v[144:145] op_sel_hi:[1,0]
	v_pk_mul_f32 v[30:31], v[30:31], v[142:143] op_sel_hi:[1,0]
	v_pk_mul_f32 v[122:123], v[122:123], v[124:125]
	v_pk_mul_f32 v[22:23], v[22:23], v[142:143] op_sel_hi:[1,0]
	v_pk_mul_f32 v[116:117], v[116:117], v[122:123]
	v_pk_mul_f32 v[26:27], v[26:27], v[142:143] op_sel_hi:[1,0]
	v_cvt_pk_bf16_f32 v121, v116, v117
	v_mul_lo_u32 v116, s12, v114
	v_mul_lo_u32 v117, s13, v153
	v_mad_u64_u32 v[114:115], s[4:5], s12, v153, 0
	v_add3_u32 v115, v115, v116, v117
	v_mul_f32_e32 v117, 0xbfb8aa3b, v110
	v_exp_f32_e32 v117, v117
	v_lshl_add_u64 v[122:123], v[114:115], 1, s[62:63]
	v_lshlrev_b64 v[114:115], 1, v[156:157]
; __device__ __forceinline__ float silu_f(float x) { return x * __builtin_amdgcn_rcpf(1.f + __builtin_amdgcn_exp2f(-LOG2E * x)); }
; __device__ __forceinline__ u32x4 pk8(const f32x4 a, const f32x4 b) { u32x4 w; w.x = pk2(a[0], a[1]); w.y = pk2(a[2], a[3]); w.z = pk2(b[0], b[1]); w.w = pk2(b[2], b[3]); return w; }
;     __device__ __forceinline__ void operator()(const Acc& acc, const Unit& u, int wr, int wc, int fr, int fq, const Pre& pre) const {
;     ...
;         for (int ai = 0; ai < 2; ++ai)
; #pragma unroll
;             for (int m = 0; m < 4; ++m) {
;                 f32x4 v0, v1; const float rs = rsq[ai][m];
; #pragma unroll
;                 for (int e = 0; e < 4; ++e) { v0[e] = silu_f(acc[ai][0][m][0][e] * rs) * (acc[ai][1][m][0][e] * rs); v1[e] = silu_f(acc[ai][0][m][1][e] * rs) * (acc[ai][1][m][1][e] * rs); }
;                 *(u32x4*)(O + (size_t)(row0 + ai * 128 + m * 16) * ldc + col0) = pk8(v0, v1);
	v_lshl_add_u64 v[122:123], v[122:123], 0, v[114:115]
	v_add_f32_e32 v117, 1.0, v117
	global_store_dwordx4 v[122:123], v[118:121], off
	v_pk_mul_f32 v[18:19], v[18:19], v[142:143] op_sel_hi:[1,0]
	v_pk_mul_f32 v[24:25], v[24:25], v[142:143] op_sel_hi:[1,0]
	v_rcp_f32_e32 v118, v117
	v_mul_f32_e32 v117, 0xbfb8aa3b, v111
	v_exp_f32_e32 v117, v117
	v_pk_mul_f32 v[20:21], v[20:21], v[142:143] op_sel_hi:[1,0]
	v_cndmask_b32_e64 v140, v140, 1.0, s[34:35]
	v_pk_mul_f32 v[14:15], v[14:15], v[140:141] op_sel_hi:[1,0]
	v_add_f32_e32 v117, 1.0, v117
	v_rcp_f32_e32 v119, v117
	v_pk_mul_f32 v[6:7], v[6:7], v[140:141] op_sel_hi:[1,0]
	v_pk_mul_f32 v[10:11], v[10:11], v[140:141] op_sel_hi:[1,0]
	v_pk_mul_f32 v[2:3], v[2:3], v[140:141] op_sel_hi:[1,0]
	v_pk_mul_f32 v[110:111], v[110:111], v[118:119]
	v_pk_mul_f32 v[8:9], v[8:9], v[140:141] op_sel_hi:[1,0]
	v_pk_mul_f32 v[102:103], v[102:103], v[110:111]
	v_mul_f32_e32 v110, 0xbfb8aa3b, v106
	v_mul_f32_e32 v111, 0xbfb8aa3b, v107
	v_exp_f32_e32 v110, v110
	v_exp_f32_e32 v111, v111
	v_pk_mul_f32 v[4:5], v[4:5], v[140:141] op_sel_hi:[1,0]
	s_and_b64 vcc, exec, s[0:1]
	v_add_f32_e32 v110, 1.0, v110
	v_add_f32_e32 v111, 1.0, v111
	v_rcp_f32_e32 v110, v110
	v_rcp_f32_e32 v111, v111
	s_mov_b32 s55, s79
	v_pk_mul_f32 v[106:107], v[106:107], v[110:111]
	s_nop 0
	v_pk_mul_f32 v[106:107], v[98:99], v[106:107]
	v_pk_mul_f32 v[98:99], v[112:113], v[152:153] op_sel_hi:[1,0]
	s_nop 0
	v_mul_f32_e32 v110, 0xbfb8aa3b, v98
	v_mul_f32_e32 v111, 0xbfb8aa3b, v99
	v_exp_f32_e32 v110, v110
	v_exp_f32_e32 v111, v111
	v_add_f32_e32 v110, 1.0, v110
	v_add_f32_e32 v111, 1.0, v111
	v_rcp_f32_e32 v110, v110
	v_rcp_f32_e32 v111, v111
	s_nop 0
	v_pk_mul_f32 v[98:99], v[98:99], v[110:111]
	s_nop 0
	v_pk_mul_f32 v[104:105], v[104:105], v[98:99]
	v_pk_mul_f32 v[98:99], v[108:109], v[152:153] op_sel_hi:[1,0]
	s_nop 0
	v_mul_f32_e32 v108, 0xbfb8aa3b, v98
	v_mul_f32_e32 v109, 0xbfb8aa3b, v99
	v_exp_f32_e32 v108, v108
	v_exp_f32_e32 v109, v109
	v_add_f32_e32 v108, 1.0, v108
	v_add_f32_e32 v109, 1.0, v109
	v_rcp_f32_e32 v108, v108
	v_rcp_f32_e32 v109, v109
	s_nop 0
	v_pk_mul_f32 v[98:99], v[98:99], v[108:109]
	s_nop 0
	v_pk_mul_f32 v[108:109], v[100:101], v[98:99]
	v_cvt_pk_bf16_f32 v98, v102, v103
	v_or_b32_e32 v102, 16, v153
	v_cvt_pk_bf16_f32 v99, v104, v105
	v_mul_lo_u32 v104, s13, v102
	v_mad_u64_u32 v[102:103], s[4:5], s12, v102, 0
	v_add3_u32 v103, v103, v116, v104
	v_lshl_add_u64 v[102:103], v[102:103], 1, s[62:63]
	v_cvt_pk_bf16_f32 v100, v106, v107
	v_cvt_pk_bf16_f32 v101, v108, v109
	v_lshl_add_u64 v[102:103], v[102:103], 0, v[114:115]
	global_store_dwordx4 v[102:103], v[98:101], off
	s_nop 1
	v_mul_f32_e32 v98, 0xbfb8aa3b, v94
	v_mul_f32_e32 v99, 0xbfb8aa3b, v95
	v_exp_f32_e32 v98, v98
	v_exp_f32_e32 v99, v99
	v_add_f32_e32 v98, 1.0, v98
	v_add_f32_e32 v99, 1.0, v99
	v_rcp_f32_e32 v98, v98
	v_rcp_f32_e32 v99, v99
	s_nop 0
	v_pk_mul_f32 v[94:95], v[94:95], v[98:99]
	s_nop 0
	v_pk_mul_f32 v[86:87], v[86:87], v[94:95]
	v_mul_f32_e32 v94, 0xbfb8aa3b, v90
	v_mul_f32_e32 v95, 0xbfb8aa3b, v91
	v_exp_f32_e32 v94, v94
	v_exp_f32_e32 v95, v95
	v_add_f32_e32 v94, 1.0, v94
	v_add_f32_e32 v95, 1.0, v95
	v_rcp_f32_e32 v94, v94
	v_rcp_f32_e32 v95, v95
	s_nop 0
	v_pk_mul_f32 v[90:91], v[90:91], v[94:95]
	s_nop 0
	v_pk_mul_f32 v[90:91], v[82:83], v[90:91]
	v_pk_mul_f32 v[82:83], v[96:97], v[150:151] op_sel_hi:[1,0]
	s_nop 0
	v_mul_f32_e32 v94, 0xbfb8aa3b, v82
	v_mul_f32_e32 v95, 0xbfb8aa3b, v83
	v_exp_f32_e32 v94, v94
	v_exp_f32_e32 v95, v95
	v_add_f32_e32 v94, 1.0, v94
	v_add_f32_e32 v95, 1.0, v95
	v_rcp_f32_e32 v94, v94
	v_rcp_f32_e32 v95, v95
	s_nop 0
	v_pk_mul_f32 v[82:83], v[82:83], v[94:95]
	s_nop 0
	v_pk_mul_f32 v[88:89], v[88:89], v[82:83]
	v_pk_mul_f32 v[82:83], v[92:93], v[150:151] op_sel_hi:[1,0]
	s_nop 0
	v_mul_f32_e32 v92, 0xbfb8aa3b, v82
	v_mul_f32_e32 v93, 0xbfb8aa3b, v83
	v_exp_f32_e32 v92, v92
	v_exp_f32_e32 v93, v93
	v_add_f32_e32 v92, 1.0, v92
	v_add_f32_e32 v93, 1.0, v93
	v_rcp_f32_e32 v92, v92
	v_rcp_f32_e32 v93, v93
	s_nop 0
	v_pk_mul_f32 v[82:83], v[82:83], v[92:93]
	s_nop 0
	v_pk_mul_f32 v[92:93], v[84:85], v[82:83]
	v_cvt_pk_bf16_f32 v82, v86, v87
	v_or_b32_e32 v86, 32, v153
	v_cvt_pk_bf16_f32 v83, v88, v89
	v_mul_lo_u32 v88, s13, v86
	v_mad_u64_u32 v[86:87], s[4:5], s12, v86, 0
	v_add3_u32 v87, v87, v116, v88
	v_lshl_add_u64 v[86:87], v[86:87], 1, s[62:63]
	v_cvt_pk_bf16_f32 v84, v90, v91
	v_cvt_pk_bf16_f32 v85, v92, v93
	v_lshl_add_u64 v[86:87], v[86:87], 0, v[114:115]
	global_store_dwordx4 v[86:87], v[82:85], off
	s_nop 1
	v_mul_f32_e32 v82, 0xbfb8aa3b, v78
	v_mul_f32_e32 v83, 0xbfb8aa3b, v79
	v_exp_f32_e32 v82, v82
	v_exp_f32_e32 v83, v83
	v_add_f32_e32 v82, 1.0, v82
	v_add_f32_e32 v83, 1.0, v83
	v_rcp_f32_e32 v82, v82
	v_rcp_f32_e32 v83, v83
	s_nop 0
	v_pk_mul_f32 v[78:79], v[78:79], v[82:83]
	s_nop 0
	v_pk_mul_f32 v[70:71], v[70:71], v[78:79]
	v_mul_f32_e32 v78, 0xbfb8aa3b, v74
	v_mul_f32_e32 v79, 0xbfb8aa3b, v75
	v_exp_f32_e32 v78, v78
	v_exp_f32_e32 v79, v79
	v_add_f32_e32 v78, 1.0, v78
	v_add_f32_e32 v79, 1.0, v79
	v_rcp_f32_e32 v78, v78
	v_rcp_f32_e32 v79, v79
	s_nop 0
	v_pk_mul_f32 v[74:75], v[74:75], v[78:79]
	s_nop 0
	v_pk_mul_f32 v[74:75], v[66:67], v[74:75]
	v_pk_mul_f32 v[66:67], v[80:81], v[148:149] op_sel_hi:[1,0]
	s_nop 0
	v_mul_f32_e32 v78, 0xbfb8aa3b, v66
	v_mul_f32_e32 v79, 0xbfb8aa3b, v67
	v_exp_f32_e32 v78, v78
	v_exp_f32_e32 v79, v79
	v_add_f32_e32 v78, 1.0, v78
	v_add_f32_e32 v79, 1.0, v79
	v_rcp_f32_e32 v78, v78
	v_rcp_f32_e32 v79, v79
	s_nop 0
	v_pk_mul_f32 v[66:67], v[66:67], v[78:79]
	s_nop 0
	v_pk_mul_f32 v[72:73], v[72:73], v[66:67]
	v_pk_mul_f32 v[66:67], v[76:77], v[148:149] op_sel_hi:[1,0]
; __device__ __forceinline__ float silu_f(float x) { return x * __builtin_amdgcn_rcpf(1.f + __builtin_amdgcn_exp2f(-LOG2E * x)); }
; __device__ __forceinline__ u32x4 pk8(const f32x4 a, const f32x4 b) { u32x4 w; w.x = pk2(a[0], a[1]); w.y = pk2(a[2], a[3]); w.z = pk2(b[0], b[1]); w.w = pk2(b[2], b[3]); return w; }
;     __device__ __forceinline__ void operator()(const Acc& acc, const Unit& u, int wr, int wc, int fr, int fq, const Pre& pre) const {
;     ...
;         for (int ai = 0; ai < 2; ++ai)
; #pragma unroll
;             for (int m = 0; m < 4; ++m) {
;                 f32x4 v0, v1; const float rs = rsq[ai][m];
; #pragma unroll
;                 for (int e = 0; e < 4; ++e) { v0[e] = silu_f(acc[ai][0][m][0][e] * rs) * (acc[ai][1][m][0][e] * rs); v1[e] = silu_f(acc[ai][0][m][1][e] * rs) * (acc[ai][1][m][1][e] * rs); }
;                 *(u32x4*)(O + (size_t)(row0 + ai * 128 + m * 16) * ldc + col0) = pk8(v0, v1);
	s_nop 0
	v_mul_f32_e32 v76, 0xbfb8aa3b, v66
	v_mul_f32_e32 v77, 0xbfb8aa3b, v67
	v_exp_f32_e32 v76, v76
	v_exp_f32_e32 v77, v77
	v_add_f32_e32 v76, 1.0, v76
	v_add_f32_e32 v77, 1.0, v77
	v_rcp_f32_e32 v76, v76
	v_rcp_f32_e32 v77, v77
	s_nop 0
	v_pk_mul_f32 v[66:67], v[66:67], v[76:77]
	s_nop 0
	v_pk_mul_f32 v[76:77], v[68:69], v[66:67]
	v_cvt_pk_bf16_f32 v66, v70, v71
	v_or_b32_e32 v70, 48, v153
	v_cvt_pk_bf16_f32 v67, v72, v73
	v_mul_lo_u32 v72, s13, v70
	v_mad_u64_u32 v[70:71], s[4:5], s12, v70, 0
	v_add3_u32 v71, v71, v116, v72
	v_lshl_add_u64 v[70:71], v[70:71], 1, s[62:63]
	v_cvt_pk_bf16_f32 v68, v74, v75
	v_cvt_pk_bf16_f32 v69, v76, v77
	v_lshl_add_u64 v[70:71], v[70:71], 0, v[114:115]
	global_store_dwordx4 v[70:71], v[66:69], off
	s_nop 1
	v_mul_f32_e32 v66, 0xbfb8aa3b, v62
	v_mul_f32_e32 v67, 0xbfb8aa3b, v63
	v_exp_f32_e32 v66, v66
	v_exp_f32_e32 v67, v67
	v_add_u32_e32 v68, 0x80, v153
	v_add_f32_e32 v66, 1.0, v66
	v_add_f32_e32 v67, 1.0, v67
	v_rcp_f32_e32 v66, v66
	v_rcp_f32_e32 v67, v67
	s_nop 0
	v_pk_mul_f32 v[62:63], v[62:63], v[66:67]
	s_nop 0
	v_pk_mul_f32 v[54:55], v[54:55], v[62:63]
	v_mul_f32_e32 v62, 0xbfb8aa3b, v58
	v_mul_f32_e32 v63, 0xbfb8aa3b, v59
	v_exp_f32_e32 v62, v62
	v_exp_f32_e32 v63, v63
	v_add_f32_e32 v62, 1.0, v62
	v_add_f32_e32 v63, 1.0, v63
	v_rcp_f32_e32 v62, v62
	v_rcp_f32_e32 v63, v63
	s_nop 0
	v_pk_mul_f32 v[58:59], v[58:59], v[62:63]
	s_nop 0
	v_pk_mul_f32 v[58:59], v[50:51], v[58:59]
	v_pk_mul_f32 v[50:51], v[64:65], v[146:147] op_sel_hi:[1,0]
	s_nop 0
	v_mul_f32_e32 v62, 0xbfb8aa3b, v50
	v_mul_f32_e32 v63, 0xbfb8aa3b, v51
	v_exp_f32_e32 v62, v62
	v_exp_f32_e32 v63, v63
	v_add_f32_e32 v62, 1.0, v62
	v_add_f32_e32 v63, 1.0, v63
	v_rcp_f32_e32 v62, v62
	v_rcp_f32_e32 v63, v63
	s_nop 0
	v_pk_mul_f32 v[50:51], v[50:51], v[62:63]
	s_nop 0
	v_pk_mul_f32 v[56:57], v[56:57], v[50:51]
	v_pk_mul_f32 v[50:51], v[60:61], v[146:147] op_sel_hi:[1,0]
	s_nop 0
	v_mul_f32_e32 v60, 0xbfb8aa3b, v50
	v_mul_f32_e32 v61, 0xbfb8aa3b, v51
	v_exp_f32_e32 v60, v60
	v_exp_f32_e32 v61, v61
	v_add_f32_e32 v60, 1.0, v60
	v_add_f32_e32 v61, 1.0, v61
	v_rcp_f32_e32 v60, v60
	v_rcp_f32_e32 v61, v61
	s_nop 0
	v_pk_mul_f32 v[50:51], v[50:51], v[60:61]
	s_nop 0
	v_pk_mul_f32 v[60:61], v[52:53], v[50:51]
	v_cvt_pk_bf16_f32 v50, v54, v55
	v_ashrrev_i32_e32 v54, 31, v68
	v_cvt_pk_bf16_f32 v51, v56, v57
	v_mul_lo_u32 v56, s12, v54
	v_mul_lo_u32 v57, s13, v68
	v_mad_u64_u32 v[54:55], s[4:5], s12, v68, 0
	v_add3_u32 v55, v55, v56, v57
	v_lshl_add_u64 v[54:55], v[54:55], 1, s[62:63]
	v_cvt_pk_bf16_f32 v52, v58, v59
	v_cvt_pk_bf16_f32 v53, v60, v61
	v_lshl_add_u64 v[54:55], v[54:55], 0, v[114:115]
	global_store_dwordx4 v[54:55], v[50:53], off
	s_nop 1
	v_mul_f32_e32 v50, 0xbfb8aa3b, v46
	v_mul_f32_e32 v51, 0xbfb8aa3b, v47
	v_exp_f32_e32 v50, v50
	v_exp_f32_e32 v51, v51
	v_add_f32_e32 v50, 1.0, v50
	v_add_f32_e32 v51, 1.0, v51
	v_rcp_f32_e32 v50, v50
	v_rcp_f32_e32 v51, v51
	s_nop 0
	v_pk_mul_f32 v[46:47], v[46:47], v[50:51]
	s_nop 0
	v_pk_mul_f32 v[38:39], v[38:39], v[46:47]
	v_mul_f32_e32 v46, 0xbfb8aa3b, v42
	v_mul_f32_e32 v47, 0xbfb8aa3b, v43
	v_exp_f32_e32 v46, v46
	v_exp_f32_e32 v47, v47
	v_add_f32_e32 v46, 1.0, v46
	v_add_f32_e32 v47, 1.0, v47
	v_rcp_f32_e32 v46, v46
	v_rcp_f32_e32 v47, v47
	s_nop 0
	v_pk_mul_f32 v[42:43], v[42:43], v[46:47]
	s_nop 0
	v_pk_mul_f32 v[42:43], v[34:35], v[42:43]
	v_pk_mul_f32 v[34:35], v[48:49], v[144:145] op_sel_hi:[1,0]
	s_nop 0
	v_mul_f32_e32 v46, 0xbfb8aa3b, v34
	v_mul_f32_e32 v47, 0xbfb8aa3b, v35
	v_exp_f32_e32 v46, v46
	v_exp_f32_e32 v47, v47
	v_add_f32_e32 v46, 1.0, v46
	v_add_f32_e32 v47, 1.0, v47
	v_rcp_f32_e32 v46, v46
	v_rcp_f32_e32 v47, v47
	s_nop 0
	v_pk_mul_f32 v[34:35], v[34:35], v[46:47]
	s_nop 0
	v_pk_mul_f32 v[40:41], v[40:41], v[34:35]
	v_pk_mul_f32 v[34:35], v[44:45], v[144:145] op_sel_hi:[1,0]
	s_nop 0
	v_mul_f32_e32 v44, 0xbfb8aa3b, v34
	v_mul_f32_e32 v45, 0xbfb8aa3b, v35
	v_exp_f32_e32 v44, v44
	v_exp_f32_e32 v45, v45
	v_add_f32_e32 v44, 1.0, v44
	v_add_f32_e32 v45, 1.0, v45
	v_rcp_f32_e32 v44, v44
	v_rcp_f32_e32 v45, v45
	s_nop 0
	v_pk_mul_f32 v[34:35], v[34:35], v[44:45]
	s_nop 0
	v_pk_mul_f32 v[44:45], v[36:37], v[34:35]
	v_cvt_pk_bf16_f32 v34, v38, v39
	v_add_u32_e32 v38, 0x90, v153
	v_ashrrev_i32_e32 v39, 31, v38
; __device__ __forceinline__ float silu_f(float x) { return x * __builtin_amdgcn_rcpf(1.f + __builtin_amdgcn_exp2f(-LOG2E * x)); }
; __device__ __forceinline__ u32x4 pk8(const f32x4 a, const f32x4 b) { u32x4 w; w.x = pk2(a[0], a[1]); w.y = pk2(a[2], a[3]); w.z = pk2(b[0], b[1]); w.w = pk2(b[2], b[3]); return w; }
; template <class Epi>
; __device__ __forceinline__ void gemm_phase(LAS unsigned char* lds, const Gemm g, const Sched& S, const Epi& E) {
;     ...
;         if (!has_next) break;
;     __device__ __forceinline__ void operator()(const Acc& acc, const Unit& u, int wr, int wc, int fr, int fq, const Pre& pre) const {
;     ...
;         for (int ai = 0; ai < 2; ++ai)
; #pragma unroll
;             for (int m = 0; m < 4; ++m) {
;                 f32x4 v0, v1; const float rs = rsq[ai][m];
; #pragma unroll
;                 for (int e = 0; e < 4; ++e) { v0[e] = silu_f(acc[ai][0][m][0][e] * rs) * (acc[ai][1][m][0][e] * rs); v1[e] = silu_f(acc[ai][0][m][1][e] * rs) * (acc[ai][1][m][1][e] * rs); }
;                 *(u32x4*)(O + (size_t)(row0 + ai * 128 + m * 16) * ldc + col0) = pk8(v0, v1);
;             }
;     }
	v_cvt_pk_bf16_f32 v35, v40, v41
	v_mul_lo_u32 v40, s12, v39
	v_mul_lo_u32 v41, s13, v38
	v_mad_u64_u32 v[38:39], s[4:5], s12, v38, 0
	v_add3_u32 v39, v39, v40, v41
	v_lshl_add_u64 v[38:39], v[38:39], 1, s[62:63]
	v_cvt_pk_bf16_f32 v36, v42, v43
	v_cvt_pk_bf16_f32 v37, v44, v45
	v_lshl_add_u64 v[38:39], v[38:39], 0, v[114:115]
	global_store_dwordx4 v[38:39], v[34:37], off
	s_nop 1
	v_mul_f32_e32 v34, 0xbfb8aa3b, v30
	v_mul_f32_e32 v35, 0xbfb8aa3b, v31
	v_exp_f32_e32 v34, v34
	v_exp_f32_e32 v35, v35
	v_add_f32_e32 v34, 1.0, v34
	v_add_f32_e32 v35, 1.0, v35
	v_rcp_f32_e32 v34, v34
	v_rcp_f32_e32 v35, v35
	s_nop 0
	v_pk_mul_f32 v[30:31], v[30:31], v[34:35]
	s_nop 0
	v_pk_mul_f32 v[22:23], v[22:23], v[30:31]
	v_mul_f32_e32 v30, 0xbfb8aa3b, v26
	v_mul_f32_e32 v31, 0xbfb8aa3b, v27
	v_exp_f32_e32 v30, v30
	v_exp_f32_e32 v31, v31
	v_add_f32_e32 v30, 1.0, v30
	v_add_f32_e32 v31, 1.0, v31
	v_rcp_f32_e32 v30, v30
	v_rcp_f32_e32 v31, v31
	s_nop 0
	v_pk_mul_f32 v[26:27], v[26:27], v[30:31]
	s_nop 0
	v_pk_mul_f32 v[26:27], v[18:19], v[26:27]
	v_pk_mul_f32 v[18:19], v[32:33], v[142:143] op_sel_hi:[1,0]
	s_nop 0
	v_mul_f32_e32 v30, 0xbfb8aa3b, v18
	v_mul_f32_e32 v31, 0xbfb8aa3b, v19
	v_exp_f32_e32 v30, v30
	v_exp_f32_e32 v31, v31
	v_add_f32_e32 v30, 1.0, v30
	v_add_f32_e32 v31, 1.0, v31
	v_rcp_f32_e32 v30, v30
	v_rcp_f32_e32 v31, v31
	s_nop 0
	v_pk_mul_f32 v[18:19], v[18:19], v[30:31]
	s_nop 0
	v_pk_mul_f32 v[24:25], v[24:25], v[18:19]
	v_pk_mul_f32 v[18:19], v[28:29], v[142:143] op_sel_hi:[1,0]
	s_nop 0
	v_mul_f32_e32 v28, 0xbfb8aa3b, v18
	v_mul_f32_e32 v29, 0xbfb8aa3b, v19
	v_exp_f32_e32 v28, v28
	v_exp_f32_e32 v29, v29
	v_add_f32_e32 v28, 1.0, v28
	v_add_f32_e32 v29, 1.0, v29
	v_rcp_f32_e32 v28, v28
	v_rcp_f32_e32 v29, v29
	s_nop 0
	v_pk_mul_f32 v[18:19], v[18:19], v[28:29]
	s_nop 0
	v_pk_mul_f32 v[28:29], v[20:21], v[18:19]
	v_cvt_pk_bf16_f32 v18, v22, v23
	v_add_u32_e32 v22, 0xa0, v153
	v_ashrrev_i32_e32 v23, 31, v22
	v_cvt_pk_bf16_f32 v19, v24, v25
	v_mul_lo_u32 v24, s12, v23
	v_mul_lo_u32 v25, s13, v22
	v_mad_u64_u32 v[22:23], s[4:5], s12, v22, 0
	v_add3_u32 v23, v23, v24, v25
	v_lshl_add_u64 v[22:23], v[22:23], 1, s[62:63]
	v_cvt_pk_bf16_f32 v20, v26, v27
	v_cvt_pk_bf16_f32 v21, v28, v29
	v_lshl_add_u64 v[22:23], v[22:23], 0, v[114:115]
	global_store_dwordx4 v[22:23], v[18:21], off
	s_nop 1
	v_mul_f32_e32 v18, 0xbfb8aa3b, v14
	v_mul_f32_e32 v19, 0xbfb8aa3b, v15
	v_exp_f32_e32 v18, v18
	v_exp_f32_e32 v19, v19
	v_add_f32_e32 v18, 1.0, v18
	v_add_f32_e32 v19, 1.0, v19
	v_rcp_f32_e32 v18, v18
	v_rcp_f32_e32 v19, v19
	s_nop 0
	v_pk_mul_f32 v[14:15], v[14:15], v[18:19]
	s_nop 0
	v_pk_mul_f32 v[6:7], v[6:7], v[14:15]
	v_mul_f32_e32 v14, 0xbfb8aa3b, v10
	v_mul_f32_e32 v15, 0xbfb8aa3b, v11
	v_exp_f32_e32 v14, v14
	v_exp_f32_e32 v15, v15
	v_add_f32_e32 v14, 1.0, v14
	v_add_f32_e32 v15, 1.0, v15
	v_rcp_f32_e32 v14, v14
	v_rcp_f32_e32 v15, v15
	s_nop 0
	v_pk_mul_f32 v[10:11], v[10:11], v[14:15]
	s_nop 0
	v_pk_mul_f32 v[10:11], v[2:3], v[10:11]
	v_pk_mul_f32 v[2:3], v[16:17], v[140:141] op_sel_hi:[1,0]
	s_nop 0
	v_mul_f32_e32 v14, 0xbfb8aa3b, v2
	v_mul_f32_e32 v15, 0xbfb8aa3b, v3
	v_exp_f32_e32 v14, v14
	v_exp_f32_e32 v15, v15
	v_add_f32_e32 v14, 1.0, v14
	v_add_f32_e32 v15, 1.0, v15
	v_rcp_f32_e32 v14, v14
	v_rcp_f32_e32 v15, v15
	s_nop 0
	v_pk_mul_f32 v[2:3], v[2:3], v[14:15]
	s_nop 0
	v_pk_mul_f32 v[8:9], v[8:9], v[2:3]
	v_pk_mul_f32 v[2:3], v[12:13], v[140:141] op_sel_hi:[1,0]
	s_nop 0
	v_mul_f32_e32 v12, 0xbfb8aa3b, v2
	v_mul_f32_e32 v13, 0xbfb8aa3b, v3
	v_exp_f32_e32 v12, v12
	v_exp_f32_e32 v13, v13
	v_add_f32_e32 v12, 1.0, v12
	v_add_f32_e32 v13, 1.0, v13
	v_rcp_f32_e32 v12, v12
	v_rcp_f32_e32 v13, v13
	s_nop 0
	v_pk_mul_f32 v[2:3], v[2:3], v[12:13]
	s_nop 0
	v_pk_mul_f32 v[12:13], v[4:5], v[2:3]
	v_cvt_pk_bf16_f32 v2, v6, v7
	v_add_u32_e32 v6, 0xb0, v153
	v_ashrrev_i32_e32 v7, 31, v6
	v_cvt_pk_bf16_f32 v3, v8, v9
	v_mul_lo_u32 v8, s12, v7
	v_mul_lo_u32 v9, s13, v6
	v_mad_u64_u32 v[6:7], s[4:5], s12, v6, 0
	v_add3_u32 v7, v7, v8, v9
	v_lshl_add_u64 v[6:7], v[6:7], 1, s[62:63]
	v_cvt_pk_bf16_f32 v4, v10, v11
	v_cvt_pk_bf16_f32 v5, v12, v13
	v_lshl_add_u64 v[6:7], v[6:7], 0, v[114:115]
	s_mov_b64 s[4:5], s[64:65]
	global_store_dwordx4 v[6:7], v[2:5], off
	s_cbranch_vccz .LBB0_813
	s_branch .LBB0_828
